# removed the 36 genuinely redundant post-barrier s_waitcnt lgkmcnt(0) at the head of the GEMM MFMA blocks (drained by the pre-barrier wait)
# speedup vs baseline: 1.0117x; 1.0065x over previous
; #define PG8_STAGE(bufoff, gbase, voff) do { _Pragma("unroll") for (int _i = 0; _i < 2; ++_i) \
;         __builtin_amdgcn_global_load_lds((const unsigned*)((const char*)(gbase) + (voff)[_i]), (PG8_LAS unsigned*)(lds + (bufoff) + ldsw + _i * 8192), 16, 0, 0); } while (0)
; #define PG8_LDA(dst, b, h) do { _Pragma("unroll") for (int m = 0; m < 4; ++m) _Pragma("unroll") for (int k = 0; k < 2; ++k) dst[m][k] = *(const PG8_LAS bf16x8*)(lds + PG8_SA(b, h) + aoff + m * 2048 + k * 1024); } while (0)
; #define PG8_LDB(dst, b, h) do { _Pragma("unroll") for (int n = 0; n < 2; ++n) _Pragma("unroll") for (int k = 0; k < 2; ++k) dst[n][k] = *(const PG8_LAS bf16x8*)(lds + PG8_SB(b, h) + boff + n * 2048 + k * 1024); } while (0)
; #define PG8_MMA(ai, bj, At, Bt) do { __builtin_amdgcn_s_setprio(1); _Pragma("unroll") for (int m = 0; m < 4; ++m) _Pragma("unroll") for (int n = 0; n < 2; ++n) _Pragma("unroll") for (int k = 0; k < 2; ++k) \
;         acc[ai][bj][m][n] = __builtin_amdgcn_mfma_f32_16x16x32_bf16(Bt[n][k], At[m][k], acc[ai][bj][m][n], 0, 0, 0); __builtin_amdgcn_s_setprio(0); } while (0)
; #define PG8_WAIT_V(n) asm volatile("s_waitcnt vmcnt(" #n ")" ::: "memory")
; #define PG8_WAIT_L(n) asm volatile("s_waitcnt lgkmcnt(" #n ")" ::: "memory")
; #define PG8_BAR __builtin_amdgcn_s_barrier()
; #define PG8_SCHED __builtin_amdgcn_sched_barrier(0)
; template <class Epi, class Sched, bool ALIGN_EPI = false, bool SP2 = false>
; __device__ __forceinline__ void gemm_phase(PG8_LAS unsigned char* lds, const Gemm g, const Sched& S, const Epi& E) {
;     ...
;             PG8_WAIT_V(8); PG8_WAIT_L(0); PG8_BAR; PG8_MMA(0, 0, At, B0); PG8_MMA(0, 1, At, B1); PG8_BAR; PG8_SCHED;
;             PG8_LDA(At, 0, 1); PG8_STAGE(PG8_SB(0, 0), b2, voffB); PG8_STAGE(PG8_SB(0, 1), b2 + hstep, voffB); PG8_STAGE(PG8_SA(0, 0), a2, voffA);
;             PG8_WAIT_V(8); PG8_WAIT_L(0); PG8_BAR; PG8_MMA(1, 0, At, B0); PG8_MMA(1, 1, At, B1); PG8_BAR; PG8_SCHED;
;             PG8_LDB(B0, 1, 0); PG8_LDB(B1, 1, 1); PG8_SCHED; PG8_LDA(At, 1, 0); PG8_STAGE(PG8_SA(0, 1), a2 + hstep, voffA);
.Lgr_p1_0:
	s_waitcnt lgkmcnt(0)
	s_barrier
	s_setprio 1
	v_mfma_f32_16x16x32_bf16 v[116:119], v[152:155], v[184:187], v[116:119]
	v_mfma_f32_16x16x32_bf16 v[112:115], v[160:163], v[184:187], v[112:115]
	v_mfma_f32_16x16x32_bf16 v[108:111], v[152:155], v[192:195], v[108:111]
	v_mfma_f32_16x16x32_bf16 v[100:103], v[160:163], v[192:195], v[100:103]
	v_mfma_f32_16x16x32_bf16 v[92:95], v[152:155], v[200:203], v[92:95]
	v_mfma_f32_16x16x32_bf16 v[84:87], v[160:163], v[200:203], v[84:87]
	v_mfma_f32_16x16x32_bf16 v[76:79], v[152:155], v[210:213], v[76:79]
	v_mfma_f32_16x16x32_bf16 v[68:71], v[160:163], v[210:213], v[68:71]
	v_mfma_f32_16x16x32_bf16 v[116:119], v[156:159], v[188:191], v[116:119]
	v_mfma_f32_16x16x32_bf16 v[112:115], v[164:167], v[188:191], v[112:115]
	v_mfma_f32_16x16x32_bf16 v[108:111], v[156:159], v[196:199], v[108:111]
	v_mfma_f32_16x16x32_bf16 v[100:103], v[164:167], v[196:199], v[100:103]
	v_mfma_f32_16x16x32_bf16 v[92:95], v[156:159], v[206:209], v[92:95]
	v_mfma_f32_16x16x32_bf16 v[84:87], v[164:167], v[206:209], v[84:87]
	v_mfma_f32_16x16x32_bf16 v[76:79], v[156:159], v[214:217], v[76:79]
	v_mfma_f32_16x16x32_bf16 v[68:71], v[164:167], v[214:217], v[68:71]
	s_setprio 0
	s_setprio 1
	v_mfma_f32_16x16x32_bf16 v[124:127], v[168:171], v[184:187], v[124:127]
	v_mfma_f32_16x16x32_bf16 v[120:123], v[176:179], v[184:187], v[120:123]
	v_mfma_f32_16x16x32_bf16 v[104:107], v[168:171], v[192:195], v[104:107]
	v_mfma_f32_16x16x32_bf16 v[96:99], v[176:179], v[192:195], v[96:99]
	v_mfma_f32_16x16x32_bf16 v[88:91], v[168:171], v[200:203], v[88:91]
	v_mfma_f32_16x16x32_bf16 v[80:83], v[176:179], v[200:203], v[80:83]
	v_mfma_f32_16x16x32_bf16 v[72:75], v[168:171], v[210:213], v[72:75]
	v_mfma_f32_16x16x32_bf16 v[64:67], v[176:179], v[210:213], v[64:67]
	v_mfma_f32_16x16x32_bf16 v[124:127], v[172:175], v[188:191], v[124:127]
	v_mfma_f32_16x16x32_bf16 v[120:123], v[180:183], v[188:191], v[120:123]
	v_mfma_f32_16x16x32_bf16 v[104:107], v[172:175], v[196:199], v[104:107]
	v_mfma_f32_16x16x32_bf16 v[96:99], v[180:183], v[196:199], v[96:99]
	v_mfma_f32_16x16x32_bf16 v[88:91], v[172:175], v[206:209], v[88:91]
	v_mfma_f32_16x16x32_bf16 v[80:83], v[180:183], v[206:209], v[80:83]
	v_mfma_f32_16x16x32_bf16 v[72:75], v[172:175], v[214:217], v[72:75]
	v_mfma_f32_16x16x32_bf16 v[64:67], v[180:183], v[214:217], v[64:67]
	s_setprio 0
	s_barrier
	s_add_i32 s52, s43, s0
	s_add_u32 vcc_lo, s24, 0x80
	s_addc_u32 vcc_hi, s25, 0
	s_mov_b32 m0, s52
	ds_read_b128 v[184:187], v149 offset:16384
	ds_read_b128 v[188:191], v149 offset:17408
	ds_read_b128 v[192:195], v149 offset:18432
	ds_read_b128 v[196:199], v149 offset:19456
	global_load_lds_dwordx4 v132, s[24:25]
	s_add_i32 m0, s52, 0x2000
	s_add_u32 s52, s24, 0x80000
	s_addc_u32 s53, s25, 0
	s_add_i32 s54, s44, s0
	global_load_lds_dwordx4 v128, s[24:25]
	s_mov_b32 m0, s54
	ds_read_b128 v[214:217], v149 offset:23552
	global_load_lds_dwordx4 v132, s[52:53]
	s_add_i32 m0, s54, 0x2000
	ds_read_b128 v[210:213], v149 offset:22528
	global_load_lds_dwordx4 v128, s[52:53]
	s_add_u32 s98, s26, 0x80
	s_addc_u32 s99, s27, 0
	s_mov_b32 m0, s29
	ds_read_b128 v[206:209], v149 offset:21504
	global_load_lds_dwordx4 v134, s[26:27]
	s_mov_b32 m0, s30
	ds_read_b128 v[200:203], v149 offset:20480
	global_load_lds_dwordx4 v130, s[26:27]
	s_cmp_lg_u32 s100, 0
	s_cbranch_scc1 .Lgr_p1_1
	s_waitcnt vmcnt(8)
.Lgr_p1_1:
	s_waitcnt lgkmcnt(0)
	s_barrier
	s_setprio 1
	v_mfma_f32_16x16x32_bf16 v[60:63], v[152:155], v[184:187], v[60:63]
	v_mfma_f32_16x16x32_bf16 v[52:55], v[160:163], v[184:187], v[52:55]
	v_mfma_f32_16x16x32_bf16 v[44:47], v[152:155], v[192:195], v[44:47]
	v_mfma_f32_16x16x32_bf16 v[36:39], v[160:163], v[192:195], v[36:39]
	v_mfma_f32_16x16x32_bf16 v[28:31], v[152:155], v[200:203], v[28:31]
	v_mfma_f32_16x16x32_bf16 v[20:23], v[160:163], v[200:203], v[20:23]
	v_mfma_f32_16x16x32_bf16 v[12:15], v[152:155], v[210:213], v[12:15]
	v_mfma_f32_16x16x32_bf16 v[4:7], v[160:163], v[210:213], v[4:7]
	v_mfma_f32_16x16x32_bf16 v[60:63], v[156:159], v[188:191], v[60:63]
	v_mfma_f32_16x16x32_bf16 v[52:55], v[164:167], v[188:191], v[52:55]
	v_mfma_f32_16x16x32_bf16 v[44:47], v[156:159], v[196:199], v[44:47]
	v_mfma_f32_16x16x32_bf16 v[36:39], v[164:167], v[196:199], v[36:39]
	v_mfma_f32_16x16x32_bf16 v[28:31], v[156:159], v[206:209], v[28:31]
	v_mfma_f32_16x16x32_bf16 v[20:23], v[164:167], v[206:209], v[20:23]
	v_mfma_f32_16x16x32_bf16 v[12:15], v[156:159], v[214:217], v[12:15]
	v_mfma_f32_16x16x32_bf16 v[4:7], v[164:167], v[214:217], v[4:7]
	s_setprio 0
	s_setprio 1
	v_mfma_f32_16x16x32_bf16 v[56:59], v[168:171], v[184:187], v[56:59]
	v_mfma_f32_16x16x32_bf16 v[48:51], v[176:179], v[184:187], v[48:51]
	v_mfma_f32_16x16x32_bf16 v[40:43], v[168:171], v[192:195], v[40:43]
	v_mfma_f32_16x16x32_bf16 v[32:35], v[176:179], v[192:195], v[32:35]
	v_mfma_f32_16x16x32_bf16 v[24:27], v[168:171], v[200:203], v[24:27]
	v_mfma_f32_16x16x32_bf16 v[16:19], v[176:179], v[200:203], v[16:19]
	v_mfma_f32_16x16x32_bf16 v[8:11], v[168:171], v[210:213], v[8:11]
	v_mfma_f32_16x16x32_bf16 v[0:3], v[176:179], v[210:213], v[0:3]
	v_mfma_f32_16x16x32_bf16 v[56:59], v[172:175], v[188:191], v[56:59]
	v_mfma_f32_16x16x32_bf16 v[48:51], v[180:183], v[188:191], v[48:51]
	v_mfma_f32_16x16x32_bf16 v[40:43], v[172:175], v[196:199], v[40:43]
	v_mfma_f32_16x16x32_bf16 v[32:35], v[180:183], v[196:199], v[32:35]
	v_mfma_f32_16x16x32_bf16 v[24:27], v[172:175], v[206:209], v[24:27]
	v_mfma_f32_16x16x32_bf16 v[16:19], v[180:183], v[206:209], v[16:19]
	v_mfma_f32_16x16x32_bf16 v[8:11], v[172:175], v[214:217], v[8:11]
	v_mfma_f32_16x16x32_bf16 v[0:3], v[180:183], v[214:217], v[0:3]
	s_setprio 0
	s_barrier
	s_add_i32 s52, 0, 0x18000
	v_add_u32_e32 v151, s52, v145
	s_add_i32 s53, 0, 0x1c000
	ds_read_b128 v[152:155], v151
	ds_read_b128 v[156:159], v151 offset:1024
	ds_read_b128 v[160:163], v151 offset:2048
	ds_read_b128 v[164:167], v151 offset:3072
	v_add_u32_e32 v151, s53, v145
	ds_read_b128 v[168:171], v151
	ds_read_b128 v[172:175], v151 offset:1024
	ds_read_b128 v[176:179], v151 offset:2048
	ds_read_b128 v[180:183], v151 offset:3072
	s_add_u32 s26, s26, 0x80000
	s_addc_u32 s27, s27, 0
	s_mov_b32 m0, s31
	ds_read_b128 v[184:187], v149 offset:32768
	ds_read_b128 v[188:191], v149 offset:33792
	ds_read_b128 v[192:195], v149 offset:34816
	ds_read_b128 v[196:199], v149 offset:35840
	ds_read_b128 v[200:203], v149 offset:36864
	ds_read_b128 v[206:209], v149 offset:37888
	ds_read_b128 v[210:213], v149 offset:38912
	global_load_lds_dwordx4 v134, s[26:27]
	s_mov_b32 m0, s33
	ds_read_b128 v[214:217], v149 offset:39936
	global_load_lds_dwordx4 v130, s[26:27]
	s_cmp_lg_u32 s100, 0
	s_cbranch_scc1 .Lgr_p1_2
	s_waitcnt vmcnt(8)
; #define PG8_STAGE(bufoff, gbase, voff) do { _Pragma("unroll") for (int _i = 0; _i < 2; ++_i) \
;         __builtin_amdgcn_global_load_lds((const unsigned*)((const char*)(gbase) + (voff)[_i]), (PG8_LAS unsigned*)(lds + (bufoff) + ldsw + _i * 8192), 16, 0, 0); } while (0)
; #define PG8_LDA(dst, b, h) do { _Pragma("unroll") for (int m = 0; m < 4; ++m) _Pragma("unroll") for (int k = 0; k < 2; ++k) dst[m][k] = *(const PG8_LAS bf16x8*)(lds + PG8_SA(b, h) + aoff + m * 2048 + k * 1024); } while (0)
; #define PG8_MMA(ai, bj, At, Bt) do { __builtin_amdgcn_s_setprio(1); _Pragma("unroll") for (int m = 0; m < 4; ++m) _Pragma("unroll") for (int n = 0; n < 2; ++n) _Pragma("unroll") for (int k = 0; k < 2; ++k) \
;         acc[ai][bj][m][n] = __builtin_amdgcn_mfma_f32_16x16x32_bf16(Bt[n][k], At[m][k], acc[ai][bj][m][n], 0, 0, 0); __builtin_amdgcn_s_setprio(0); } while (0)
; #define PG8_WAIT_V(n) asm volatile("s_waitcnt vmcnt(" #n ")" ::: "memory")
; #define PG8_WAIT_L(n) asm volatile("s_waitcnt lgkmcnt(" #n ")" ::: "memory")
; #define PG8_BAR __builtin_amdgcn_s_barrier()
; #define PG8_SCHED __builtin_amdgcn_sched_barrier(0)
; template <class Epi, class Sched, bool ALIGN_EPI = false, bool SP2 = false>
; __device__ __forceinline__ void gemm_phase(PG8_LAS unsigned char* lds, const Gemm g, const Sched& S, const Epi& E) {
;     ...
;         for (int t = 0; t < nt; t += 2) {
;     ...
;             PG8_WAIT_V(8); PG8_WAIT_L(0); PG8_BAR; PG8_MMA(0, 0, At, B0); PG8_MMA(0, 1, At, B1); PG8_BAR; PG8_SCHED;
;             PG8_LDA(At, 1, 1); PG8_STAGE(PG8_SB(1, 0), b3, voffB); PG8_STAGE(PG8_SB(1, 1), b3 + hstep, voffB); PG8_STAGE(PG8_SA(1, 0), a3, voffA);
;             PG8_WAIT_V(8); PG8_WAIT_L(0); PG8_BAR; PG8_MMA(1, 0, At, B0); PG8_MMA(1, 1, At, B1); PG8_BAR; PG8_SCHED;
.Lgr_p1_2:
	s_waitcnt lgkmcnt(0)
	s_barrier
	s_setprio 1
	v_mfma_f32_16x16x32_bf16 v[116:119], v[152:155], v[184:187], v[116:119]
	v_mfma_f32_16x16x32_bf16 v[112:115], v[160:163], v[184:187], v[112:115]
	v_mfma_f32_16x16x32_bf16 v[108:111], v[152:155], v[192:195], v[108:111]
	v_mfma_f32_16x16x32_bf16 v[100:103], v[160:163], v[192:195], v[100:103]
	v_mfma_f32_16x16x32_bf16 v[92:95], v[152:155], v[200:203], v[92:95]
	v_mfma_f32_16x16x32_bf16 v[84:87], v[160:163], v[200:203], v[84:87]
	v_mfma_f32_16x16x32_bf16 v[76:79], v[152:155], v[210:213], v[76:79]
	v_mfma_f32_16x16x32_bf16 v[68:71], v[160:163], v[210:213], v[68:71]
	v_mfma_f32_16x16x32_bf16 v[116:119], v[156:159], v[188:191], v[116:119]
	v_mfma_f32_16x16x32_bf16 v[112:115], v[164:167], v[188:191], v[112:115]
	v_mfma_f32_16x16x32_bf16 v[108:111], v[156:159], v[196:199], v[108:111]
	v_mfma_f32_16x16x32_bf16 v[100:103], v[164:167], v[196:199], v[100:103]
	v_mfma_f32_16x16x32_bf16 v[92:95], v[156:159], v[206:209], v[92:95]
	v_mfma_f32_16x16x32_bf16 v[84:87], v[164:167], v[206:209], v[84:87]
	v_mfma_f32_16x16x32_bf16 v[76:79], v[156:159], v[214:217], v[76:79]
	v_mfma_f32_16x16x32_bf16 v[68:71], v[164:167], v[214:217], v[68:71]
	s_setprio 0
	s_setprio 1
	v_mfma_f32_16x16x32_bf16 v[124:127], v[168:171], v[184:187], v[124:127]
	v_mfma_f32_16x16x32_bf16 v[120:123], v[176:179], v[184:187], v[120:123]
	v_mfma_f32_16x16x32_bf16 v[104:107], v[168:171], v[192:195], v[104:107]
	v_mfma_f32_16x16x32_bf16 v[96:99], v[176:179], v[192:195], v[96:99]
	v_mfma_f32_16x16x32_bf16 v[88:91], v[168:171], v[200:203], v[88:91]
	v_mfma_f32_16x16x32_bf16 v[80:83], v[176:179], v[200:203], v[80:83]
	v_mfma_f32_16x16x32_bf16 v[72:75], v[168:171], v[210:213], v[72:75]
	v_mfma_f32_16x16x32_bf16 v[64:67], v[176:179], v[210:213], v[64:67]
	v_mfma_f32_16x16x32_bf16 v[124:127], v[172:175], v[188:191], v[124:127]
	v_mfma_f32_16x16x32_bf16 v[120:123], v[180:183], v[188:191], v[120:123]
	v_mfma_f32_16x16x32_bf16 v[104:107], v[172:175], v[196:199], v[104:107]
	v_mfma_f32_16x16x32_bf16 v[96:99], v[180:183], v[196:199], v[96:99]
	v_mfma_f32_16x16x32_bf16 v[88:91], v[172:175], v[206:209], v[88:91]
	v_mfma_f32_16x16x32_bf16 v[80:83], v[180:183], v[206:209], v[80:83]
	v_mfma_f32_16x16x32_bf16 v[72:75], v[172:175], v[214:217], v[72:75]
	v_mfma_f32_16x16x32_bf16 v[64:67], v[180:183], v[214:217], v[64:67]
	s_setprio 0
	s_barrier
	s_add_i32 s26, s52, s0
	s_mov_b32 m0, s26
	ds_read_b128 v[184:187], v149 offset:49152
	ds_read_b128 v[188:191], v149 offset:50176
	ds_read_b128 v[192:195], v149 offset:51200
	ds_read_b128 v[196:199], v149 offset:52224
	global_load_lds_dwordx4 v132, vcc
	s_add_i32 m0, s26, 0x2000
	s_add_u32 s24, s24, 0x80080
	s_addc_u32 s25, s25, 0
	s_add_i32 s26, s53, s0
	global_load_lds_dwordx4 v128, vcc
	s_mov_b32 m0, s26
	ds_read_b128 v[214:217], v149 offset:56320
	global_load_lds_dwordx4 v132, s[24:25]
	s_add_i32 m0, s26, 0x2000
	ds_read_b128 v[210:213], v149 offset:55296
	global_load_lds_dwordx4 v128, s[24:25]
	s_mov_b32 m0, s35
	ds_read_b128 v[206:209], v149 offset:54272
	global_load_lds_dwordx4 v134, s[98:99]
	s_mov_b32 m0, s40
	ds_read_b128 v[200:203], v149 offset:53248
	global_load_lds_dwordx4 v130, s[98:99]
	s_waitcnt vmcnt(8)
	s_waitcnt lgkmcnt(0)
	s_barrier
	s_setprio 1
	v_mfma_f32_16x16x32_bf16 v[60:63], v[152:155], v[184:187], v[60:63]
	v_mfma_f32_16x16x32_bf16 v[52:55], v[160:163], v[184:187], v[52:55]
	v_mfma_f32_16x16x32_bf16 v[44:47], v[152:155], v[192:195], v[44:47]
	v_mfma_f32_16x16x32_bf16 v[36:39], v[160:163], v[192:195], v[36:39]
	v_mfma_f32_16x16x32_bf16 v[28:31], v[152:155], v[200:203], v[28:31]
	v_mfma_f32_16x16x32_bf16 v[20:23], v[160:163], v[200:203], v[20:23]
	v_mfma_f32_16x16x32_bf16 v[12:15], v[152:155], v[210:213], v[12:15]
	v_mfma_f32_16x16x32_bf16 v[4:7], v[160:163], v[210:213], v[4:7]
	v_mfma_f32_16x16x32_bf16 v[60:63], v[156:159], v[188:191], v[60:63]
	v_mfma_f32_16x16x32_bf16 v[52:55], v[164:167], v[188:191], v[52:55]
	v_mfma_f32_16x16x32_bf16 v[44:47], v[156:159], v[196:199], v[44:47]
	v_mfma_f32_16x16x32_bf16 v[36:39], v[164:167], v[196:199], v[36:39]
	v_mfma_f32_16x16x32_bf16 v[28:31], v[156:159], v[206:209], v[28:31]
	v_mfma_f32_16x16x32_bf16 v[20:23], v[164:167], v[206:209], v[20:23]
	v_mfma_f32_16x16x32_bf16 v[12:15], v[156:159], v[214:217], v[12:15]
	v_mfma_f32_16x16x32_bf16 v[4:7], v[164:167], v[214:217], v[4:7]
	s_setprio 0
	s_setprio 1
	v_mfma_f32_16x16x32_bf16 v[56:59], v[168:171], v[184:187], v[56:59]
	v_mfma_f32_16x16x32_bf16 v[48:51], v[176:179], v[184:187], v[48:51]
	v_mfma_f32_16x16x32_bf16 v[40:43], v[168:171], v[192:195], v[40:43]
	v_mfma_f32_16x16x32_bf16 v[32:35], v[176:179], v[192:195], v[32:35]
	v_mfma_f32_16x16x32_bf16 v[24:27], v[168:171], v[200:203], v[24:27]
	v_mfma_f32_16x16x32_bf16 v[16:19], v[176:179], v[200:203], v[16:19]
	v_mfma_f32_16x16x32_bf16 v[8:11], v[168:171], v[210:213], v[8:11]
	v_mfma_f32_16x16x32_bf16 v[0:3], v[176:179], v[210:213], v[0:3]
	v_mfma_f32_16x16x32_bf16 v[56:59], v[172:175], v[188:191], v[56:59]
	v_mfma_f32_16x16x32_bf16 v[48:51], v[180:183], v[188:191], v[48:51]
	v_mfma_f32_16x16x32_bf16 v[40:43], v[172:175], v[196:199], v[40:43]
	v_mfma_f32_16x16x32_bf16 v[32:35], v[180:183], v[196:199], v[32:35]
	v_mfma_f32_16x16x32_bf16 v[24:27], v[172:175], v[206:209], v[24:27]
	v_mfma_f32_16x16x32_bf16 v[16:19], v[180:183], v[206:209], v[16:19]
	v_mfma_f32_16x16x32_bf16 v[8:11], v[172:175], v[214:217], v[8:11]
	v_mfma_f32_16x16x32_bf16 v[0:3], v[180:183], v[214:217], v[0:3]
	s_setprio 0
	s_barrier
	s_mov_b32 s100, 0
	s_add_i32 s51, s51, 2
	s_add_u32 s22, s22, 0x100
	s_addc_u32 s23, s23, 0
	s_add_u32 s49, s49, 0x100
	s_addc_u32 s50, s50, 0
	s_cmp_gt_u32 s51, 29
	s_cbranch_scc0 .LBB0_204
	s_and_b64 vcc, exec, s[12:13]
	s_cbranch_vccz .LBB0_207
	s_barrier

; #define PG8_STAGE(bufoff, gbase, voff) do { _Pragma("unroll") for (int _i = 0; _i < 2; ++_i) \
;         __builtin_amdgcn_global_load_lds((const unsigned*)((const char*)(gbase) + (voff)[_i]), (PG8_LAS unsigned*)(lds + (bufoff) + ldsw + _i * 8192), 16, 0, 0); } while (0)
; #define PG8_LDA(dst, b, h) do { _Pragma("unroll") for (int m = 0; m < 4; ++m) _Pragma("unroll") for (int k = 0; k < 2; ++k) dst[m][k] = *(const PG8_LAS bf16x8*)(lds + PG8_SA(b, h) + aoff + m * 2048 + k * 1024); } while (0)
; #define PG8_LDB(dst, b, h) do { _Pragma("unroll") for (int n = 0; n < 2; ++n) _Pragma("unroll") for (int k = 0; k < 2; ++k) dst[n][k] = *(const PG8_LAS bf16x8*)(lds + PG8_SB(b, h) + boff + n * 2048 + k * 1024); } while (0)
; #define PG8_MMA(ai, bj, At, Bt) do { __builtin_amdgcn_s_setprio(1); _Pragma("unroll") for (int m = 0; m < 4; ++m) _Pragma("unroll") for (int n = 0; n < 2; ++n) _Pragma("unroll") for (int k = 0; k < 2; ++k) \
;         acc[ai][bj][m][n] = __builtin_amdgcn_mfma_f32_16x16x32_bf16(Bt[n][k], At[m][k], acc[ai][bj][m][n], 0, 0, 0); __builtin_amdgcn_s_setprio(0); } while (0)
; #define PG8_WAIT_V(n) asm volatile("s_waitcnt vmcnt(" #n ")" ::: "memory")
; #define PG8_WAIT_L(n) asm volatile("s_waitcnt lgkmcnt(" #n ")" ::: "memory")
; template <class Epi, class Sched, bool ALIGN_EPI = false, bool SP2 = false>
; __device__ __forceinline__ void gemm_phase(PG8_LAS unsigned char* lds, const Gemm g, const Sched& S, const Epi& E) {
;     ...
;             const bool last = (t == nt - 2);
;             const char* a1 = cA + (size_t)(t + 1) * kstep;
;             const char* a2 = last ? nA : cA + (size_t)(t + 2) * kstep; const char* b2 = last ? nB : cB + (size_t)(t + 2) * kstep;
;             const char* a3 = a2 + kstep; const char* b3 = b2 + kstep;
;             if (last && has_next) S.a_ready(nxt);
;             if constexpr (SP2) {
;             PG8_LDB(B0, 0, 0); PG8_LDB(B1, 0, 1); PG8_SCHED; PG8_LDA(At, 0, 0); PG8_STAGE(PG8_SA(1, 1), a1 + hstep, voffA);
;             PG8_WAIT_V(8); PG8_WAIT_L(0); PG8_BAR; PG8_MMA(0, 0, At, B0); PG8_MMA(0, 1, At, B1); PG8_BAR; PG8_SCHED;
;             PG8_LDA(At, 0, 1); PG8_STAGE(PG8_SB(0, 0), b2, voffB); PG8_STAGE(PG8_SB(0, 1), b2 + hstep, voffB); PG8_STAGE(PG8_SA(0, 0), a2, voffA);
;             PG8_WAIT_V(8); PG8_WAIT_L(0); PG8_BAR; PG8_MMA(1, 0, At, B0); PG8_MMA(1, 1, At, B1); PG8_BAR; PG8_SCHED;
.LBB0_285:
	ds_read_b128 v[128:131], v208
	ds_read_b128 v[132:135], v208 offset:1024
	ds_read_b128 v[136:139], v208 offset:2048
	ds_read_b128 v[140:143], v208 offset:3072
	ds_read_b128 v[144:147], v209
	ds_read_b128 v[148:151], v209 offset:1024
	ds_read_b128 v[152:155], v209 offset:2048
	ds_read_b128 v[156:159], v209 offset:3072
	s_add_u32 s22, s20, 0xffea0080
	s_addc_u32 s23, s21, -1
	s_cmpk_eq_i32 s48, 0x54
	s_cselect_b32 s25, s7, s23
	s_cselect_b32 s24, s6, s22
	s_cselect_b32 s23, s19, s47
	s_cselect_b32 s22, s18, s46
	s_add_i32 m0, s1, 0xc000
	ds_read_b128 v[160:163], v210
	ds_read_b128 v[164:167], v210 offset:1024
	ds_read_b128 v[168:171], v210 offset:2048
	ds_read_b128 v[172:175], v210 offset:3072
	ds_read_b128 v[192:195], v210 offset:4096
	ds_read_b128 v[196:199], v210 offset:5120
	ds_read_b128 v[200:203], v210 offset:6144
	global_load_lds_dwordx4 v184, s[20:21]
	s_add_i32 m0, s1, 0xe000
	ds_read_b128 v[212:215], v210 offset:7168
	global_load_lds_dwordx4 v186, s[20:21]
	s_waitcnt vmcnt(8)
	s_waitcnt lgkmcnt(0)
	s_barrier
	s_setprio 1
	v_mfma_f32_16x16x32_bf16 v[124:127], v[128:131], v[160:163], v[124:127]
	v_mfma_f32_16x16x32_bf16 v[120:123], v[136:139], v[160:163], v[120:123]
	v_mfma_f32_16x16x32_bf16 v[108:111], v[128:131], v[168:171], v[108:111]
	v_mfma_f32_16x16x32_bf16 v[104:107], v[136:139], v[168:171], v[104:107]
	v_mfma_f32_16x16x32_bf16 v[92:95], v[128:131], v[192:195], v[92:95]
	v_mfma_f32_16x16x32_bf16 v[88:91], v[136:139], v[192:195], v[88:91]
	v_mfma_f32_16x16x32_bf16 v[76:79], v[128:131], v[200:203], v[76:79]
	v_mfma_f32_16x16x32_bf16 v[72:75], v[136:139], v[200:203], v[72:75]
	v_mfma_f32_16x16x32_bf16 v[124:127], v[132:135], v[164:167], v[124:127]
	v_mfma_f32_16x16x32_bf16 v[120:123], v[140:143], v[164:167], v[120:123]
	v_mfma_f32_16x16x32_bf16 v[108:111], v[132:135], v[172:175], v[108:111]
	v_mfma_f32_16x16x32_bf16 v[104:107], v[140:143], v[172:175], v[104:107]
	v_mfma_f32_16x16x32_bf16 v[92:95], v[132:135], v[196:199], v[92:95]
	v_mfma_f32_16x16x32_bf16 v[88:91], v[140:143], v[196:199], v[88:91]
	v_mfma_f32_16x16x32_bf16 v[76:79], v[132:135], v[212:215], v[76:79]
	v_mfma_f32_16x16x32_bf16 v[72:75], v[140:143], v[212:215], v[72:75]
	s_setprio 0
	s_setprio 1
	v_mfma_f32_16x16x32_bf16 v[116:119], v[144:147], v[160:163], v[116:119]
	v_mfma_f32_16x16x32_bf16 v[112:115], v[152:155], v[160:163], v[112:115]
	v_mfma_f32_16x16x32_bf16 v[100:103], v[144:147], v[168:171], v[100:103]
	v_mfma_f32_16x16x32_bf16 v[96:99], v[152:155], v[168:171], v[96:99]
	v_mfma_f32_16x16x32_bf16 v[84:87], v[144:147], v[192:195], v[84:87]
	v_mfma_f32_16x16x32_bf16 v[80:83], v[152:155], v[192:195], v[80:83]
	v_mfma_f32_16x16x32_bf16 v[68:71], v[144:147], v[200:203], v[68:71]
	v_mfma_f32_16x16x32_bf16 v[64:67], v[152:155], v[200:203], v[64:67]
	v_mfma_f32_16x16x32_bf16 v[116:119], v[148:151], v[164:167], v[116:119]
	v_mfma_f32_16x16x32_bf16 v[112:115], v[156:159], v[164:167], v[112:115]
	v_mfma_f32_16x16x32_bf16 v[100:103], v[148:151], v[172:175], v[100:103]
	v_mfma_f32_16x16x32_bf16 v[96:99], v[156:159], v[172:175], v[96:99]
	v_mfma_f32_16x16x32_bf16 v[84:87], v[148:151], v[196:199], v[84:87]
	v_mfma_f32_16x16x32_bf16 v[80:83], v[156:159], v[196:199], v[80:83]
	v_mfma_f32_16x16x32_bf16 v[68:71], v[148:151], v[212:215], v[68:71]
	v_mfma_f32_16x16x32_bf16 v[64:67], v[156:159], v[212:215], v[64:67]
	s_setprio 0
	s_barrier
	s_add_i32 s49, s40, s0
	s_add_u32 vcc_lo, s22, 0x80
	s_addc_u32 vcc_hi, s23, 0
	s_mov_b32 m0, s49
	ds_read_b128 v[160:163], v210 offset:16384
	ds_read_b128 v[164:167], v210 offset:17408
	ds_read_b128 v[168:171], v210 offset:18432
	ds_read_b128 v[172:175], v210 offset:19456
	global_load_lds_dwordx4 v178, s[22:23]
	s_add_i32 m0, s49, 0x2000
	s_add_u32 s50, s22, 0x160000
	s_addc_u32 s51, s23, 0
	s_add_i32 s49, s41, s0
	global_load_lds_dwordx4 v182, s[22:23]
	s_mov_b32 m0, s49
	ds_read_b128 v[212:215], v210 offset:23552
	global_load_lds_dwordx4 v178, s[50:51]
	s_add_i32 m0, s49, 0x2000
	ds_read_b128 v[200:203], v210 offset:22528
	global_load_lds_dwordx4 v182, s[50:51]
	s_add_u32 s98, s24, 0x80
	s_addc_u32 s99, s25, 0
	s_mov_b32 m0, s1
	ds_read_b128 v[196:199], v210 offset:21504
	global_load_lds_dwordx4 v176, s[24:25]
	s_mov_b32 m0, s26
	ds_read_b128 v[192:195], v210 offset:20480
	global_load_lds_dwordx4 v180, s[24:25]
	s_waitcnt vmcnt(8)
	s_waitcnt lgkmcnt(0)
	s_barrier
	s_setprio 1
	v_mfma_f32_16x16x32_bf16 v[60:63], v[128:131], v[160:163], v[60:63]
	v_mfma_f32_16x16x32_bf16 v[56:59], v[136:139], v[160:163], v[56:59]
	v_mfma_f32_16x16x32_bf16 v[44:47], v[128:131], v[168:171], v[44:47]
	v_mfma_f32_16x16x32_bf16 v[40:43], v[136:139], v[168:171], v[40:43]
	v_mfma_f32_16x16x32_bf16 v[28:31], v[128:131], v[192:195], v[28:31]
	v_mfma_f32_16x16x32_bf16 v[24:27], v[136:139], v[192:195], v[24:27]
	v_mfma_f32_16x16x32_bf16 v[12:15], v[128:131], v[200:203], v[12:15]
	v_mfma_f32_16x16x32_bf16 v[8:11], v[136:139], v[200:203], v[8:11]
	v_mfma_f32_16x16x32_bf16 v[60:63], v[132:135], v[164:167], v[60:63]
	v_mfma_f32_16x16x32_bf16 v[56:59], v[140:143], v[164:167], v[56:59]
	v_mfma_f32_16x16x32_bf16 v[44:47], v[132:135], v[172:175], v[44:47]
	v_mfma_f32_16x16x32_bf16 v[40:43], v[140:143], v[172:175], v[40:43]
	v_mfma_f32_16x16x32_bf16 v[28:31], v[132:135], v[196:199], v[28:31]
	v_mfma_f32_16x16x32_bf16 v[24:27], v[140:143], v[196:199], v[24:27]
	v_mfma_f32_16x16x32_bf16 v[12:15], v[132:135], v[212:215], v[12:15]
	v_mfma_f32_16x16x32_bf16 v[8:11], v[140:143], v[212:215], v[8:11]
	s_setprio 0
	s_setprio 1
	v_mfma_f32_16x16x32_bf16 v[52:55], v[144:147], v[160:163], v[52:55]
	v_mfma_f32_16x16x32_bf16 v[48:51], v[152:155], v[160:163], v[48:51]
	v_mfma_f32_16x16x32_bf16 v[36:39], v[144:147], v[168:171], v[36:39]
	v_mfma_f32_16x16x32_bf16 v[32:35], v[152:155], v[168:171], v[32:35]
	v_mfma_f32_16x16x32_bf16 v[20:23], v[144:147], v[192:195], v[20:23]
	v_mfma_f32_16x16x32_bf16 v[16:19], v[152:155], v[192:195], v[16:19]
	v_mfma_f32_16x16x32_bf16 v[4:7], v[144:147], v[200:203], v[4:7]
	v_mfma_f32_16x16x32_bf16 v[0:3], v[152:155], v[200:203], v[0:3]
	v_mfma_f32_16x16x32_bf16 v[52:55], v[148:151], v[164:167], v[52:55]
	v_mfma_f32_16x16x32_bf16 v[48:51], v[156:159], v[164:167], v[48:51]
	v_mfma_f32_16x16x32_bf16 v[36:39], v[148:151], v[172:175], v[36:39]
	v_mfma_f32_16x16x32_bf16 v[32:35], v[156:159], v[172:175], v[32:35]
	v_mfma_f32_16x16x32_bf16 v[20:23], v[148:151], v[196:199], v[20:23]
	v_mfma_f32_16x16x32_bf16 v[16:19], v[156:159], v[196:199], v[16:19]
	v_mfma_f32_16x16x32_bf16 v[4:7], v[148:151], v[212:215], v[4:7]
	v_mfma_f32_16x16x32_bf16 v[0:3], v[156:159], v[212:215], v[0:3]
	s_setprio 0
	s_barrier
; #define PG8_STAGE(bufoff, gbase, voff) do { _Pragma("unroll") for (int _i = 0; _i < 2; ++_i) \
;         __builtin_amdgcn_global_load_lds((const unsigned*)((const char*)(gbase) + (voff)[_i]), (PG8_LAS unsigned*)(lds + (bufoff) + ldsw + _i * 8192), 16, 0, 0); } while (0)
; #define PG8_LDA(dst, b, h) do { _Pragma("unroll") for (int m = 0; m < 4; ++m) _Pragma("unroll") for (int k = 0; k < 2; ++k) dst[m][k] = *(const PG8_LAS bf16x8*)(lds + PG8_SA(b, h) + aoff + m * 2048 + k * 1024); } while (0)
; #define PG8_LDB(dst, b, h) do { _Pragma("unroll") for (int n = 0; n < 2; ++n) _Pragma("unroll") for (int k = 0; k < 2; ++k) dst[n][k] = *(const PG8_LAS bf16x8*)(lds + PG8_SB(b, h) + boff + n * 2048 + k * 1024); } while (0)
; #define PG8_MMA(ai, bj, At, Bt) do { __builtin_amdgcn_s_setprio(1); _Pragma("unroll") for (int m = 0; m < 4; ++m) _Pragma("unroll") for (int n = 0; n < 2; ++n) _Pragma("unroll") for (int k = 0; k < 2; ++k) \
;         acc[ai][bj][m][n] = __builtin_amdgcn_mfma_f32_16x16x32_bf16(Bt[n][k], At[m][k], acc[ai][bj][m][n], 0, 0, 0); __builtin_amdgcn_s_setprio(0); } while (0)
; #define PG8_WAIT_V(n) asm volatile("s_waitcnt vmcnt(" #n ")" ::: "memory")
; #define PG8_WAIT_L(n) asm volatile("s_waitcnt lgkmcnt(" #n ")" ::: "memory")
; #define PG8_BAR __builtin_amdgcn_s_barrier()
; #define PG8_SCHED __builtin_amdgcn_sched_barrier(0)
; template <class Epi, class Sched, bool ALIGN_EPI = false, bool SP2 = false>
; __device__ __forceinline__ void gemm_phase(PG8_LAS unsigned char* lds, const Gemm g, const Sched& S, const Epi& E) {
;     ...
;         for (int t = 0; t < nt; t += 2) {
;     ...
;             PG8_LDB(B0, 1, 0); PG8_LDB(B1, 1, 1); PG8_SCHED; PG8_LDA(At, 1, 0); PG8_STAGE(PG8_SA(0, 1), a2 + hstep, voffA);
;             PG8_WAIT_V(8); PG8_WAIT_L(0); PG8_BAR; PG8_MMA(0, 0, At, B0); PG8_MMA(0, 1, At, B1); PG8_BAR; PG8_SCHED;
;             PG8_LDA(At, 1, 1); PG8_STAGE(PG8_SB(1, 0), b3, voffB); PG8_STAGE(PG8_SB(1, 1), b3 + hstep, voffB); PG8_STAGE(PG8_SA(1, 0), a3, voffA);
;             PG8_WAIT_V(8); PG8_WAIT_L(0); PG8_BAR; PG8_MMA(1, 0, At, B0); PG8_MMA(1, 1, At, B1); PG8_BAR; PG8_SCHED;
	s_add_i32 s49, 0, 0x18000
	s_add_i32 s50, 0, 0x1c000
	v_add_u32_e32 v140, s49, v206
	v_add_u32_e32 v156, s50, v206
	ds_read_b128 v[128:131], v140
	ds_read_b128 v[132:135], v140 offset:1024
	ds_read_b128 v[136:139], v140 offset:2048
	ds_read_b128 v[140:143], v140 offset:3072
	ds_read_b128 v[144:147], v156
	ds_read_b128 v[148:151], v156 offset:1024
	ds_read_b128 v[152:155], v156 offset:2048
	ds_read_b128 v[156:159], v156 offset:3072
	s_add_u32 s24, s24, 0x160000
	s_addc_u32 s25, s25, 0
	s_mov_b32 m0, s27
	ds_read_b128 v[160:163], v210 offset:32768
	ds_read_b128 v[164:167], v210 offset:33792
	ds_read_b128 v[168:171], v210 offset:34816
	ds_read_b128 v[172:175], v210 offset:35840
	ds_read_b128 v[192:195], v210 offset:36864
	ds_read_b128 v[196:199], v210 offset:37888
	ds_read_b128 v[200:203], v210 offset:38912
	global_load_lds_dwordx4 v176, s[24:25]
	s_mov_b32 m0, s28
	ds_read_b128 v[212:215], v210 offset:39936
	global_load_lds_dwordx4 v180, s[24:25]
	s_waitcnt vmcnt(8)
	s_waitcnt lgkmcnt(0)
	s_barrier
	s_setprio 1
	v_mfma_f32_16x16x32_bf16 v[124:127], v[128:131], v[160:163], v[124:127]
	v_mfma_f32_16x16x32_bf16 v[120:123], v[136:139], v[160:163], v[120:123]
	v_mfma_f32_16x16x32_bf16 v[108:111], v[128:131], v[168:171], v[108:111]
	v_mfma_f32_16x16x32_bf16 v[104:107], v[136:139], v[168:171], v[104:107]
	v_mfma_f32_16x16x32_bf16 v[92:95], v[128:131], v[192:195], v[92:95]
	v_mfma_f32_16x16x32_bf16 v[88:91], v[136:139], v[192:195], v[88:91]
	v_mfma_f32_16x16x32_bf16 v[76:79], v[128:131], v[200:203], v[76:79]
	v_mfma_f32_16x16x32_bf16 v[72:75], v[136:139], v[200:203], v[72:75]
	v_mfma_f32_16x16x32_bf16 v[124:127], v[132:135], v[164:167], v[124:127]
	v_mfma_f32_16x16x32_bf16 v[120:123], v[140:143], v[164:167], v[120:123]
	v_mfma_f32_16x16x32_bf16 v[108:111], v[132:135], v[172:175], v[108:111]
	v_mfma_f32_16x16x32_bf16 v[104:107], v[140:143], v[172:175], v[104:107]
	v_mfma_f32_16x16x32_bf16 v[92:95], v[132:135], v[196:199], v[92:95]
	v_mfma_f32_16x16x32_bf16 v[88:91], v[140:143], v[196:199], v[88:91]
	v_mfma_f32_16x16x32_bf16 v[76:79], v[132:135], v[212:215], v[76:79]
	v_mfma_f32_16x16x32_bf16 v[72:75], v[140:143], v[212:215], v[72:75]
	s_setprio 0
	s_setprio 1
	v_mfma_f32_16x16x32_bf16 v[116:119], v[144:147], v[160:163], v[116:119]
	v_mfma_f32_16x16x32_bf16 v[112:115], v[152:155], v[160:163], v[112:115]
	v_mfma_f32_16x16x32_bf16 v[100:103], v[144:147], v[168:171], v[100:103]
	v_mfma_f32_16x16x32_bf16 v[96:99], v[152:155], v[168:171], v[96:99]
	v_mfma_f32_16x16x32_bf16 v[84:87], v[144:147], v[192:195], v[84:87]
	v_mfma_f32_16x16x32_bf16 v[80:83], v[152:155], v[192:195], v[80:83]
	v_mfma_f32_16x16x32_bf16 v[68:71], v[144:147], v[200:203], v[68:71]
	v_mfma_f32_16x16x32_bf16 v[64:67], v[152:155], v[200:203], v[64:67]
	v_mfma_f32_16x16x32_bf16 v[116:119], v[148:151], v[164:167], v[116:119]
	v_mfma_f32_16x16x32_bf16 v[112:115], v[156:159], v[164:167], v[112:115]
	v_mfma_f32_16x16x32_bf16 v[100:103], v[148:151], v[172:175], v[100:103]
	v_mfma_f32_16x16x32_bf16 v[96:99], v[156:159], v[172:175], v[96:99]
	v_mfma_f32_16x16x32_bf16 v[84:87], v[148:151], v[196:199], v[84:87]
	v_mfma_f32_16x16x32_bf16 v[80:83], v[156:159], v[196:199], v[80:83]
	v_mfma_f32_16x16x32_bf16 v[68:71], v[148:151], v[212:215], v[68:71]
	v_mfma_f32_16x16x32_bf16 v[64:67], v[156:159], v[212:215], v[64:67]
	s_setprio 0
	s_barrier
	s_add_i32 s24, s49, s0
	s_mov_b32 m0, s24
	ds_read_b128 v[160:163], v210 offset:49152
	ds_read_b128 v[164:167], v210 offset:50176
	ds_read_b128 v[168:171], v210 offset:51200
	ds_read_b128 v[172:175], v210 offset:52224
	global_load_lds_dwordx4 v178, vcc
	s_add_i32 m0, s24, 0x2000
	s_add_u32 s22, s22, 0x160080
	s_addc_u32 s23, s23, 0
	s_add_i32 s24, s50, s0
	global_load_lds_dwordx4 v182, vcc
	s_mov_b32 m0, s24
	ds_read_b128 v[212:215], v210 offset:56320
	global_load_lds_dwordx4 v178, s[22:23]
	s_add_i32 m0, s24, 0x2000
	ds_read_b128 v[200:203], v210 offset:55296
	global_load_lds_dwordx4 v182, s[22:23]
	s_mov_b32 m0, s30
	ds_read_b128 v[196:199], v210 offset:54272
	global_load_lds_dwordx4 v176, s[98:99]
	s_mov_b32 m0, s31
	ds_read_b128 v[192:195], v210 offset:53248
	global_load_lds_dwordx4 v180, s[98:99]
	s_waitcnt vmcnt(8)
	s_waitcnt lgkmcnt(0)
	s_barrier
	s_setprio 1
	v_mfma_f32_16x16x32_bf16 v[60:63], v[128:131], v[160:163], v[60:63]
	v_mfma_f32_16x16x32_bf16 v[56:59], v[136:139], v[160:163], v[56:59]
	v_mfma_f32_16x16x32_bf16 v[44:47], v[128:131], v[168:171], v[44:47]
	v_mfma_f32_16x16x32_bf16 v[40:43], v[136:139], v[168:171], v[40:43]
	v_mfma_f32_16x16x32_bf16 v[28:31], v[128:131], v[192:195], v[28:31]
	v_mfma_f32_16x16x32_bf16 v[24:27], v[136:139], v[192:195], v[24:27]
	v_mfma_f32_16x16x32_bf16 v[12:15], v[128:131], v[200:203], v[12:15]
	v_mfma_f32_16x16x32_bf16 v[8:11], v[136:139], v[200:203], v[8:11]
	v_mfma_f32_16x16x32_bf16 v[60:63], v[132:135], v[164:167], v[60:63]
	v_mfma_f32_16x16x32_bf16 v[56:59], v[140:143], v[164:167], v[56:59]
	v_mfma_f32_16x16x32_bf16 v[44:47], v[132:135], v[172:175], v[44:47]
	v_mfma_f32_16x16x32_bf16 v[40:43], v[140:143], v[172:175], v[40:43]
	v_mfma_f32_16x16x32_bf16 v[28:31], v[132:135], v[196:199], v[28:31]
	v_mfma_f32_16x16x32_bf16 v[24:27], v[140:143], v[196:199], v[24:27]
	v_mfma_f32_16x16x32_bf16 v[12:15], v[132:135], v[212:215], v[12:15]
	v_mfma_f32_16x16x32_bf16 v[8:11], v[140:143], v[212:215], v[8:11]
	s_setprio 0
	s_setprio 1
	v_mfma_f32_16x16x32_bf16 v[52:55], v[144:147], v[160:163], v[52:55]
	v_mfma_f32_16x16x32_bf16 v[48:51], v[152:155], v[160:163], v[48:51]
	v_mfma_f32_16x16x32_bf16 v[36:39], v[144:147], v[168:171], v[36:39]
	v_mfma_f32_16x16x32_bf16 v[32:35], v[152:155], v[168:171], v[32:35]
	v_mfma_f32_16x16x32_bf16 v[20:23], v[144:147], v[192:195], v[20:23]
	v_mfma_f32_16x16x32_bf16 v[16:19], v[152:155], v[192:195], v[16:19]
	v_mfma_f32_16x16x32_bf16 v[4:7], v[144:147], v[200:203], v[4:7]
	v_mfma_f32_16x16x32_bf16 v[0:3], v[152:155], v[200:203], v[0:3]
	v_mfma_f32_16x16x32_bf16 v[52:55], v[148:151], v[164:167], v[52:55]
	v_mfma_f32_16x16x32_bf16 v[48:51], v[156:159], v[164:167], v[48:51]
	v_mfma_f32_16x16x32_bf16 v[36:39], v[148:151], v[172:175], v[36:39]
	v_mfma_f32_16x16x32_bf16 v[32:35], v[156:159], v[172:175], v[32:35]
	v_mfma_f32_16x16x32_bf16 v[20:23], v[148:151], v[196:199], v[20:23]
	v_mfma_f32_16x16x32_bf16 v[16:19], v[156:159], v[196:199], v[16:19]
	v_mfma_f32_16x16x32_bf16 v[4:7], v[148:151], v[212:215], v[4:7]
	v_mfma_f32_16x16x32_bf16 v[0:3], v[156:159], v[212:215], v[0:3]
	s_setprio 0
	s_barrier
	s_add_i32 s48, s48, 2
	s_add_u32 s20, s20, 0x100
	s_addc_u32 s21, s21, 0
	s_add_u32 s46, s46, 0x100
	s_addc_u32 s47, s47, 0
	s_cmpk_gt_u32 s48, 0x55
	s_cbranch_scc0 .LBB0_285
	s_and_b64 vcc, exec, s[16:17]
	s_cbranch_vccz .LBB0_288
	s_barrier

; #define PG8_STAGE(bufoff, gbase, voff) do { _Pragma("unroll") for (int _i = 0; _i < 2; ++_i) \
;         __builtin_amdgcn_global_load_lds((const unsigned*)((const char*)(gbase) + (voff)[_i]), (PG8_LAS unsigned*)(lds + (bufoff) + ldsw + _i * 8192), 16, 0, 0); } while (0)
; #define PG8_LDA(dst, b, h) do { _Pragma("unroll") for (int m = 0; m < 4; ++m) _Pragma("unroll") for (int k = 0; k < 2; ++k) dst[m][k] = *(const PG8_LAS bf16x8*)(lds + PG8_SA(b, h) + aoff + m * 2048 + k * 1024); } while (0)
; #define PG8_LDB(dst, b, h) do { _Pragma("unroll") for (int n = 0; n < 2; ++n) _Pragma("unroll") for (int k = 0; k < 2; ++k) dst[n][k] = *(const PG8_LAS bf16x8*)(lds + PG8_SB(b, h) + boff + n * 2048 + k * 1024); } while (0)
; #define PG8_MMA(ai, bj, At, Bt) do { __builtin_amdgcn_s_setprio(1); _Pragma("unroll") for (int m = 0; m < 4; ++m) _Pragma("unroll") for (int n = 0; n < 2; ++n) _Pragma("unroll") for (int k = 0; k < 2; ++k) \
;         acc[ai][bj][m][n] = __builtin_amdgcn_mfma_f32_16x16x32_bf16(Bt[n][k], At[m][k], acc[ai][bj][m][n], 0, 0, 0); __builtin_amdgcn_s_setprio(0); } while (0)
; #define PG8_WAIT_V(n) asm volatile("s_waitcnt vmcnt(" #n ")" ::: "memory")
; #define PG8_WAIT_L(n) asm volatile("s_waitcnt lgkmcnt(" #n ")" ::: "memory")
; #define PG8_BAR __builtin_amdgcn_s_barrier()
; #define PG8_SCHED __builtin_amdgcn_sched_barrier(0)
; template <class Epi, class Sched, bool ALIGN_EPI = false, bool SP2 = false>
; __device__ __forceinline__ void gemm_phase(PG8_LAS unsigned char* lds, const Gemm g, const Sched& S, const Epi& E) {
;     ...
;             PG8_WAIT_V(8); PG8_WAIT_L(0); PG8_BAR; PG8_MMA(0, 0, At, B0); PG8_MMA(0, 1, At, B1); PG8_BAR; PG8_SCHED;
;             PG8_LDA(At, 0, 1); PG8_STAGE(PG8_SB(0, 0), b2, voffB); PG8_STAGE(PG8_SB(0, 1), b2 + hstep, voffB); PG8_STAGE(PG8_SA(0, 0), a2, voffA);
;             PG8_WAIT_V(8); PG8_WAIT_L(0); PG8_BAR; PG8_MMA(1, 0, At, B0); PG8_MMA(1, 1, At, B1); PG8_BAR; PG8_SCHED;
;             PG8_LDB(B0, 1, 0); PG8_LDB(B1, 1, 1); PG8_SCHED; PG8_LDA(At, 1, 0); PG8_STAGE(PG8_SA(0, 1), a2 + hstep, voffA);
.Lgr_p3_0:
	s_waitcnt lgkmcnt(0)
	s_barrier
	s_setprio 1
	v_mfma_f32_16x16x32_bf16 v[124:127], v[128:131], v[190:193], v[124:127]
	v_mfma_f32_16x16x32_bf16 v[120:123], v[156:159], v[190:193], v[120:123]
	v_mfma_f32_16x16x32_bf16 v[108:111], v[128:131], v[198:201], v[108:111]
	v_mfma_f32_16x16x32_bf16 v[104:107], v[156:159], v[198:201], v[104:107]
	v_mfma_f32_16x16x32_bf16 v[92:95], v[128:131], v[210:213], v[92:95]
	v_mfma_f32_16x16x32_bf16 v[88:91], v[156:159], v[210:213], v[88:91]
	v_mfma_f32_16x16x32_bf16 v[76:79], v[128:131], v[222:225], v[76:79]
	v_mfma_f32_16x16x32_bf16 v[72:75], v[156:159], v[222:225], v[72:75]
	v_mfma_f32_16x16x32_bf16 v[124:127], v[132:135], v[194:197], v[124:127]
	v_mfma_f32_16x16x32_bf16 v[120:123], v[160:163], v[194:197], v[120:123]
	v_mfma_f32_16x16x32_bf16 v[108:111], v[132:135], v[206:209], v[108:111]
	v_mfma_f32_16x16x32_bf16 v[104:107], v[160:163], v[206:209], v[104:107]
	v_mfma_f32_16x16x32_bf16 v[92:95], v[132:135], v[214:217], v[92:95]
	v_mfma_f32_16x16x32_bf16 v[88:91], v[160:163], v[214:217], v[88:91]
	v_mfma_f32_16x16x32_bf16 v[76:79], v[132:135], v[226:229], v[76:79]
	v_mfma_f32_16x16x32_bf16 v[72:75], v[160:163], v[226:229], v[72:75]
	s_setprio 0
	s_setprio 1
	v_mfma_f32_16x16x32_bf16 v[116:119], v[164:167], v[190:193], v[116:119]
	v_mfma_f32_16x16x32_bf16 v[112:115], v[182:185], v[190:193], v[112:115]
	v_mfma_f32_16x16x32_bf16 v[100:103], v[164:167], v[198:201], v[100:103]
	v_mfma_f32_16x16x32_bf16 v[96:99], v[182:185], v[198:201], v[96:99]
	v_mfma_f32_16x16x32_bf16 v[84:87], v[164:167], v[210:213], v[84:87]
	v_mfma_f32_16x16x32_bf16 v[80:83], v[182:185], v[210:213], v[80:83]
	v_mfma_f32_16x16x32_bf16 v[68:71], v[164:167], v[222:225], v[68:71]
	v_mfma_f32_16x16x32_bf16 v[64:67], v[182:185], v[222:225], v[64:67]
	v_mfma_f32_16x16x32_bf16 v[116:119], v[178:181], v[194:197], v[116:119]
	v_mfma_f32_16x16x32_bf16 v[112:115], v[186:189], v[194:197], v[112:115]
	v_mfma_f32_16x16x32_bf16 v[100:103], v[178:181], v[206:209], v[100:103]
	v_mfma_f32_16x16x32_bf16 v[96:99], v[186:189], v[206:209], v[96:99]
	v_mfma_f32_16x16x32_bf16 v[84:87], v[178:181], v[214:217], v[84:87]
	v_mfma_f32_16x16x32_bf16 v[80:83], v[186:189], v[214:217], v[80:83]
	v_mfma_f32_16x16x32_bf16 v[68:71], v[178:181], v[226:229], v[68:71]
	v_mfma_f32_16x16x32_bf16 v[64:67], v[186:189], v[226:229], v[64:67]
	s_setprio 0
	s_barrier
	s_add_i32 s69, s53, s0
	s_add_u32 vcc_lo, s6, 0x80
	s_addc_u32 vcc_hi, s7, 0
	s_mov_b32 m0, s69
	ds_read_b128 v[190:193], v175 offset:16384
	ds_read_b128 v[194:197], v175 offset:17408
	ds_read_b128 v[198:201], v175 offset:18432
	ds_read_b128 v[206:209], v175 offset:19456
	global_load_lds_dwordx4 v138, s[6:7]
	s_add_i32 m0, s69, 0x2000
	s_add_u32 s70, s6, 0x80000
	s_addc_u32 s71, s7, 0
	s_add_i32 s69, s54, s0
	global_load_lds_dwordx4 v142, s[6:7]
	s_mov_b32 m0, s69
	ds_read_b128 v[226:229], v175 offset:23552
	global_load_lds_dwordx4 v138, s[70:71]
	s_add_i32 m0, s69, 0x2000
	ds_read_b128 v[222:225], v175 offset:22528
	global_load_lds_dwordx4 v142, s[70:71]
	s_add_u32 s98, s42, 0x80
	s_addc_u32 s99, s43, 0
	s_mov_b32 m0, s1
	ds_read_b128 v[214:217], v175 offset:21504
	global_load_lds_dwordx4 v136, s[42:43]
	s_mov_b32 m0, s33
	ds_read_b128 v[210:213], v175 offset:20480
	global_load_lds_dwordx4 v140, s[42:43]
	s_cmp_lg_u32 s100, 0
	s_cbranch_scc1 .Lgr_p3_1
	s_waitcnt vmcnt(8)
.Lgr_p3_1:
	s_waitcnt lgkmcnt(0)
	s_barrier
	s_setprio 1
	v_mfma_f32_16x16x32_bf16 v[60:63], v[128:131], v[190:193], v[60:63]
	v_mfma_f32_16x16x32_bf16 v[56:59], v[156:159], v[190:193], v[56:59]
	v_mfma_f32_16x16x32_bf16 v[44:47], v[128:131], v[198:201], v[44:47]
	v_mfma_f32_16x16x32_bf16 v[40:43], v[156:159], v[198:201], v[40:43]
	v_mfma_f32_16x16x32_bf16 v[28:31], v[128:131], v[210:213], v[28:31]
	v_mfma_f32_16x16x32_bf16 v[24:27], v[156:159], v[210:213], v[24:27]
	v_mfma_f32_16x16x32_bf16 v[12:15], v[128:131], v[222:225], v[12:15]
	v_mfma_f32_16x16x32_bf16 v[8:11], v[156:159], v[222:225], v[8:11]
	v_mfma_f32_16x16x32_bf16 v[60:63], v[132:135], v[194:197], v[60:63]
	v_mfma_f32_16x16x32_bf16 v[56:59], v[160:163], v[194:197], v[56:59]
	v_mfma_f32_16x16x32_bf16 v[44:47], v[132:135], v[206:209], v[44:47]
	v_mfma_f32_16x16x32_bf16 v[40:43], v[160:163], v[206:209], v[40:43]
	v_mfma_f32_16x16x32_bf16 v[28:31], v[132:135], v[214:217], v[28:31]
	v_mfma_f32_16x16x32_bf16 v[24:27], v[160:163], v[214:217], v[24:27]
	v_mfma_f32_16x16x32_bf16 v[12:15], v[132:135], v[226:229], v[12:15]
	v_mfma_f32_16x16x32_bf16 v[8:11], v[160:163], v[226:229], v[8:11]
	s_setprio 0
	s_setprio 1
	v_mfma_f32_16x16x32_bf16 v[52:55], v[164:167], v[190:193], v[52:55]
	v_mfma_f32_16x16x32_bf16 v[48:51], v[182:185], v[190:193], v[48:51]
	v_mfma_f32_16x16x32_bf16 v[36:39], v[164:167], v[198:201], v[36:39]
	v_mfma_f32_16x16x32_bf16 v[32:35], v[182:185], v[198:201], v[32:35]
	v_mfma_f32_16x16x32_bf16 v[20:23], v[164:167], v[210:213], v[20:23]
	v_mfma_f32_16x16x32_bf16 v[16:19], v[182:185], v[210:213], v[16:19]
	v_mfma_f32_16x16x32_bf16 v[4:7], v[164:167], v[222:225], v[4:7]
	v_mfma_f32_16x16x32_bf16 v[0:3], v[182:185], v[222:225], v[0:3]
	v_mfma_f32_16x16x32_bf16 v[52:55], v[178:181], v[194:197], v[52:55]
	v_mfma_f32_16x16x32_bf16 v[48:51], v[186:189], v[194:197], v[48:51]
	v_mfma_f32_16x16x32_bf16 v[36:39], v[178:181], v[206:209], v[36:39]
	v_mfma_f32_16x16x32_bf16 v[32:35], v[186:189], v[206:209], v[32:35]
	v_mfma_f32_16x16x32_bf16 v[20:23], v[178:181], v[214:217], v[20:23]
	v_mfma_f32_16x16x32_bf16 v[16:19], v[186:189], v[214:217], v[16:19]
	v_mfma_f32_16x16x32_bf16 v[4:7], v[178:181], v[226:229], v[4:7]
	v_mfma_f32_16x16x32_bf16 v[0:3], v[186:189], v[226:229], v[0:3]
	s_setprio 0
	s_barrier
	s_add_i32 s69, 0, 0x18000
	v_add_u32_e32 v144, s69, v171
	s_add_i32 s70, 0, 0x1c000
	ds_read_b128 v[128:131], v144
	ds_read_b128 v[132:135], v144 offset:1024
	ds_read_b128 v[156:159], v144 offset:2048
	ds_read_b128 v[160:163], v144 offset:3072
	v_add_u32_e32 v144, s70, v171
	ds_read_b128 v[164:167], v144
	ds_read_b128 v[178:181], v144 offset:1024
	ds_read_b128 v[182:185], v144 offset:2048
	ds_read_b128 v[186:189], v144 offset:3072
	s_add_u32 s42, s42, 0x80000
	s_addc_u32 s43, s43, 0
	s_mov_b32 m0, s37
	ds_read_b128 v[190:193], v175 offset:32768
	ds_read_b128 v[194:197], v175 offset:33792
	ds_read_b128 v[198:201], v175 offset:34816
	ds_read_b128 v[206:209], v175 offset:35840
	ds_read_b128 v[210:213], v175 offset:36864
	ds_read_b128 v[214:217], v175 offset:37888
	ds_read_b128 v[222:225], v175 offset:38912
	global_load_lds_dwordx4 v136, s[42:43]
	s_mov_b32 m0, s41
	ds_read_b128 v[226:229], v175 offset:39936
	global_load_lds_dwordx4 v140, s[42:43]
	s_cmp_lg_u32 s100, 0
	s_cbranch_scc1 .Lgr_p3_2
	s_waitcnt vmcnt(8)
; #define PG8_STAGE(bufoff, gbase, voff) do { _Pragma("unroll") for (int _i = 0; _i < 2; ++_i) \
;         __builtin_amdgcn_global_load_lds((const unsigned*)((const char*)(gbase) + (voff)[_i]), (PG8_LAS unsigned*)(lds + (bufoff) + ldsw + _i * 8192), 16, 0, 0); } while (0)
; #define PG8_LDA(dst, b, h) do { _Pragma("unroll") for (int m = 0; m < 4; ++m) _Pragma("unroll") for (int k = 0; k < 2; ++k) dst[m][k] = *(const PG8_LAS bf16x8*)(lds + PG8_SA(b, h) + aoff + m * 2048 + k * 1024); } while (0)
; #define PG8_MMA(ai, bj, At, Bt) do { __builtin_amdgcn_s_setprio(1); _Pragma("unroll") for (int m = 0; m < 4; ++m) _Pragma("unroll") for (int n = 0; n < 2; ++n) _Pragma("unroll") for (int k = 0; k < 2; ++k) \
;         acc[ai][bj][m][n] = __builtin_amdgcn_mfma_f32_16x16x32_bf16(Bt[n][k], At[m][k], acc[ai][bj][m][n], 0, 0, 0); __builtin_amdgcn_s_setprio(0); } while (0)
; #define PG8_WAIT_V(n) asm volatile("s_waitcnt vmcnt(" #n ")" ::: "memory")
; #define PG8_WAIT_L(n) asm volatile("s_waitcnt lgkmcnt(" #n ")" ::: "memory")
; #define PG8_BAR __builtin_amdgcn_s_barrier()
; #define PG8_SCHED __builtin_amdgcn_sched_barrier(0)
; template <class Epi, class Sched, bool ALIGN_EPI = false, bool SP2 = false>
; __device__ __forceinline__ void gemm_phase(PG8_LAS unsigned char* lds, const Gemm g, const Sched& S, const Epi& E) {
;     ...
;         for (int t = 0; t < nt; t += 2) {
;     ...
;             PG8_WAIT_V(8); PG8_WAIT_L(0); PG8_BAR; PG8_MMA(0, 0, At, B0); PG8_MMA(0, 1, At, B1); PG8_BAR; PG8_SCHED;
;             PG8_LDA(At, 1, 1); PG8_STAGE(PG8_SB(1, 0), b3, voffB); PG8_STAGE(PG8_SB(1, 1), b3 + hstep, voffB); PG8_STAGE(PG8_SA(1, 0), a3, voffA);
;             PG8_WAIT_V(8); PG8_WAIT_L(0); PG8_BAR; PG8_MMA(1, 0, At, B0); PG8_MMA(1, 1, At, B1); PG8_BAR; PG8_SCHED;
.Lgr_p3_2:
	s_waitcnt lgkmcnt(0)
	s_barrier
	s_setprio 1
	v_mfma_f32_16x16x32_bf16 v[124:127], v[128:131], v[190:193], v[124:127]
	v_mfma_f32_16x16x32_bf16 v[120:123], v[156:159], v[190:193], v[120:123]
	v_mfma_f32_16x16x32_bf16 v[108:111], v[128:131], v[198:201], v[108:111]
	v_mfma_f32_16x16x32_bf16 v[104:107], v[156:159], v[198:201], v[104:107]
	v_mfma_f32_16x16x32_bf16 v[92:95], v[128:131], v[210:213], v[92:95]
	v_mfma_f32_16x16x32_bf16 v[88:91], v[156:159], v[210:213], v[88:91]
	v_mfma_f32_16x16x32_bf16 v[76:79], v[128:131], v[222:225], v[76:79]
	v_mfma_f32_16x16x32_bf16 v[72:75], v[156:159], v[222:225], v[72:75]
	v_mfma_f32_16x16x32_bf16 v[124:127], v[132:135], v[194:197], v[124:127]
	v_mfma_f32_16x16x32_bf16 v[120:123], v[160:163], v[194:197], v[120:123]
	v_mfma_f32_16x16x32_bf16 v[108:111], v[132:135], v[206:209], v[108:111]
	v_mfma_f32_16x16x32_bf16 v[104:107], v[160:163], v[206:209], v[104:107]
	v_mfma_f32_16x16x32_bf16 v[92:95], v[132:135], v[214:217], v[92:95]
	v_mfma_f32_16x16x32_bf16 v[88:91], v[160:163], v[214:217], v[88:91]
	v_mfma_f32_16x16x32_bf16 v[76:79], v[132:135], v[226:229], v[76:79]
	v_mfma_f32_16x16x32_bf16 v[72:75], v[160:163], v[226:229], v[72:75]
	s_setprio 0
	s_setprio 1
	v_mfma_f32_16x16x32_bf16 v[116:119], v[164:167], v[190:193], v[116:119]
	v_mfma_f32_16x16x32_bf16 v[112:115], v[182:185], v[190:193], v[112:115]
	v_mfma_f32_16x16x32_bf16 v[100:103], v[164:167], v[198:201], v[100:103]
	v_mfma_f32_16x16x32_bf16 v[96:99], v[182:185], v[198:201], v[96:99]
	v_mfma_f32_16x16x32_bf16 v[84:87], v[164:167], v[210:213], v[84:87]
	v_mfma_f32_16x16x32_bf16 v[80:83], v[182:185], v[210:213], v[80:83]
	v_mfma_f32_16x16x32_bf16 v[68:71], v[164:167], v[222:225], v[68:71]
	v_mfma_f32_16x16x32_bf16 v[64:67], v[182:185], v[222:225], v[64:67]
	v_mfma_f32_16x16x32_bf16 v[116:119], v[178:181], v[194:197], v[116:119]
	v_mfma_f32_16x16x32_bf16 v[112:115], v[186:189], v[194:197], v[112:115]
	v_mfma_f32_16x16x32_bf16 v[100:103], v[178:181], v[206:209], v[100:103]
	v_mfma_f32_16x16x32_bf16 v[96:99], v[186:189], v[206:209], v[96:99]
	v_mfma_f32_16x16x32_bf16 v[84:87], v[178:181], v[214:217], v[84:87]
	v_mfma_f32_16x16x32_bf16 v[80:83], v[186:189], v[214:217], v[80:83]
	v_mfma_f32_16x16x32_bf16 v[68:71], v[178:181], v[226:229], v[68:71]
	v_mfma_f32_16x16x32_bf16 v[64:67], v[186:189], v[226:229], v[64:67]
	s_setprio 0
	s_barrier
	s_add_i32 s42, s69, s0
	s_mov_b32 m0, s42
	ds_read_b128 v[190:193], v175 offset:49152
	ds_read_b128 v[194:197], v175 offset:50176
	ds_read_b128 v[198:201], v175 offset:51200
	ds_read_b128 v[206:209], v175 offset:52224
	global_load_lds_dwordx4 v138, vcc
	s_add_i32 m0, s42, 0x2000
	s_add_u32 s6, s6, 0x80080
	s_addc_u32 s7, s7, 0
	s_add_i32 s42, s70, s0
	global_load_lds_dwordx4 v142, vcc
	s_mov_b32 m0, s42
	ds_read_b128 v[226:229], v175 offset:56320
	global_load_lds_dwordx4 v138, s[6:7]
	s_add_i32 m0, s42, 0x2000
	ds_read_b128 v[222:225], v175 offset:55296
	global_load_lds_dwordx4 v142, s[6:7]
	s_mov_b32 m0, s48
	ds_read_b128 v[214:217], v175 offset:54272
	global_load_lds_dwordx4 v136, s[98:99]
	s_mov_b32 m0, s49
	ds_read_b128 v[210:213], v175 offset:53248
	global_load_lds_dwordx4 v140, s[98:99]
	s_waitcnt vmcnt(8)
	s_waitcnt lgkmcnt(0)
	s_barrier
	s_setprio 1
	v_mfma_f32_16x16x32_bf16 v[60:63], v[128:131], v[190:193], v[60:63]
	v_mfma_f32_16x16x32_bf16 v[56:59], v[156:159], v[190:193], v[56:59]
	v_mfma_f32_16x16x32_bf16 v[44:47], v[128:131], v[198:201], v[44:47]
	v_mfma_f32_16x16x32_bf16 v[40:43], v[156:159], v[198:201], v[40:43]
	v_mfma_f32_16x16x32_bf16 v[28:31], v[128:131], v[210:213], v[28:31]
	v_mfma_f32_16x16x32_bf16 v[24:27], v[156:159], v[210:213], v[24:27]
	v_mfma_f32_16x16x32_bf16 v[12:15], v[128:131], v[222:225], v[12:15]
	v_mfma_f32_16x16x32_bf16 v[8:11], v[156:159], v[222:225], v[8:11]
	v_mfma_f32_16x16x32_bf16 v[60:63], v[132:135], v[194:197], v[60:63]
	v_mfma_f32_16x16x32_bf16 v[56:59], v[160:163], v[194:197], v[56:59]
	v_mfma_f32_16x16x32_bf16 v[44:47], v[132:135], v[206:209], v[44:47]
	v_mfma_f32_16x16x32_bf16 v[40:43], v[160:163], v[206:209], v[40:43]
	v_mfma_f32_16x16x32_bf16 v[28:31], v[132:135], v[214:217], v[28:31]
	v_mfma_f32_16x16x32_bf16 v[24:27], v[160:163], v[214:217], v[24:27]
	v_mfma_f32_16x16x32_bf16 v[12:15], v[132:135], v[226:229], v[12:15]
	v_mfma_f32_16x16x32_bf16 v[8:11], v[160:163], v[226:229], v[8:11]
	s_setprio 0
	s_setprio 1
	v_mfma_f32_16x16x32_bf16 v[52:55], v[164:167], v[190:193], v[52:55]
	v_mfma_f32_16x16x32_bf16 v[48:51], v[182:185], v[190:193], v[48:51]
	v_mfma_f32_16x16x32_bf16 v[36:39], v[164:167], v[198:201], v[36:39]
	v_mfma_f32_16x16x32_bf16 v[32:35], v[182:185], v[198:201], v[32:35]
	v_mfma_f32_16x16x32_bf16 v[20:23], v[164:167], v[210:213], v[20:23]
	v_mfma_f32_16x16x32_bf16 v[16:19], v[182:185], v[210:213], v[16:19]
	v_mfma_f32_16x16x32_bf16 v[4:7], v[164:167], v[222:225], v[4:7]
	v_mfma_f32_16x16x32_bf16 v[0:3], v[182:185], v[222:225], v[0:3]
	v_mfma_f32_16x16x32_bf16 v[52:55], v[178:181], v[194:197], v[52:55]
	v_mfma_f32_16x16x32_bf16 v[48:51], v[186:189], v[194:197], v[48:51]
	v_mfma_f32_16x16x32_bf16 v[36:39], v[178:181], v[206:209], v[36:39]
	v_mfma_f32_16x16x32_bf16 v[32:35], v[186:189], v[206:209], v[32:35]
	v_mfma_f32_16x16x32_bf16 v[20:23], v[178:181], v[214:217], v[20:23]
	v_mfma_f32_16x16x32_bf16 v[16:19], v[186:189], v[214:217], v[16:19]
	v_mfma_f32_16x16x32_bf16 v[4:7], v[178:181], v[226:229], v[4:7]
	v_mfma_f32_16x16x32_bf16 v[0:3], v[186:189], v[226:229], v[0:3]
	s_setprio 0
	s_barrier
	s_mov_b32 s100, 0
	s_add_i32 s47, s47, 2
	s_add_u32 s4, s4, 0x100
	s_addc_u32 s5, s5, 0
	s_add_u32 s45, s45, 0x100
	s_addc_u32 s46, s46, 0
	s_cmp_gt_u32 s47, 29
	s_cbranch_scc0 .LBB0_370
	s_and_b64 vcc, exec, s[18:19]
	s_cbranch_vccnz .LBB0_375
	s_add_u32 s98, s29, 0x80080
	s_addc_u32 s99, s10, 0
	v_lshl_add_u64 v[252:253], s[98:99], 0, v[146:147]
	s_add_i32 m0, s1, 0xc000
	s_nop 0
	global_load_lds_dwordx4 v[252:253], off
	v_lshl_add_u64 v[252:253], s[98:99], 0, v[148:149]
	s_add_i32 m0, s1, 0xe000
	s_nop 0
	global_load_lds_dwordx4 v[252:253], off
	s_mov_b32 s100, 1
	s_cmp_gt_i32 s36, 7
	s_mov_b64 s[4:5], -1
	s_cbranch_scc1 .LBB0_376

; #define PG8_STAGE(bufoff, gbase, voff) do { _Pragma("unroll") for (int _i = 0; _i < 2; ++_i) \
;         __builtin_amdgcn_global_load_lds((const unsigned*)((const char*)(gbase) + (voff)[_i]), (PG8_LAS unsigned*)(lds + (bufoff) + ldsw + _i * 8192), 16, 0, 0); } while (0)
; #define PG8_LDA(dst, b, h) do { _Pragma("unroll") for (int m = 0; m < 4; ++m) _Pragma("unroll") for (int k = 0; k < 2; ++k) dst[m][k] = *(const PG8_LAS bf16x8*)(lds + PG8_SA(b, h) + aoff + m * 2048 + k * 1024); } while (0)
; #define PG8_LDB(dst, b, h) do { _Pragma("unroll") for (int n = 0; n < 2; ++n) _Pragma("unroll") for (int k = 0; k < 2; ++k) dst[n][k] = *(const PG8_LAS bf16x8*)(lds + PG8_SB(b, h) + boff + n * 2048 + k * 1024); } while (0)
; #define PG8_MMA(ai, bj, At, Bt) do { __builtin_amdgcn_s_setprio(1); _Pragma("unroll") for (int m = 0; m < 4; ++m) _Pragma("unroll") for (int n = 0; n < 2; ++n) _Pragma("unroll") for (int k = 0; k < 2; ++k) \
;         acc[ai][bj][m][n] = __builtin_amdgcn_mfma_f32_16x16x32_bf16(Bt[n][k], At[m][k], acc[ai][bj][m][n], 0, 0, 0); __builtin_amdgcn_s_setprio(0); } while (0)
; #define PG8_WAIT_V(n) asm volatile("s_waitcnt vmcnt(" #n ")" ::: "memory")
; #define PG8_WAIT_L(n) asm volatile("s_waitcnt lgkmcnt(" #n ")" ::: "memory")
; #define PG8_BAR __builtin_amdgcn_s_barrier()
; #define PG8_SCHED __builtin_amdgcn_sched_barrier(0)
; template <class Epi, class Sched, bool ALIGN_EPI = false, bool SP2 = false>
; __device__ __forceinline__ void gemm_phase(PG8_LAS unsigned char* lds, const Gemm g, const Sched& S, const Epi& E) {
;     ...
;             PG8_WAIT_V(8); PG8_WAIT_L(0); PG8_BAR; PG8_MMA(0, 0, At, B0); PG8_MMA(0, 1, At, B1); PG8_BAR; PG8_SCHED;
;             PG8_LDA(At, 0, 1); PG8_STAGE(PG8_SB(0, 0), b2, voffB); PG8_STAGE(PG8_SB(0, 1), b2 + hstep, voffB); PG8_STAGE(PG8_SA(0, 0), a2, voffA);
;             PG8_WAIT_V(8); PG8_WAIT_L(0); PG8_BAR; PG8_MMA(1, 0, At, B0); PG8_MMA(1, 1, At, B1); PG8_BAR; PG8_SCHED;
;             PG8_LDB(B0, 1, 0); PG8_LDB(B1, 1, 1); PG8_SCHED; PG8_LDA(At, 1, 0); PG8_STAGE(PG8_SA(0, 1), a2 + hstep, voffA);
.Lgr_p5_0:
	s_waitcnt lgkmcnt(0)
	s_barrier
	s_setprio 1
	v_mfma_f32_16x16x32_bf16 v[124:127], v[128:131], v[160:163], v[124:127]
	v_mfma_f32_16x16x32_bf16 v[120:123], v[136:139], v[160:163], v[120:123]
	v_mfma_f32_16x16x32_bf16 v[108:111], v[128:131], v[168:171], v[108:111]
	v_mfma_f32_16x16x32_bf16 v[104:107], v[136:139], v[168:171], v[104:107]
	v_mfma_f32_16x16x32_bf16 v[92:95], v[128:131], v[176:179], v[92:95]
	v_mfma_f32_16x16x32_bf16 v[88:91], v[136:139], v[176:179], v[88:91]
	v_mfma_f32_16x16x32_bf16 v[76:79], v[128:131], v[184:187], v[76:79]
	v_mfma_f32_16x16x32_bf16 v[72:75], v[136:139], v[184:187], v[72:75]
	v_mfma_f32_16x16x32_bf16 v[124:127], v[132:135], v[164:167], v[124:127]
	v_mfma_f32_16x16x32_bf16 v[120:123], v[140:143], v[164:167], v[120:123]
	v_mfma_f32_16x16x32_bf16 v[108:111], v[132:135], v[172:175], v[108:111]
	v_mfma_f32_16x16x32_bf16 v[104:107], v[140:143], v[172:175], v[104:107]
	v_mfma_f32_16x16x32_bf16 v[92:95], v[132:135], v[180:183], v[92:95]
	v_mfma_f32_16x16x32_bf16 v[88:91], v[140:143], v[180:183], v[88:91]
	v_mfma_f32_16x16x32_bf16 v[76:79], v[132:135], v[188:191], v[76:79]
	v_mfma_f32_16x16x32_bf16 v[72:75], v[140:143], v[188:191], v[72:75]
	s_setprio 0
	s_setprio 1
	v_mfma_f32_16x16x32_bf16 v[116:119], v[144:147], v[160:163], v[116:119]
	v_mfma_f32_16x16x32_bf16 v[112:115], v[152:155], v[160:163], v[112:115]
	v_mfma_f32_16x16x32_bf16 v[100:103], v[144:147], v[168:171], v[100:103]
	v_mfma_f32_16x16x32_bf16 v[96:99], v[152:155], v[168:171], v[96:99]
	v_mfma_f32_16x16x32_bf16 v[84:87], v[144:147], v[176:179], v[84:87]
	v_mfma_f32_16x16x32_bf16 v[80:83], v[152:155], v[176:179], v[80:83]
	v_mfma_f32_16x16x32_bf16 v[68:71], v[144:147], v[184:187], v[68:71]
	v_mfma_f32_16x16x32_bf16 v[64:67], v[152:155], v[184:187], v[64:67]
	v_mfma_f32_16x16x32_bf16 v[116:119], v[148:151], v[164:167], v[116:119]
	v_mfma_f32_16x16x32_bf16 v[112:115], v[156:159], v[164:167], v[112:115]
	v_mfma_f32_16x16x32_bf16 v[100:103], v[148:151], v[172:175], v[100:103]
	v_mfma_f32_16x16x32_bf16 v[96:99], v[156:159], v[172:175], v[96:99]
	v_mfma_f32_16x16x32_bf16 v[84:87], v[148:151], v[180:183], v[84:87]
	v_mfma_f32_16x16x32_bf16 v[80:83], v[156:159], v[180:183], v[80:83]
	v_mfma_f32_16x16x32_bf16 v[68:71], v[148:151], v[188:191], v[68:71]
	v_mfma_f32_16x16x32_bf16 v[64:67], v[156:159], v[188:191], v[64:67]
	s_setprio 0
	s_barrier
	s_add_i32 s47, s41, s29
	s_add_u32 vcc_lo, s24, 0x80
	s_addc_u32 vcc_hi, s25, 0
	s_mov_b32 m0, s47
	ds_read_b128 v[160:163], v226 offset:16384
	ds_read_b128 v[164:167], v226 offset:17408
	ds_read_b128 v[168:171], v226 offset:18432
	ds_read_b128 v[172:175], v226 offset:19456
	global_load_lds_dwordx4 v194, s[24:25]
	s_add_i32 m0, s47, 0x2000
	s_add_u32 s48, s24, 0x40000
	s_addc_u32 s49, s25, 0
	s_add_i32 s47, s42, s29
	global_load_lds_dwordx4 v198, s[24:25]
	s_mov_b32 m0, s47
	ds_read_b128 v[188:191], v226 offset:23552
	global_load_lds_dwordx4 v194, s[48:49]
	s_add_i32 m0, s47, 0x2000
	ds_read_b128 v[184:187], v226 offset:22528
	global_load_lds_dwordx4 v198, s[48:49]
	s_add_u32 s98, s26, 0x80
	s_addc_u32 s99, s27, 0
	s_mov_b32 m0, s21
	ds_read_b128 v[180:183], v226 offset:21504
	global_load_lds_dwordx4 v192, s[26:27]
	s_mov_b32 m0, s30
	ds_read_b128 v[176:179], v226 offset:20480
	global_load_lds_dwordx4 v196, s[26:27]
	s_cmp_lg_u32 s100, 0
	s_cbranch_scc1 .Lgr_p5_1
	s_waitcnt vmcnt(8)
.Lgr_p5_1:
	s_waitcnt lgkmcnt(0)
	s_barrier
	s_setprio 1
	v_mfma_f32_16x16x32_bf16 v[60:63], v[128:131], v[160:163], v[60:63]
	v_mfma_f32_16x16x32_bf16 v[56:59], v[136:139], v[160:163], v[56:59]
	v_mfma_f32_16x16x32_bf16 v[44:47], v[128:131], v[168:171], v[44:47]
	v_mfma_f32_16x16x32_bf16 v[40:43], v[136:139], v[168:171], v[40:43]
	v_mfma_f32_16x16x32_bf16 v[28:31], v[128:131], v[176:179], v[28:31]
	v_mfma_f32_16x16x32_bf16 v[24:27], v[136:139], v[176:179], v[24:27]
	v_mfma_f32_16x16x32_bf16 v[12:15], v[128:131], v[184:187], v[12:15]
	v_mfma_f32_16x16x32_bf16 v[8:11], v[136:139], v[184:187], v[8:11]
	v_mfma_f32_16x16x32_bf16 v[60:63], v[132:135], v[164:167], v[60:63]
	v_mfma_f32_16x16x32_bf16 v[56:59], v[140:143], v[164:167], v[56:59]
	v_mfma_f32_16x16x32_bf16 v[44:47], v[132:135], v[172:175], v[44:47]
	v_mfma_f32_16x16x32_bf16 v[40:43], v[140:143], v[172:175], v[40:43]
	v_mfma_f32_16x16x32_bf16 v[28:31], v[132:135], v[180:183], v[28:31]
	v_mfma_f32_16x16x32_bf16 v[24:27], v[140:143], v[180:183], v[24:27]
	v_mfma_f32_16x16x32_bf16 v[12:15], v[132:135], v[188:191], v[12:15]
	v_mfma_f32_16x16x32_bf16 v[8:11], v[140:143], v[188:191], v[8:11]
	s_setprio 0
	s_setprio 1
	v_mfma_f32_16x16x32_bf16 v[52:55], v[144:147], v[160:163], v[52:55]
	v_mfma_f32_16x16x32_bf16 v[48:51], v[152:155], v[160:163], v[48:51]
	v_mfma_f32_16x16x32_bf16 v[36:39], v[144:147], v[168:171], v[36:39]
	v_mfma_f32_16x16x32_bf16 v[32:35], v[152:155], v[168:171], v[32:35]
	v_mfma_f32_16x16x32_bf16 v[20:23], v[144:147], v[176:179], v[20:23]
	v_mfma_f32_16x16x32_bf16 v[16:19], v[152:155], v[176:179], v[16:19]
	v_mfma_f32_16x16x32_bf16 v[4:7], v[144:147], v[184:187], v[4:7]
	v_mfma_f32_16x16x32_bf16 v[0:3], v[152:155], v[184:187], v[0:3]
	v_mfma_f32_16x16x32_bf16 v[52:55], v[148:151], v[164:167], v[52:55]
	v_mfma_f32_16x16x32_bf16 v[48:51], v[156:159], v[164:167], v[48:51]
	v_mfma_f32_16x16x32_bf16 v[36:39], v[148:151], v[172:175], v[36:39]
	v_mfma_f32_16x16x32_bf16 v[32:35], v[156:159], v[172:175], v[32:35]
	v_mfma_f32_16x16x32_bf16 v[20:23], v[148:151], v[180:183], v[20:23]
	v_mfma_f32_16x16x32_bf16 v[16:19], v[156:159], v[180:183], v[16:19]
	v_mfma_f32_16x16x32_bf16 v[4:7], v[148:151], v[188:191], v[4:7]
	v_mfma_f32_16x16x32_bf16 v[0:3], v[156:159], v[188:191], v[0:3]
	s_setprio 0
	s_barrier
	s_add_i32 s47, 0, 0x18000
	s_add_i32 s48, 0, 0x1c000
	v_add_u32_e32 v140, s47, v222
	v_add_u32_e32 v156, s48, v222
	ds_read_b128 v[128:131], v140
	ds_read_b128 v[132:135], v140 offset:1024
	ds_read_b128 v[136:139], v140 offset:2048
	ds_read_b128 v[140:143], v140 offset:3072
	ds_read_b128 v[144:147], v156
	ds_read_b128 v[148:151], v156 offset:1024
	ds_read_b128 v[152:155], v156 offset:2048
	ds_read_b128 v[156:159], v156 offset:3072
	s_add_u32 s26, s26, 0x40000
	s_addc_u32 s27, s27, 0
	s_mov_b32 m0, s31
	ds_read_b128 v[160:163], v226 offset:32768
	ds_read_b128 v[164:167], v226 offset:33792
	ds_read_b128 v[168:171], v226 offset:34816
	ds_read_b128 v[172:175], v226 offset:35840
	ds_read_b128 v[176:179], v226 offset:36864
	ds_read_b128 v[180:183], v226 offset:37888
	ds_read_b128 v[184:187], v226 offset:38912
	global_load_lds_dwordx4 v192, s[26:27]
	s_mov_b32 m0, s33
	ds_read_b128 v[188:191], v226 offset:39936
	global_load_lds_dwordx4 v196, s[26:27]
	s_cmp_lg_u32 s100, 0
	s_cbranch_scc1 .Lgr_p5_2
	s_waitcnt vmcnt(8)
; #define PG8_STAGE(bufoff, gbase, voff) do { _Pragma("unroll") for (int _i = 0; _i < 2; ++_i) \
;         __builtin_amdgcn_global_load_lds((const unsigned*)((const char*)(gbase) + (voff)[_i]), (PG8_LAS unsigned*)(lds + (bufoff) + ldsw + _i * 8192), 16, 0, 0); } while (0)
; #define PG8_LDA(dst, b, h) do { _Pragma("unroll") for (int m = 0; m < 4; ++m) _Pragma("unroll") for (int k = 0; k < 2; ++k) dst[m][k] = *(const PG8_LAS bf16x8*)(lds + PG8_SA(b, h) + aoff + m * 2048 + k * 1024); } while (0)
; #define PG8_MMA(ai, bj, At, Bt) do { __builtin_amdgcn_s_setprio(1); _Pragma("unroll") for (int m = 0; m < 4; ++m) _Pragma("unroll") for (int n = 0; n < 2; ++n) _Pragma("unroll") for (int k = 0; k < 2; ++k) \
;         acc[ai][bj][m][n] = __builtin_amdgcn_mfma_f32_16x16x32_bf16(Bt[n][k], At[m][k], acc[ai][bj][m][n], 0, 0, 0); __builtin_amdgcn_s_setprio(0); } while (0)
; #define PG8_WAIT_V(n) asm volatile("s_waitcnt vmcnt(" #n ")" ::: "memory")
; #define PG8_WAIT_L(n) asm volatile("s_waitcnt lgkmcnt(" #n ")" ::: "memory")
; #define PG8_BAR __builtin_amdgcn_s_barrier()
; #define PG8_SCHED __builtin_amdgcn_sched_barrier(0)
; template <class Epi, class Sched, bool ALIGN_EPI = false, bool SP2 = false>
; __device__ __forceinline__ void gemm_phase(PG8_LAS unsigned char* lds, const Gemm g, const Sched& S, const Epi& E) {
;     ...
;         for (int t = 0; t < nt; t += 2) {
;     ...
;             PG8_WAIT_V(8); PG8_WAIT_L(0); PG8_BAR; PG8_MMA(0, 0, At, B0); PG8_MMA(0, 1, At, B1); PG8_BAR; PG8_SCHED;
;             PG8_LDA(At, 1, 1); PG8_STAGE(PG8_SB(1, 0), b3, voffB); PG8_STAGE(PG8_SB(1, 1), b3 + hstep, voffB); PG8_STAGE(PG8_SA(1, 0), a3, voffA);
;             PG8_WAIT_V(8); PG8_WAIT_L(0); PG8_BAR; PG8_MMA(1, 0, At, B0); PG8_MMA(1, 1, At, B1); PG8_BAR; PG8_SCHED;
.Lgr_p5_2:
	s_waitcnt lgkmcnt(0)
	s_barrier
	s_setprio 1
	v_mfma_f32_16x16x32_bf16 v[124:127], v[128:131], v[160:163], v[124:127]
	v_mfma_f32_16x16x32_bf16 v[120:123], v[136:139], v[160:163], v[120:123]
	v_mfma_f32_16x16x32_bf16 v[108:111], v[128:131], v[168:171], v[108:111]
	v_mfma_f32_16x16x32_bf16 v[104:107], v[136:139], v[168:171], v[104:107]
	v_mfma_f32_16x16x32_bf16 v[92:95], v[128:131], v[176:179], v[92:95]
	v_mfma_f32_16x16x32_bf16 v[88:91], v[136:139], v[176:179], v[88:91]
	v_mfma_f32_16x16x32_bf16 v[76:79], v[128:131], v[184:187], v[76:79]
	v_mfma_f32_16x16x32_bf16 v[72:75], v[136:139], v[184:187], v[72:75]
	v_mfma_f32_16x16x32_bf16 v[124:127], v[132:135], v[164:167], v[124:127]
	v_mfma_f32_16x16x32_bf16 v[120:123], v[140:143], v[164:167], v[120:123]
	v_mfma_f32_16x16x32_bf16 v[108:111], v[132:135], v[172:175], v[108:111]
	v_mfma_f32_16x16x32_bf16 v[104:107], v[140:143], v[172:175], v[104:107]
	v_mfma_f32_16x16x32_bf16 v[92:95], v[132:135], v[180:183], v[92:95]
	v_mfma_f32_16x16x32_bf16 v[88:91], v[140:143], v[180:183], v[88:91]
	v_mfma_f32_16x16x32_bf16 v[76:79], v[132:135], v[188:191], v[76:79]
	v_mfma_f32_16x16x32_bf16 v[72:75], v[140:143], v[188:191], v[72:75]
	s_setprio 0
	s_setprio 1
	v_mfma_f32_16x16x32_bf16 v[116:119], v[144:147], v[160:163], v[116:119]
	v_mfma_f32_16x16x32_bf16 v[112:115], v[152:155], v[160:163], v[112:115]
	v_mfma_f32_16x16x32_bf16 v[100:103], v[144:147], v[168:171], v[100:103]
	v_mfma_f32_16x16x32_bf16 v[96:99], v[152:155], v[168:171], v[96:99]
	v_mfma_f32_16x16x32_bf16 v[84:87], v[144:147], v[176:179], v[84:87]
	v_mfma_f32_16x16x32_bf16 v[80:83], v[152:155], v[176:179], v[80:83]
	v_mfma_f32_16x16x32_bf16 v[68:71], v[144:147], v[184:187], v[68:71]
	v_mfma_f32_16x16x32_bf16 v[64:67], v[152:155], v[184:187], v[64:67]
	v_mfma_f32_16x16x32_bf16 v[116:119], v[148:151], v[164:167], v[116:119]
	v_mfma_f32_16x16x32_bf16 v[112:115], v[156:159], v[164:167], v[112:115]
	v_mfma_f32_16x16x32_bf16 v[100:103], v[148:151], v[172:175], v[100:103]
	v_mfma_f32_16x16x32_bf16 v[96:99], v[156:159], v[172:175], v[96:99]
	v_mfma_f32_16x16x32_bf16 v[84:87], v[148:151], v[180:183], v[84:87]
	v_mfma_f32_16x16x32_bf16 v[80:83], v[156:159], v[180:183], v[80:83]
	v_mfma_f32_16x16x32_bf16 v[68:71], v[148:151], v[188:191], v[68:71]
	v_mfma_f32_16x16x32_bf16 v[64:67], v[156:159], v[188:191], v[64:67]
	s_setprio 0
	s_barrier
	s_add_i32 s26, s47, s29
	s_mov_b32 m0, s26
	ds_read_b128 v[160:163], v226 offset:49152
	ds_read_b128 v[164:167], v226 offset:50176
	ds_read_b128 v[168:171], v226 offset:51200
	ds_read_b128 v[172:175], v226 offset:52224
	global_load_lds_dwordx4 v194, vcc
	s_add_i32 m0, s26, 0x2000
	s_add_u32 s24, s24, 0x40080
	s_addc_u32 s25, s25, 0
	s_add_i32 s26, s48, s29
	global_load_lds_dwordx4 v198, vcc
	s_mov_b32 m0, s26
	ds_read_b128 v[188:191], v226 offset:56320
	global_load_lds_dwordx4 v194, s[24:25]
	s_add_i32 m0, s26, 0x2000
	ds_read_b128 v[184:187], v226 offset:55296
	global_load_lds_dwordx4 v198, s[24:25]
	s_mov_b32 m0, s37
	ds_read_b128 v[180:183], v226 offset:54272
	global_load_lds_dwordx4 v192, s[98:99]
	s_mov_b32 m0, s38
	ds_read_b128 v[176:179], v226 offset:53248
	global_load_lds_dwordx4 v196, s[98:99]
	s_waitcnt vmcnt(8)
	s_waitcnt lgkmcnt(0)
	s_barrier
	s_setprio 1
	v_mfma_f32_16x16x32_bf16 v[60:63], v[128:131], v[160:163], v[60:63]
	v_mfma_f32_16x16x32_bf16 v[56:59], v[136:139], v[160:163], v[56:59]
	v_mfma_f32_16x16x32_bf16 v[44:47], v[128:131], v[168:171], v[44:47]
	v_mfma_f32_16x16x32_bf16 v[40:43], v[136:139], v[168:171], v[40:43]
	v_mfma_f32_16x16x32_bf16 v[28:31], v[128:131], v[176:179], v[28:31]
	v_mfma_f32_16x16x32_bf16 v[24:27], v[136:139], v[176:179], v[24:27]
	v_mfma_f32_16x16x32_bf16 v[12:15], v[128:131], v[184:187], v[12:15]
	v_mfma_f32_16x16x32_bf16 v[8:11], v[136:139], v[184:187], v[8:11]
	v_mfma_f32_16x16x32_bf16 v[60:63], v[132:135], v[164:167], v[60:63]
	v_mfma_f32_16x16x32_bf16 v[56:59], v[140:143], v[164:167], v[56:59]
	v_mfma_f32_16x16x32_bf16 v[44:47], v[132:135], v[172:175], v[44:47]
	v_mfma_f32_16x16x32_bf16 v[40:43], v[140:143], v[172:175], v[40:43]
	v_mfma_f32_16x16x32_bf16 v[28:31], v[132:135], v[180:183], v[28:31]
	v_mfma_f32_16x16x32_bf16 v[24:27], v[140:143], v[180:183], v[24:27]
	v_mfma_f32_16x16x32_bf16 v[12:15], v[132:135], v[188:191], v[12:15]
	v_mfma_f32_16x16x32_bf16 v[8:11], v[140:143], v[188:191], v[8:11]
	s_setprio 0
	s_setprio 1
	v_mfma_f32_16x16x32_bf16 v[52:55], v[144:147], v[160:163], v[52:55]
	v_mfma_f32_16x16x32_bf16 v[48:51], v[152:155], v[160:163], v[48:51]
	v_mfma_f32_16x16x32_bf16 v[36:39], v[144:147], v[168:171], v[36:39]
	v_mfma_f32_16x16x32_bf16 v[32:35], v[152:155], v[168:171], v[32:35]
	v_mfma_f32_16x16x32_bf16 v[20:23], v[144:147], v[176:179], v[20:23]
	v_mfma_f32_16x16x32_bf16 v[16:19], v[152:155], v[176:179], v[16:19]
	v_mfma_f32_16x16x32_bf16 v[4:7], v[144:147], v[184:187], v[4:7]
	v_mfma_f32_16x16x32_bf16 v[0:3], v[152:155], v[184:187], v[0:3]
	v_mfma_f32_16x16x32_bf16 v[52:55], v[148:151], v[164:167], v[52:55]
	v_mfma_f32_16x16x32_bf16 v[48:51], v[156:159], v[164:167], v[48:51]
	v_mfma_f32_16x16x32_bf16 v[36:39], v[148:151], v[172:175], v[36:39]
	v_mfma_f32_16x16x32_bf16 v[32:35], v[156:159], v[172:175], v[32:35]
	v_mfma_f32_16x16x32_bf16 v[20:23], v[148:151], v[180:183], v[20:23]
	v_mfma_f32_16x16x32_bf16 v[16:19], v[156:159], v[180:183], v[16:19]
	v_mfma_f32_16x16x32_bf16 v[4:7], v[148:151], v[188:191], v[4:7]
	v_mfma_f32_16x16x32_bf16 v[0:3], v[156:159], v[188:191], v[0:3]
	s_setprio 0
	s_barrier
	s_mov_b32 s100, 0
	s_add_i32 s46, s46, 2
	s_add_u32 s0, s0, 0x100
	s_addc_u32 s1, s1, 0
	s_add_u32 s44, s44, 0x100
	s_addc_u32 s45, s45, 0
	s_cmp_gt_u32 s46, 13
	s_cbranch_scc0 .LBB0_884
	s_and_b64 vcc, exec, s[8:9]
	s_cbranch_vccz .LBB0_887
	s_barrier

; #define PG8_STAGE(bufoff, gbase, voff) do { _Pragma("unroll") for (int _i = 0; _i < 2; ++_i) \
;         __builtin_amdgcn_global_load_lds((const unsigned*)((const char*)(gbase) + (voff)[_i]), (PG8_LAS unsigned*)(lds + (bufoff) + ldsw + _i * 8192), 16, 0, 0); } while (0)
; #define PG8_LDA(dst, b, h) do { _Pragma("unroll") for (int m = 0; m < 4; ++m) _Pragma("unroll") for (int k = 0; k < 2; ++k) dst[m][k] = *(const PG8_LAS bf16x8*)(lds + PG8_SA(b, h) + aoff + m * 2048 + k * 1024); } while (0)
; #define PG8_LDB(dst, b, h) do { _Pragma("unroll") for (int n = 0; n < 2; ++n) _Pragma("unroll") for (int k = 0; k < 2; ++k) dst[n][k] = *(const PG8_LAS bf16x8*)(lds + PG8_SB(b, h) + boff + n * 2048 + k * 1024); } while (0)
; #define PG8_MMA(ai, bj, At, Bt) do { __builtin_amdgcn_s_setprio(1); _Pragma("unroll") for (int m = 0; m < 4; ++m) _Pragma("unroll") for (int n = 0; n < 2; ++n) _Pragma("unroll") for (int k = 0; k < 2; ++k) \
;         acc[ai][bj][m][n] = __builtin_amdgcn_mfma_f32_16x16x32_bf16(Bt[n][k], At[m][k], acc[ai][bj][m][n], 0, 0, 0); __builtin_amdgcn_s_setprio(0); } while (0)
; #define PG8_WAIT_V(n) asm volatile("s_waitcnt vmcnt(" #n ")" ::: "memory")
; #define PG8_WAIT_L(n) asm volatile("s_waitcnt lgkmcnt(" #n ")" ::: "memory")
; template <class Epi, class Sched, bool ALIGN_EPI = false, bool SP2 = false>
; __device__ __forceinline__ void gemm_phase(PG8_LAS unsigned char* lds, const Gemm g, const Sched& S, const Epi& E) {
;     ...
;             const bool last = (t == nt - 2);
;             const char* a1 = cA + (size_t)(t + 1) * kstep;
;             const char* a2 = last ? nA : cA + (size_t)(t + 2) * kstep; const char* b2 = last ? nB : cB + (size_t)(t + 2) * kstep;
;             const char* a3 = a2 + kstep; const char* b3 = b2 + kstep;
;             if (last && has_next) S.a_ready(nxt);
;             if constexpr (SP2) {
;             PG8_LDB(B0, 0, 0); PG8_LDB(B1, 0, 1); PG8_SCHED; PG8_LDA(At, 0, 0); PG8_STAGE(PG8_SA(1, 1), a1 + hstep, voffA);
;             PG8_WAIT_V(8); PG8_WAIT_L(0); PG8_BAR; PG8_MMA(0, 0, At, B0); PG8_MMA(0, 1, At, B1); PG8_BAR; PG8_SCHED;
;             PG8_LDA(At, 0, 1); PG8_STAGE(PG8_SB(0, 0), b2, voffB); PG8_STAGE(PG8_SB(0, 1), b2 + hstep, voffB); PG8_STAGE(PG8_SA(0, 0), a2, voffA);
;             PG8_WAIT_V(8); PG8_WAIT_L(0); PG8_BAR; PG8_MMA(1, 0, At, B0); PG8_MMA(1, 1, At, B1); PG8_BAR; PG8_SCHED;
.LBB0_993:
	ds_read_b128 v[128:131], v213
	ds_read_b128 v[132:135], v213 offset:1024
	ds_read_b128 v[136:139], v213 offset:2048
	ds_read_b128 v[140:143], v213 offset:3072
	ds_read_b128 v[144:147], v214
	ds_read_b128 v[148:151], v214 offset:1024
	ds_read_b128 v[152:155], v214 offset:2048
	ds_read_b128 v[156:159], v214 offset:3072
	s_add_u32 s28, s26, 0xfff80080
	s_addc_u32 s29, s27, -1
	s_cmp_eq_u32 s48, 28
	s_cselect_b32 s31, s17, s29
	s_cselect_b32 s30, s23, s28
	s_cselect_b32 s29, s15, s47
	s_cselect_b32 s28, s45, s46
	s_add_i32 m0, s25, 0xc000
	ds_read_b128 v[160:163], v215
	ds_read_b128 v[164:167], v215 offset:1024
	ds_read_b128 v[168:171], v215 offset:2048
	ds_read_b128 v[172:175], v215 offset:3072
	ds_read_b128 v[192:195], v215 offset:4096
	ds_read_b128 v[196:199], v215 offset:5120
	ds_read_b128 v[200:203], v215 offset:6144
	global_load_lds_dwordx4 v184, s[26:27]
	s_add_i32 m0, s25, 0xe000
	ds_read_b128 v[204:207], v215 offset:7168
	global_load_lds_dwordx4 v186, s[26:27]
	s_waitcnt vmcnt(8)
	s_waitcnt lgkmcnt(0)
	s_barrier
	s_setprio 1
	v_mfma_f32_16x16x32_bf16 v[124:127], v[128:131], v[160:163], v[124:127]
	v_mfma_f32_16x16x32_bf16 v[120:123], v[136:139], v[160:163], v[120:123]
	v_mfma_f32_16x16x32_bf16 v[108:111], v[128:131], v[168:171], v[108:111]
	v_mfma_f32_16x16x32_bf16 v[104:107], v[136:139], v[168:171], v[104:107]
	v_mfma_f32_16x16x32_bf16 v[92:95], v[128:131], v[192:195], v[92:95]
	v_mfma_f32_16x16x32_bf16 v[88:91], v[136:139], v[192:195], v[88:91]
	v_mfma_f32_16x16x32_bf16 v[76:79], v[128:131], v[200:203], v[76:79]
	v_mfma_f32_16x16x32_bf16 v[72:75], v[136:139], v[200:203], v[72:75]
	v_mfma_f32_16x16x32_bf16 v[124:127], v[132:135], v[164:167], v[124:127]
	v_mfma_f32_16x16x32_bf16 v[120:123], v[140:143], v[164:167], v[120:123]
	v_mfma_f32_16x16x32_bf16 v[108:111], v[132:135], v[172:175], v[108:111]
	v_mfma_f32_16x16x32_bf16 v[104:107], v[140:143], v[172:175], v[104:107]
	v_mfma_f32_16x16x32_bf16 v[92:95], v[132:135], v[196:199], v[92:95]
	v_mfma_f32_16x16x32_bf16 v[88:91], v[140:143], v[196:199], v[88:91]
	v_mfma_f32_16x16x32_bf16 v[76:79], v[132:135], v[204:207], v[76:79]
	v_mfma_f32_16x16x32_bf16 v[72:75], v[140:143], v[204:207], v[72:75]
	s_setprio 0
	s_setprio 1
	v_mfma_f32_16x16x32_bf16 v[116:119], v[144:147], v[160:163], v[116:119]
	v_mfma_f32_16x16x32_bf16 v[112:115], v[152:155], v[160:163], v[112:115]
	v_mfma_f32_16x16x32_bf16 v[100:103], v[144:147], v[168:171], v[100:103]
	v_mfma_f32_16x16x32_bf16 v[96:99], v[152:155], v[168:171], v[96:99]
	v_mfma_f32_16x16x32_bf16 v[84:87], v[144:147], v[192:195], v[84:87]
	v_mfma_f32_16x16x32_bf16 v[80:83], v[152:155], v[192:195], v[80:83]
	v_mfma_f32_16x16x32_bf16 v[68:71], v[144:147], v[200:203], v[68:71]
	v_mfma_f32_16x16x32_bf16 v[64:67], v[152:155], v[200:203], v[64:67]
	v_mfma_f32_16x16x32_bf16 v[116:119], v[148:151], v[164:167], v[116:119]
	v_mfma_f32_16x16x32_bf16 v[112:115], v[156:159], v[164:167], v[112:115]
	v_mfma_f32_16x16x32_bf16 v[100:103], v[148:151], v[172:175], v[100:103]
	v_mfma_f32_16x16x32_bf16 v[96:99], v[156:159], v[172:175], v[96:99]
	v_mfma_f32_16x16x32_bf16 v[84:87], v[148:151], v[196:199], v[84:87]
	v_mfma_f32_16x16x32_bf16 v[80:83], v[156:159], v[196:199], v[80:83]
	v_mfma_f32_16x16x32_bf16 v[68:71], v[148:151], v[204:207], v[68:71]
	v_mfma_f32_16x16x32_bf16 v[64:67], v[156:159], v[204:207], v[64:67]
	s_setprio 0
	s_barrier
	s_add_i32 s49, s43, s33
	s_add_u32 vcc_lo, s28, 0x80
	s_addc_u32 vcc_hi, s29, 0
	s_mov_b32 m0, s49
	ds_read_b128 v[160:163], v215 offset:16384
	ds_read_b128 v[164:167], v215 offset:17408
	ds_read_b128 v[168:171], v215 offset:18432
	ds_read_b128 v[172:175], v215 offset:19456
	global_load_lds_dwordx4 v178, s[28:29]
	s_add_i32 m0, s49, 0x2000
	s_add_u32 s50, s28, 0x80000
	s_addc_u32 s51, s29, 0
	s_add_i32 s49, s44, s33
	global_load_lds_dwordx4 v182, s[28:29]
	s_mov_b32 m0, s49
	ds_read_b128 v[204:207], v215 offset:23552
	global_load_lds_dwordx4 v178, s[50:51]
	s_add_i32 m0, s49, 0x2000
	ds_read_b128 v[200:203], v215 offset:22528
	global_load_lds_dwordx4 v182, s[50:51]
	s_add_u32 s98, s30, 0x80
	s_addc_u32 s99, s31, 0
	s_mov_b32 m0, s25
	ds_read_b128 v[196:199], v215 offset:21504
	global_load_lds_dwordx4 v176, s[30:31]
	s_mov_b32 m0, s34
	ds_read_b128 v[192:195], v215 offset:20480
	global_load_lds_dwordx4 v180, s[30:31]
	s_waitcnt vmcnt(8)
	s_waitcnt lgkmcnt(0)
	s_barrier
	s_setprio 1
	v_mfma_f32_16x16x32_bf16 v[60:63], v[128:131], v[160:163], v[60:63]
	v_mfma_f32_16x16x32_bf16 v[56:59], v[136:139], v[160:163], v[56:59]
	v_mfma_f32_16x16x32_bf16 v[44:47], v[128:131], v[168:171], v[44:47]
	v_mfma_f32_16x16x32_bf16 v[40:43], v[136:139], v[168:171], v[40:43]
	v_mfma_f32_16x16x32_bf16 v[28:31], v[128:131], v[192:195], v[28:31]
	v_mfma_f32_16x16x32_bf16 v[24:27], v[136:139], v[192:195], v[24:27]
	v_mfma_f32_16x16x32_bf16 v[12:15], v[128:131], v[200:203], v[12:15]
	v_mfma_f32_16x16x32_bf16 v[8:11], v[136:139], v[200:203], v[8:11]
	v_mfma_f32_16x16x32_bf16 v[60:63], v[132:135], v[164:167], v[60:63]
	v_mfma_f32_16x16x32_bf16 v[56:59], v[140:143], v[164:167], v[56:59]
	v_mfma_f32_16x16x32_bf16 v[44:47], v[132:135], v[172:175], v[44:47]
	v_mfma_f32_16x16x32_bf16 v[40:43], v[140:143], v[172:175], v[40:43]
	v_mfma_f32_16x16x32_bf16 v[28:31], v[132:135], v[196:199], v[28:31]
	v_mfma_f32_16x16x32_bf16 v[24:27], v[140:143], v[196:199], v[24:27]
	v_mfma_f32_16x16x32_bf16 v[12:15], v[132:135], v[204:207], v[12:15]
	v_mfma_f32_16x16x32_bf16 v[8:11], v[140:143], v[204:207], v[8:11]
	s_setprio 0
	s_setprio 1
	v_mfma_f32_16x16x32_bf16 v[52:55], v[144:147], v[160:163], v[52:55]
	v_mfma_f32_16x16x32_bf16 v[48:51], v[152:155], v[160:163], v[48:51]
	v_mfma_f32_16x16x32_bf16 v[36:39], v[144:147], v[168:171], v[36:39]
	v_mfma_f32_16x16x32_bf16 v[32:35], v[152:155], v[168:171], v[32:35]
	v_mfma_f32_16x16x32_bf16 v[20:23], v[144:147], v[192:195], v[20:23]
	v_mfma_f32_16x16x32_bf16 v[16:19], v[152:155], v[192:195], v[16:19]
	v_mfma_f32_16x16x32_bf16 v[4:7], v[144:147], v[200:203], v[4:7]
	v_mfma_f32_16x16x32_bf16 v[0:3], v[152:155], v[200:203], v[0:3]
	v_mfma_f32_16x16x32_bf16 v[52:55], v[148:151], v[164:167], v[52:55]
	v_mfma_f32_16x16x32_bf16 v[48:51], v[156:159], v[164:167], v[48:51]
	v_mfma_f32_16x16x32_bf16 v[36:39], v[148:151], v[172:175], v[36:39]
	v_mfma_f32_16x16x32_bf16 v[32:35], v[156:159], v[172:175], v[32:35]
	v_mfma_f32_16x16x32_bf16 v[20:23], v[148:151], v[196:199], v[20:23]
	v_mfma_f32_16x16x32_bf16 v[16:19], v[156:159], v[196:199], v[16:19]
	v_mfma_f32_16x16x32_bf16 v[4:7], v[148:151], v[204:207], v[4:7]
	v_mfma_f32_16x16x32_bf16 v[0:3], v[156:159], v[204:207], v[0:3]
	s_setprio 0
	s_barrier
; #define PG8_STAGE(bufoff, gbase, voff) do { _Pragma("unroll") for (int _i = 0; _i < 2; ++_i) \
;         __builtin_amdgcn_global_load_lds((const unsigned*)((const char*)(gbase) + (voff)[_i]), (PG8_LAS unsigned*)(lds + (bufoff) + ldsw + _i * 8192), 16, 0, 0); } while (0)
; #define PG8_LDA(dst, b, h) do { _Pragma("unroll") for (int m = 0; m < 4; ++m) _Pragma("unroll") for (int k = 0; k < 2; ++k) dst[m][k] = *(const PG8_LAS bf16x8*)(lds + PG8_SA(b, h) + aoff + m * 2048 + k * 1024); } while (0)
; #define PG8_LDB(dst, b, h) do { _Pragma("unroll") for (int n = 0; n < 2; ++n) _Pragma("unroll") for (int k = 0; k < 2; ++k) dst[n][k] = *(const PG8_LAS bf16x8*)(lds + PG8_SB(b, h) + boff + n * 2048 + k * 1024); } while (0)
; #define PG8_MMA(ai, bj, At, Bt) do { __builtin_amdgcn_s_setprio(1); _Pragma("unroll") for (int m = 0; m < 4; ++m) _Pragma("unroll") for (int n = 0; n < 2; ++n) _Pragma("unroll") for (int k = 0; k < 2; ++k) \
;         acc[ai][bj][m][n] = __builtin_amdgcn_mfma_f32_16x16x32_bf16(Bt[n][k], At[m][k], acc[ai][bj][m][n], 0, 0, 0); __builtin_amdgcn_s_setprio(0); } while (0)
; #define PG8_WAIT_V(n) asm volatile("s_waitcnt vmcnt(" #n ")" ::: "memory")
; #define PG8_WAIT_L(n) asm volatile("s_waitcnt lgkmcnt(" #n ")" ::: "memory")
; #define PG8_BAR __builtin_amdgcn_s_barrier()
; #define PG8_SCHED __builtin_amdgcn_sched_barrier(0)
; template <class Epi, class Sched, bool ALIGN_EPI = false, bool SP2 = false>
; __device__ __forceinline__ void gemm_phase(PG8_LAS unsigned char* lds, const Gemm g, const Sched& S, const Epi& E) {
;     ...
;         for (int t = 0; t < nt; t += 2) {
;     ...
;             PG8_LDB(B0, 1, 0); PG8_LDB(B1, 1, 1); PG8_SCHED; PG8_LDA(At, 1, 0); PG8_STAGE(PG8_SA(0, 1), a2 + hstep, voffA);
;             PG8_WAIT_V(8); PG8_WAIT_L(0); PG8_BAR; PG8_MMA(0, 0, At, B0); PG8_MMA(0, 1, At, B1); PG8_BAR; PG8_SCHED;
;             PG8_LDA(At, 1, 1); PG8_STAGE(PG8_SB(1, 0), b3, voffB); PG8_STAGE(PG8_SB(1, 1), b3 + hstep, voffB); PG8_STAGE(PG8_SA(1, 0), a3, voffA);
;             PG8_WAIT_V(8); PG8_WAIT_L(0); PG8_BAR; PG8_MMA(1, 0, At, B0); PG8_MMA(1, 1, At, B1); PG8_BAR; PG8_SCHED;
	s_add_i32 s49, 0, 0x18000
	s_add_i32 s50, 0, 0x1c000
	v_add_u32_e32 v140, s49, v211
	v_add_u32_e32 v156, s50, v211
	ds_read_b128 v[128:131], v140
	ds_read_b128 v[132:135], v140 offset:1024
	ds_read_b128 v[136:139], v140 offset:2048
	ds_read_b128 v[140:143], v140 offset:3072
	ds_read_b128 v[144:147], v156
	ds_read_b128 v[148:151], v156 offset:1024
	ds_read_b128 v[152:155], v156 offset:2048
	ds_read_b128 v[156:159], v156 offset:3072
	s_add_u32 s30, s30, 0x80000
	s_addc_u32 s31, s31, 0
	s_mov_b32 m0, s35
	ds_read_b128 v[160:163], v215 offset:32768
	ds_read_b128 v[164:167], v215 offset:33792
	ds_read_b128 v[168:171], v215 offset:34816
	ds_read_b128 v[172:175], v215 offset:35840
	ds_read_b128 v[192:195], v215 offset:36864
	ds_read_b128 v[196:199], v215 offset:37888
	ds_read_b128 v[200:203], v215 offset:38912
	global_load_lds_dwordx4 v176, s[30:31]
	s_mov_b32 m0, s36
	ds_read_b128 v[204:207], v215 offset:39936
	global_load_lds_dwordx4 v180, s[30:31]
	s_waitcnt vmcnt(8)
	s_waitcnt lgkmcnt(0)
	s_barrier
	s_setprio 1
	v_mfma_f32_16x16x32_bf16 v[124:127], v[128:131], v[160:163], v[124:127]
	v_mfma_f32_16x16x32_bf16 v[120:123], v[136:139], v[160:163], v[120:123]
	v_mfma_f32_16x16x32_bf16 v[108:111], v[128:131], v[168:171], v[108:111]
	v_mfma_f32_16x16x32_bf16 v[104:107], v[136:139], v[168:171], v[104:107]
	v_mfma_f32_16x16x32_bf16 v[92:95], v[128:131], v[192:195], v[92:95]
	v_mfma_f32_16x16x32_bf16 v[88:91], v[136:139], v[192:195], v[88:91]
	v_mfma_f32_16x16x32_bf16 v[76:79], v[128:131], v[200:203], v[76:79]
	v_mfma_f32_16x16x32_bf16 v[72:75], v[136:139], v[200:203], v[72:75]
	v_mfma_f32_16x16x32_bf16 v[124:127], v[132:135], v[164:167], v[124:127]
	v_mfma_f32_16x16x32_bf16 v[120:123], v[140:143], v[164:167], v[120:123]
	v_mfma_f32_16x16x32_bf16 v[108:111], v[132:135], v[172:175], v[108:111]
	v_mfma_f32_16x16x32_bf16 v[104:107], v[140:143], v[172:175], v[104:107]
	v_mfma_f32_16x16x32_bf16 v[92:95], v[132:135], v[196:199], v[92:95]
	v_mfma_f32_16x16x32_bf16 v[88:91], v[140:143], v[196:199], v[88:91]
	v_mfma_f32_16x16x32_bf16 v[76:79], v[132:135], v[204:207], v[76:79]
	v_mfma_f32_16x16x32_bf16 v[72:75], v[140:143], v[204:207], v[72:75]
	s_setprio 0
	s_setprio 1
	v_mfma_f32_16x16x32_bf16 v[116:119], v[144:147], v[160:163], v[116:119]
	v_mfma_f32_16x16x32_bf16 v[112:115], v[152:155], v[160:163], v[112:115]
	v_mfma_f32_16x16x32_bf16 v[100:103], v[144:147], v[168:171], v[100:103]
	v_mfma_f32_16x16x32_bf16 v[96:99], v[152:155], v[168:171], v[96:99]
	v_mfma_f32_16x16x32_bf16 v[84:87], v[144:147], v[192:195], v[84:87]
	v_mfma_f32_16x16x32_bf16 v[80:83], v[152:155], v[192:195], v[80:83]
	v_mfma_f32_16x16x32_bf16 v[68:71], v[144:147], v[200:203], v[68:71]
	v_mfma_f32_16x16x32_bf16 v[64:67], v[152:155], v[200:203], v[64:67]
	v_mfma_f32_16x16x32_bf16 v[116:119], v[148:151], v[164:167], v[116:119]
	v_mfma_f32_16x16x32_bf16 v[112:115], v[156:159], v[164:167], v[112:115]
	v_mfma_f32_16x16x32_bf16 v[100:103], v[148:151], v[172:175], v[100:103]
	v_mfma_f32_16x16x32_bf16 v[96:99], v[156:159], v[172:175], v[96:99]
	v_mfma_f32_16x16x32_bf16 v[84:87], v[148:151], v[196:199], v[84:87]
	v_mfma_f32_16x16x32_bf16 v[80:83], v[156:159], v[196:199], v[80:83]
	v_mfma_f32_16x16x32_bf16 v[68:71], v[148:151], v[204:207], v[68:71]
	v_mfma_f32_16x16x32_bf16 v[64:67], v[156:159], v[204:207], v[64:67]
	s_setprio 0
	s_barrier
	s_add_i32 s30, s49, s33
	s_mov_b32 m0, s30
	ds_read_b128 v[160:163], v215 offset:49152
	ds_read_b128 v[164:167], v215 offset:50176
	ds_read_b128 v[168:171], v215 offset:51200
	ds_read_b128 v[172:175], v215 offset:52224
	global_load_lds_dwordx4 v178, vcc
	s_add_i32 m0, s30, 0x2000
	s_add_u32 s28, s28, 0x80080
	s_addc_u32 s29, s29, 0
	s_add_i32 s30, s50, s33
	global_load_lds_dwordx4 v182, vcc
	s_mov_b32 m0, s30
	ds_read_b128 v[204:207], v215 offset:56320
	global_load_lds_dwordx4 v178, s[28:29]
	s_add_i32 m0, s30, 0x2000
	ds_read_b128 v[200:203], v215 offset:55296
	global_load_lds_dwordx4 v182, s[28:29]
	s_mov_b32 m0, s38
	ds_read_b128 v[196:199], v215 offset:54272
	global_load_lds_dwordx4 v176, s[98:99]
	s_mov_b32 m0, s39
	ds_read_b128 v[192:195], v215 offset:53248
	global_load_lds_dwordx4 v180, s[98:99]
	s_waitcnt vmcnt(8)
	s_waitcnt lgkmcnt(0)
	s_barrier
	s_setprio 1
	v_mfma_f32_16x16x32_bf16 v[60:63], v[128:131], v[160:163], v[60:63]
	v_mfma_f32_16x16x32_bf16 v[56:59], v[136:139], v[160:163], v[56:59]
	v_mfma_f32_16x16x32_bf16 v[44:47], v[128:131], v[168:171], v[44:47]
	v_mfma_f32_16x16x32_bf16 v[40:43], v[136:139], v[168:171], v[40:43]
	v_mfma_f32_16x16x32_bf16 v[28:31], v[128:131], v[192:195], v[28:31]
	v_mfma_f32_16x16x32_bf16 v[24:27], v[136:139], v[192:195], v[24:27]
	v_mfma_f32_16x16x32_bf16 v[12:15], v[128:131], v[200:203], v[12:15]
	v_mfma_f32_16x16x32_bf16 v[8:11], v[136:139], v[200:203], v[8:11]
	v_mfma_f32_16x16x32_bf16 v[60:63], v[132:135], v[164:167], v[60:63]
	v_mfma_f32_16x16x32_bf16 v[56:59], v[140:143], v[164:167], v[56:59]
	v_mfma_f32_16x16x32_bf16 v[44:47], v[132:135], v[172:175], v[44:47]
	v_mfma_f32_16x16x32_bf16 v[40:43], v[140:143], v[172:175], v[40:43]
	v_mfma_f32_16x16x32_bf16 v[28:31], v[132:135], v[196:199], v[28:31]
	v_mfma_f32_16x16x32_bf16 v[24:27], v[140:143], v[196:199], v[24:27]
	v_mfma_f32_16x16x32_bf16 v[12:15], v[132:135], v[204:207], v[12:15]
	v_mfma_f32_16x16x32_bf16 v[8:11], v[140:143], v[204:207], v[8:11]
	s_setprio 0
	s_setprio 1
	v_mfma_f32_16x16x32_bf16 v[52:55], v[144:147], v[160:163], v[52:55]
	v_mfma_f32_16x16x32_bf16 v[48:51], v[152:155], v[160:163], v[48:51]
	v_mfma_f32_16x16x32_bf16 v[36:39], v[144:147], v[168:171], v[36:39]
	v_mfma_f32_16x16x32_bf16 v[32:35], v[152:155], v[168:171], v[32:35]
	v_mfma_f32_16x16x32_bf16 v[20:23], v[144:147], v[192:195], v[20:23]
	v_mfma_f32_16x16x32_bf16 v[16:19], v[152:155], v[192:195], v[16:19]
	v_mfma_f32_16x16x32_bf16 v[4:7], v[144:147], v[200:203], v[4:7]
	v_mfma_f32_16x16x32_bf16 v[0:3], v[152:155], v[200:203], v[0:3]
	v_mfma_f32_16x16x32_bf16 v[52:55], v[148:151], v[164:167], v[52:55]
	v_mfma_f32_16x16x32_bf16 v[48:51], v[156:159], v[164:167], v[48:51]
	v_mfma_f32_16x16x32_bf16 v[36:39], v[148:151], v[172:175], v[36:39]
	v_mfma_f32_16x16x32_bf16 v[32:35], v[156:159], v[172:175], v[32:35]
	v_mfma_f32_16x16x32_bf16 v[20:23], v[148:151], v[196:199], v[20:23]
	v_mfma_f32_16x16x32_bf16 v[16:19], v[156:159], v[196:199], v[16:19]
	v_mfma_f32_16x16x32_bf16 v[4:7], v[148:151], v[204:207], v[4:7]
	v_mfma_f32_16x16x32_bf16 v[0:3], v[156:159], v[204:207], v[0:3]
	s_setprio 0
	s_barrier
	s_add_i32 s48, s48, 2
	s_add_u32 s26, s26, 0x100
	s_addc_u32 s27, s27, 0
	s_add_u32 s46, s46, 0x100
	s_addc_u32 s47, s47, 0
	s_cmp_gt_u32 s48, 29
	s_cbranch_scc0 .LBB0_993
	s_and_b64 vcc, exec, s[12:13]
	s_cbranch_vccz .LBB0_996
	s_barrier

; #define PG8_STAGE(bufoff, gbase, voff) do { _Pragma("unroll") for (int _i = 0; _i < 2; ++_i) \
;         __builtin_amdgcn_global_load_lds((const unsigned*)((const char*)(gbase) + (voff)[_i]), (PG8_LAS unsigned*)(lds + (bufoff) + ldsw + _i * 8192), 16, 0, 0); } while (0)
; #define PG8_LDA(dst, b, h) do { _Pragma("unroll") for (int m = 0; m < 4; ++m) _Pragma("unroll") for (int k = 0; k < 2; ++k) dst[m][k] = *(const PG8_LAS bf16x8*)(lds + PG8_SA(b, h) + aoff + m * 2048 + k * 1024); } while (0)
; #define PG8_LDB(dst, b, h) do { _Pragma("unroll") for (int n = 0; n < 2; ++n) _Pragma("unroll") for (int k = 0; k < 2; ++k) dst[n][k] = *(const PG8_LAS bf16x8*)(lds + PG8_SB(b, h) + boff + n * 2048 + k * 1024); } while (0)
; #define PG8_MMA(ai, bj, At, Bt) do { __builtin_amdgcn_s_setprio(1); _Pragma("unroll") for (int m = 0; m < 4; ++m) _Pragma("unroll") for (int n = 0; n < 2; ++n) _Pragma("unroll") for (int k = 0; k < 2; ++k) \
;         acc[ai][bj][m][n] = __builtin_amdgcn_mfma_f32_16x16x32_bf16(Bt[n][k], At[m][k], acc[ai][bj][m][n], 0, 0, 0); __builtin_amdgcn_s_setprio(0); } while (0)
; #define PG8_WAIT_V(n) asm volatile("s_waitcnt vmcnt(" #n ")" ::: "memory")
; #define PG8_WAIT_L(n) asm volatile("s_waitcnt lgkmcnt(" #n ")" ::: "memory")
; #define PG8_BAR __builtin_amdgcn_s_barrier()
; #define PG8_SCHED __builtin_amdgcn_sched_barrier(0)
; template <class Epi, class Sched, bool ALIGN_EPI = false, bool SP2 = false>
; __device__ __forceinline__ void gemm_phase(PG8_LAS unsigned char* lds, const Gemm g, const Sched& S, const Epi& E) {
;     ...
;             PG8_WAIT_V(8); PG8_WAIT_L(0); PG8_BAR; PG8_MMA(0, 0, At, B0); PG8_MMA(0, 1, At, B1); PG8_BAR; PG8_SCHED;
;             PG8_LDA(At, 0, 1); PG8_STAGE(PG8_SB(0, 0), b2, voffB); PG8_STAGE(PG8_SB(0, 1), b2 + hstep, voffB); PG8_STAGE(PG8_SA(0, 0), a2, voffA);
;             PG8_WAIT_V(8); PG8_WAIT_L(0); PG8_BAR; PG8_MMA(1, 0, At, B0); PG8_MMA(1, 1, At, B1); PG8_BAR; PG8_SCHED;
;             PG8_LDB(B0, 1, 0); PG8_LDB(B1, 1, 1); PG8_SCHED; PG8_LDA(At, 1, 0); PG8_STAGE(PG8_SA(0, 1), a2 + hstep, voffA);
.Lgr_p7_0:
	s_waitcnt lgkmcnt(0)
	s_barrier
	s_setprio 1
	v_mfma_f32_16x16x32_bf16 v[116:119], v[166:169], v[198:201], v[116:119]
	v_mfma_f32_16x16x32_bf16 v[112:115], v[174:177], v[198:201], v[112:115]
	v_mfma_f32_16x16x32_bf16 v[108:111], v[166:169], v[206:209], v[108:111]
	v_mfma_f32_16x16x32_bf16 v[100:103], v[174:177], v[206:209], v[100:103]
	v_mfma_f32_16x16x32_bf16 v[92:95], v[166:169], v[214:217], v[92:95]
	v_mfma_f32_16x16x32_bf16 v[84:87], v[174:177], v[214:217], v[84:87]
	v_mfma_f32_16x16x32_bf16 v[76:79], v[166:169], v[226:229], v[76:79]
	v_mfma_f32_16x16x32_bf16 v[68:71], v[174:177], v[226:229], v[68:71]
	v_mfma_f32_16x16x32_bf16 v[116:119], v[170:173], v[202:205], v[116:119]
	v_mfma_f32_16x16x32_bf16 v[112:115], v[178:181], v[202:205], v[112:115]
	v_mfma_f32_16x16x32_bf16 v[108:111], v[170:173], v[210:213], v[108:111]
	v_mfma_f32_16x16x32_bf16 v[100:103], v[178:181], v[210:213], v[100:103]
	v_mfma_f32_16x16x32_bf16 v[92:95], v[170:173], v[222:225], v[92:95]
	v_mfma_f32_16x16x32_bf16 v[84:87], v[178:181], v[222:225], v[84:87]
	v_mfma_f32_16x16x32_bf16 v[76:79], v[170:173], v[230:233], v[76:79]
	v_mfma_f32_16x16x32_bf16 v[68:71], v[178:181], v[230:233], v[68:71]
	s_setprio 0
	s_setprio 1
	v_mfma_f32_16x16x32_bf16 v[124:127], v[182:185], v[198:201], v[124:127]
	v_mfma_f32_16x16x32_bf16 v[120:123], v[190:193], v[198:201], v[120:123]
	v_mfma_f32_16x16x32_bf16 v[104:107], v[182:185], v[206:209], v[104:107]
	v_mfma_f32_16x16x32_bf16 v[96:99], v[190:193], v[206:209], v[96:99]
	v_mfma_f32_16x16x32_bf16 v[88:91], v[182:185], v[214:217], v[88:91]
	v_mfma_f32_16x16x32_bf16 v[80:83], v[190:193], v[214:217], v[80:83]
	v_mfma_f32_16x16x32_bf16 v[72:75], v[182:185], v[226:229], v[72:75]
	v_mfma_f32_16x16x32_bf16 v[64:67], v[190:193], v[226:229], v[64:67]
	v_mfma_f32_16x16x32_bf16 v[124:127], v[186:189], v[202:205], v[124:127]
	v_mfma_f32_16x16x32_bf16 v[120:123], v[194:197], v[202:205], v[120:123]
	v_mfma_f32_16x16x32_bf16 v[104:107], v[186:189], v[210:213], v[104:107]
	v_mfma_f32_16x16x32_bf16 v[96:99], v[194:197], v[210:213], v[96:99]
	v_mfma_f32_16x16x32_bf16 v[88:91], v[186:189], v[222:225], v[88:91]
	v_mfma_f32_16x16x32_bf16 v[80:83], v[194:197], v[222:225], v[80:83]
	v_mfma_f32_16x16x32_bf16 v[72:75], v[186:189], v[230:233], v[72:75]
	v_mfma_f32_16x16x32_bf16 v[64:67], v[194:197], v[230:233], v[64:67]
	s_setprio 0
	s_barrier
	s_add_i32 s52, s43, s30
	s_add_u32 vcc_lo, s26, 0x80
	s_addc_u32 vcc_hi, s27, 0
	s_mov_b32 m0, s52
	ds_read_b128 v[198:201], v164 offset:16384
	ds_read_b128 v[202:205], v164 offset:17408
	ds_read_b128 v[206:209], v164 offset:18432
	ds_read_b128 v[210:213], v164 offset:19456
	global_load_lds_dwordx4 v132, s[26:27]
	s_add_i32 m0, s52, 0x2000
	s_add_u32 s52, s26, 0x80000
	s_addc_u32 s53, s27, 0
	s_add_i32 s54, s44, s30
	global_load_lds_dwordx4 v128, s[26:27]
	s_mov_b32 m0, s54
	ds_read_b128 v[230:233], v164 offset:23552
	global_load_lds_dwordx4 v132, s[52:53]
	s_add_i32 m0, s54, 0x2000
	ds_read_b128 v[226:229], v164 offset:22528
	global_load_lds_dwordx4 v128, s[52:53]
	s_add_u32 s98, s28, 0x80
	s_addc_u32 s99, s29, 0
	s_mov_b32 m0, s34
	ds_read_b128 v[222:225], v164 offset:21504
	global_load_lds_dwordx4 v134, s[28:29]
	s_mov_b32 m0, s35
	ds_read_b128 v[214:217], v164 offset:20480
	global_load_lds_dwordx4 v130, s[28:29]
	s_cmp_lg_u32 s100, 0
	s_cbranch_scc1 .Lgr_p7_1
	s_waitcnt vmcnt(8)
.Lgr_p7_1:
	s_waitcnt lgkmcnt(0)
	s_barrier
	s_setprio 1
	v_mfma_f32_16x16x32_bf16 v[60:63], v[166:169], v[198:201], v[60:63]
	v_mfma_f32_16x16x32_bf16 v[52:55], v[174:177], v[198:201], v[52:55]
	v_mfma_f32_16x16x32_bf16 v[44:47], v[166:169], v[206:209], v[44:47]
	v_mfma_f32_16x16x32_bf16 v[36:39], v[174:177], v[206:209], v[36:39]
	v_mfma_f32_16x16x32_bf16 v[28:31], v[166:169], v[214:217], v[28:31]
	v_mfma_f32_16x16x32_bf16 v[20:23], v[174:177], v[214:217], v[20:23]
	v_mfma_f32_16x16x32_bf16 v[12:15], v[166:169], v[226:229], v[12:15]
	v_mfma_f32_16x16x32_bf16 v[4:7], v[174:177], v[226:229], v[4:7]
	v_mfma_f32_16x16x32_bf16 v[60:63], v[170:173], v[202:205], v[60:63]
	v_mfma_f32_16x16x32_bf16 v[52:55], v[178:181], v[202:205], v[52:55]
	v_mfma_f32_16x16x32_bf16 v[44:47], v[170:173], v[210:213], v[44:47]
	v_mfma_f32_16x16x32_bf16 v[36:39], v[178:181], v[210:213], v[36:39]
	v_mfma_f32_16x16x32_bf16 v[28:31], v[170:173], v[222:225], v[28:31]
	v_mfma_f32_16x16x32_bf16 v[20:23], v[178:181], v[222:225], v[20:23]
	v_mfma_f32_16x16x32_bf16 v[12:15], v[170:173], v[230:233], v[12:15]
	v_mfma_f32_16x16x32_bf16 v[4:7], v[178:181], v[230:233], v[4:7]
	s_setprio 0
	s_setprio 1
	v_mfma_f32_16x16x32_bf16 v[56:59], v[182:185], v[198:201], v[56:59]
	v_mfma_f32_16x16x32_bf16 v[48:51], v[190:193], v[198:201], v[48:51]
	v_mfma_f32_16x16x32_bf16 v[40:43], v[182:185], v[206:209], v[40:43]
	v_mfma_f32_16x16x32_bf16 v[32:35], v[190:193], v[206:209], v[32:35]
	v_mfma_f32_16x16x32_bf16 v[24:27], v[182:185], v[214:217], v[24:27]
	v_mfma_f32_16x16x32_bf16 v[16:19], v[190:193], v[214:217], v[16:19]
	v_mfma_f32_16x16x32_bf16 v[8:11], v[182:185], v[226:229], v[8:11]
	v_mfma_f32_16x16x32_bf16 v[0:3], v[190:193], v[226:229], v[0:3]
	v_mfma_f32_16x16x32_bf16 v[56:59], v[186:189], v[202:205], v[56:59]
	v_mfma_f32_16x16x32_bf16 v[48:51], v[194:197], v[202:205], v[48:51]
	v_mfma_f32_16x16x32_bf16 v[40:43], v[186:189], v[210:213], v[40:43]
	v_mfma_f32_16x16x32_bf16 v[32:35], v[194:197], v[210:213], v[32:35]
	v_mfma_f32_16x16x32_bf16 v[24:27], v[186:189], v[222:225], v[24:27]
	v_mfma_f32_16x16x32_bf16 v[16:19], v[194:197], v[222:225], v[16:19]
	v_mfma_f32_16x16x32_bf16 v[8:11], v[186:189], v[230:233], v[8:11]
	v_mfma_f32_16x16x32_bf16 v[0:3], v[194:197], v[230:233], v[0:3]
	s_setprio 0
	s_barrier
	s_add_i32 s52, 0, 0x18000
	s_add_i32 s53, 0, 0x1c000
	v_add_u32_e32 v178, s52, v160
	v_add_u32_e32 v194, s53, v160
	ds_read_b128 v[166:169], v178
	ds_read_b128 v[170:173], v178 offset:1024
	ds_read_b128 v[174:177], v178 offset:2048
	ds_read_b128 v[178:181], v178 offset:3072
	ds_read_b128 v[182:185], v194
	ds_read_b128 v[186:189], v194 offset:1024
	ds_read_b128 v[190:193], v194 offset:2048
	ds_read_b128 v[194:197], v194 offset:3072
	s_add_u32 s28, s28, 0x80000
	s_addc_u32 s29, s29, 0
	s_mov_b32 m0, s36
	ds_read_b128 v[198:201], v164 offset:32768
	ds_read_b128 v[202:205], v164 offset:33792
	ds_read_b128 v[206:209], v164 offset:34816
	ds_read_b128 v[210:213], v164 offset:35840
	ds_read_b128 v[214:217], v164 offset:36864
	ds_read_b128 v[222:225], v164 offset:37888
	ds_read_b128 v[226:229], v164 offset:38912
	global_load_lds_dwordx4 v134, s[28:29]
	s_mov_b32 m0, s37
	ds_read_b128 v[230:233], v164 offset:39936
	global_load_lds_dwordx4 v130, s[28:29]
	s_cmp_lg_u32 s100, 0
	s_cbranch_scc1 .Lgr_p7_2
	s_waitcnt vmcnt(8)
; #define PG8_STAGE(bufoff, gbase, voff) do { _Pragma("unroll") for (int _i = 0; _i < 2; ++_i) \
;         __builtin_amdgcn_global_load_lds((const unsigned*)((const char*)(gbase) + (voff)[_i]), (PG8_LAS unsigned*)(lds + (bufoff) + ldsw + _i * 8192), 16, 0, 0); } while (0)
; #define PG8_LDA(dst, b, h) do { _Pragma("unroll") for (int m = 0; m < 4; ++m) _Pragma("unroll") for (int k = 0; k < 2; ++k) dst[m][k] = *(const PG8_LAS bf16x8*)(lds + PG8_SA(b, h) + aoff + m * 2048 + k * 1024); } while (0)
; #define PG8_MMA(ai, bj, At, Bt) do { __builtin_amdgcn_s_setprio(1); _Pragma("unroll") for (int m = 0; m < 4; ++m) _Pragma("unroll") for (int n = 0; n < 2; ++n) _Pragma("unroll") for (int k = 0; k < 2; ++k) \
;         acc[ai][bj][m][n] = __builtin_amdgcn_mfma_f32_16x16x32_bf16(Bt[n][k], At[m][k], acc[ai][bj][m][n], 0, 0, 0); __builtin_amdgcn_s_setprio(0); } while (0)
; #define PG8_WAIT_V(n) asm volatile("s_waitcnt vmcnt(" #n ")" ::: "memory")
; #define PG8_WAIT_L(n) asm volatile("s_waitcnt lgkmcnt(" #n ")" ::: "memory")
; #define PG8_BAR __builtin_amdgcn_s_barrier()
; #define PG8_SCHED __builtin_amdgcn_sched_barrier(0)
; template <class Epi, class Sched, bool ALIGN_EPI = false, bool SP2 = false>
; __device__ __forceinline__ void gemm_phase(PG8_LAS unsigned char* lds, const Gemm g, const Sched& S, const Epi& E) {
;     ...
;         for (int t = 0; t < nt; t += 2) {
;     ...
;             PG8_WAIT_V(8); PG8_WAIT_L(0); PG8_BAR; PG8_MMA(0, 0, At, B0); PG8_MMA(0, 1, At, B1); PG8_BAR; PG8_SCHED;
;             PG8_LDA(At, 1, 1); PG8_STAGE(PG8_SB(1, 0), b3, voffB); PG8_STAGE(PG8_SB(1, 1), b3 + hstep, voffB); PG8_STAGE(PG8_SA(1, 0), a3, voffA);
;             PG8_WAIT_V(8); PG8_WAIT_L(0); PG8_BAR; PG8_MMA(1, 0, At, B0); PG8_MMA(1, 1, At, B1); PG8_BAR; PG8_SCHED;
.Lgr_p7_2:
	s_waitcnt lgkmcnt(0)
	s_barrier
	s_setprio 1
	v_mfma_f32_16x16x32_bf16 v[116:119], v[166:169], v[198:201], v[116:119]
	v_mfma_f32_16x16x32_bf16 v[112:115], v[174:177], v[198:201], v[112:115]
	v_mfma_f32_16x16x32_bf16 v[108:111], v[166:169], v[206:209], v[108:111]
	v_mfma_f32_16x16x32_bf16 v[100:103], v[174:177], v[206:209], v[100:103]
	v_mfma_f32_16x16x32_bf16 v[92:95], v[166:169], v[214:217], v[92:95]
	v_mfma_f32_16x16x32_bf16 v[84:87], v[174:177], v[214:217], v[84:87]
	v_mfma_f32_16x16x32_bf16 v[76:79], v[166:169], v[226:229], v[76:79]
	v_mfma_f32_16x16x32_bf16 v[68:71], v[174:177], v[226:229], v[68:71]
	v_mfma_f32_16x16x32_bf16 v[116:119], v[170:173], v[202:205], v[116:119]
	v_mfma_f32_16x16x32_bf16 v[112:115], v[178:181], v[202:205], v[112:115]
	v_mfma_f32_16x16x32_bf16 v[108:111], v[170:173], v[210:213], v[108:111]
	v_mfma_f32_16x16x32_bf16 v[100:103], v[178:181], v[210:213], v[100:103]
	v_mfma_f32_16x16x32_bf16 v[92:95], v[170:173], v[222:225], v[92:95]
	v_mfma_f32_16x16x32_bf16 v[84:87], v[178:181], v[222:225], v[84:87]
	v_mfma_f32_16x16x32_bf16 v[76:79], v[170:173], v[230:233], v[76:79]
	v_mfma_f32_16x16x32_bf16 v[68:71], v[178:181], v[230:233], v[68:71]
	s_setprio 0
	s_setprio 1
	v_mfma_f32_16x16x32_bf16 v[124:127], v[182:185], v[198:201], v[124:127]
	v_mfma_f32_16x16x32_bf16 v[120:123], v[190:193], v[198:201], v[120:123]
	v_mfma_f32_16x16x32_bf16 v[104:107], v[182:185], v[206:209], v[104:107]
	v_mfma_f32_16x16x32_bf16 v[96:99], v[190:193], v[206:209], v[96:99]
	v_mfma_f32_16x16x32_bf16 v[88:91], v[182:185], v[214:217], v[88:91]
	v_mfma_f32_16x16x32_bf16 v[80:83], v[190:193], v[214:217], v[80:83]
	v_mfma_f32_16x16x32_bf16 v[72:75], v[182:185], v[226:229], v[72:75]
	v_mfma_f32_16x16x32_bf16 v[64:67], v[190:193], v[226:229], v[64:67]
	v_mfma_f32_16x16x32_bf16 v[124:127], v[186:189], v[202:205], v[124:127]
	v_mfma_f32_16x16x32_bf16 v[120:123], v[194:197], v[202:205], v[120:123]
	v_mfma_f32_16x16x32_bf16 v[104:107], v[186:189], v[210:213], v[104:107]
	v_mfma_f32_16x16x32_bf16 v[96:99], v[194:197], v[210:213], v[96:99]
	v_mfma_f32_16x16x32_bf16 v[88:91], v[186:189], v[222:225], v[88:91]
	v_mfma_f32_16x16x32_bf16 v[80:83], v[194:197], v[222:225], v[80:83]
	v_mfma_f32_16x16x32_bf16 v[72:75], v[186:189], v[230:233], v[72:75]
	v_mfma_f32_16x16x32_bf16 v[64:67], v[194:197], v[230:233], v[64:67]
	s_setprio 0
	s_barrier
	s_add_i32 s28, s52, s30
	s_mov_b32 m0, s28
	ds_read_b128 v[198:201], v164 offset:49152
	ds_read_b128 v[202:205], v164 offset:50176
	ds_read_b128 v[206:209], v164 offset:51200
	ds_read_b128 v[210:213], v164 offset:52224
	global_load_lds_dwordx4 v132, vcc
	s_add_i32 m0, s28, 0x2000
	s_add_u32 s26, s26, 0x80080
	s_addc_u32 s27, s27, 0
	s_add_i32 s28, s53, s30
	global_load_lds_dwordx4 v128, vcc
	s_mov_b32 m0, s28
	ds_read_b128 v[230:233], v164 offset:56320
	global_load_lds_dwordx4 v132, s[26:27]
	s_add_i32 m0, s28, 0x2000
	ds_read_b128 v[226:229], v164 offset:55296
	global_load_lds_dwordx4 v128, s[26:27]
	s_mov_b32 m0, s39
	ds_read_b128 v[222:225], v164 offset:54272
	global_load_lds_dwordx4 v134, s[98:99]
	s_mov_b32 m0, s40
	ds_read_b128 v[214:217], v164 offset:53248
	global_load_lds_dwordx4 v130, s[98:99]
	s_waitcnt vmcnt(8)
	s_waitcnt lgkmcnt(0)
	s_barrier
	s_setprio 1
	v_mfma_f32_16x16x32_bf16 v[60:63], v[166:169], v[198:201], v[60:63]
	v_mfma_f32_16x16x32_bf16 v[52:55], v[174:177], v[198:201], v[52:55]
	v_mfma_f32_16x16x32_bf16 v[44:47], v[166:169], v[206:209], v[44:47]
	v_mfma_f32_16x16x32_bf16 v[36:39], v[174:177], v[206:209], v[36:39]
	v_mfma_f32_16x16x32_bf16 v[28:31], v[166:169], v[214:217], v[28:31]
	v_mfma_f32_16x16x32_bf16 v[20:23], v[174:177], v[214:217], v[20:23]
	v_mfma_f32_16x16x32_bf16 v[12:15], v[166:169], v[226:229], v[12:15]
	v_mfma_f32_16x16x32_bf16 v[4:7], v[174:177], v[226:229], v[4:7]
	v_mfma_f32_16x16x32_bf16 v[60:63], v[170:173], v[202:205], v[60:63]
	v_mfma_f32_16x16x32_bf16 v[52:55], v[178:181], v[202:205], v[52:55]
	v_mfma_f32_16x16x32_bf16 v[44:47], v[170:173], v[210:213], v[44:47]
	v_mfma_f32_16x16x32_bf16 v[36:39], v[178:181], v[210:213], v[36:39]
	v_mfma_f32_16x16x32_bf16 v[28:31], v[170:173], v[222:225], v[28:31]
	v_mfma_f32_16x16x32_bf16 v[20:23], v[178:181], v[222:225], v[20:23]
	v_mfma_f32_16x16x32_bf16 v[12:15], v[170:173], v[230:233], v[12:15]
	v_mfma_f32_16x16x32_bf16 v[4:7], v[178:181], v[230:233], v[4:7]
	s_setprio 0
	s_setprio 1
	v_mfma_f32_16x16x32_bf16 v[56:59], v[182:185], v[198:201], v[56:59]
	v_mfma_f32_16x16x32_bf16 v[48:51], v[190:193], v[198:201], v[48:51]
	v_mfma_f32_16x16x32_bf16 v[40:43], v[182:185], v[206:209], v[40:43]
	v_mfma_f32_16x16x32_bf16 v[32:35], v[190:193], v[206:209], v[32:35]
	v_mfma_f32_16x16x32_bf16 v[24:27], v[182:185], v[214:217], v[24:27]
	v_mfma_f32_16x16x32_bf16 v[16:19], v[190:193], v[214:217], v[16:19]
	v_mfma_f32_16x16x32_bf16 v[8:11], v[182:185], v[226:229], v[8:11]
	v_mfma_f32_16x16x32_bf16 v[0:3], v[190:193], v[226:229], v[0:3]
	v_mfma_f32_16x16x32_bf16 v[56:59], v[186:189], v[202:205], v[56:59]
	v_mfma_f32_16x16x32_bf16 v[48:51], v[194:197], v[202:205], v[48:51]
	v_mfma_f32_16x16x32_bf16 v[40:43], v[186:189], v[210:213], v[40:43]
	v_mfma_f32_16x16x32_bf16 v[32:35], v[194:197], v[210:213], v[32:35]
	v_mfma_f32_16x16x32_bf16 v[24:27], v[186:189], v[222:225], v[24:27]
	v_mfma_f32_16x16x32_bf16 v[16:19], v[194:197], v[222:225], v[16:19]
	v_mfma_f32_16x16x32_bf16 v[8:11], v[186:189], v[230:233], v[8:11]
	v_mfma_f32_16x16x32_bf16 v[0:3], v[194:197], v[230:233], v[0:3]
	s_setprio 0
	s_barrier
	s_mov_b32 s100, 0
	s_add_i32 s51, s51, 2
	s_add_u32 s24, s24, 0x100
	s_addc_u32 s25, s25, 0
	s_add_u32 s49, s49, 0x100
	s_addc_u32 s50, s50, 0
	s_cmp_gt_u32 s51, 29
	s_cbranch_scc0 .LBB0_1076
	s_and_b64 vcc, exec, s[14:15]
	s_cbranch_vccz .LBB0_1079
	s_barrier

; #define PG8_STAGE(bufoff, gbase, voff) do { _Pragma("unroll") for (int _i = 0; _i < 2; ++_i) \
;         __builtin_amdgcn_global_load_lds((const unsigned*)((const char*)(gbase) + (voff)[_i]), (PG8_LAS unsigned*)(lds + (bufoff) + ldsw + _i * 8192), 16, 0, 0); } while (0)
; #define PG8_LDA(dst, b, h) do { _Pragma("unroll") for (int m = 0; m < 4; ++m) _Pragma("unroll") for (int k = 0; k < 2; ++k) dst[m][k] = *(const PG8_LAS bf16x8*)(lds + PG8_SA(b, h) + aoff + m * 2048 + k * 1024); } while (0)
; #define PG8_LDB(dst, b, h) do { _Pragma("unroll") for (int n = 0; n < 2; ++n) _Pragma("unroll") for (int k = 0; k < 2; ++k) dst[n][k] = *(const PG8_LAS bf16x8*)(lds + PG8_SB(b, h) + boff + n * 2048 + k * 1024); } while (0)
; #define PG8_MMA(ai, bj, At, Bt) do { __builtin_amdgcn_s_setprio(1); _Pragma("unroll") for (int m = 0; m < 4; ++m) _Pragma("unroll") for (int n = 0; n < 2; ++n) _Pragma("unroll") for (int k = 0; k < 2; ++k) \
;         acc[ai][bj][m][n] = __builtin_amdgcn_mfma_f32_16x16x32_bf16(Bt[n][k], At[m][k], acc[ai][bj][m][n], 0, 0, 0); __builtin_amdgcn_s_setprio(0); } while (0)
; #define PG8_WAIT_V(n) asm volatile("s_waitcnt vmcnt(" #n ")" ::: "memory")
; #define PG8_WAIT_L(n) asm volatile("s_waitcnt lgkmcnt(" #n ")" ::: "memory")
; template <class Epi, class Sched, bool ALIGN_EPI = false, bool SP2 = false>
; __device__ __forceinline__ void gemm_phase(PG8_LAS unsigned char* lds, const Gemm g, const Sched& S, const Epi& E) {
;     ...
;             const bool last = (t == nt - 2);
;             const char* a1 = cA + (size_t)(t + 1) * kstep;
;             const char* a2 = last ? nA : cA + (size_t)(t + 2) * kstep; const char* b2 = last ? nB : cB + (size_t)(t + 2) * kstep;
;             const char* a3 = a2 + kstep; const char* b3 = b2 + kstep;
;             if (last && has_next) S.a_ready(nxt);
;             if constexpr (SP2) {
;             PG8_LDB(B0, 0, 0); PG8_LDB(B1, 0, 1); PG8_SCHED; PG8_LDA(At, 0, 0); PG8_STAGE(PG8_SA(1, 1), a1 + hstep, voffA);
;             PG8_WAIT_V(8); PG8_WAIT_L(0); PG8_BAR; PG8_MMA(0, 0, At, B0); PG8_MMA(0, 1, At, B1); PG8_BAR; PG8_SCHED;
;             PG8_LDA(At, 0, 1); PG8_STAGE(PG8_SB(0, 0), b2, voffB); PG8_STAGE(PG8_SB(0, 1), b2 + hstep, voffB); PG8_STAGE(PG8_SA(0, 0), a2, voffA);
;             PG8_WAIT_V(8); PG8_WAIT_L(0); PG8_BAR; PG8_MMA(1, 0, At, B0); PG8_MMA(1, 1, At, B1); PG8_BAR; PG8_SCHED;
.LBB0_1107:
	ds_read_b128 v[156:159], v148
	ds_read_b128 v[160:163], v148 offset:1024
	ds_read_b128 v[164:167], v148 offset:2048
	ds_read_b128 v[168:171], v148 offset:3072
	ds_read_b128 v[172:175], v149
	ds_read_b128 v[176:179], v149 offset:1024
	ds_read_b128 v[180:183], v149 offset:2048
	ds_read_b128 v[184:187], v149 offset:3072
	s_add_i32 s56, s30, 2
	s_add_u32 s57, s28, 0x80
	s_addc_u32 s31, s29, 0
	s_cmp_eq_u32 s43, s30
	s_cselect_b32 s30, s4, s57
	s_cselect_b32 s31, s5, s31
	s_cselect_b32 s59, s27, s55
	s_cselect_b32 s58, s26, s54
	v_lshl_add_u64 v[146:147], s[28:29], 0, v[138:139]
	s_add_i32 m0, s36, 0xc000
	ds_read_b128 v[188:191], v150
	ds_read_b128 v[192:195], v150 offset:1024
	ds_read_b128 v[196:199], v150 offset:2048
	ds_read_b128 v[200:203], v150 offset:3072
	ds_read_b128 v[204:207], v150 offset:4096
	ds_read_b128 v[208:211], v150 offset:5120
	ds_read_b128 v[212:215], v150 offset:6144
	ds_read_b128 v[216:219], v150 offset:7168
	global_load_lds_dwordx4 v[146:147], off
	v_lshl_add_u64 v[146:147], s[28:29], 0, v[140:141]
	s_add_i32 m0, s36, 0xe000
	s_nop 0
	global_load_lds_dwordx4 v[146:147], off
	s_waitcnt vmcnt(8)
	s_waitcnt lgkmcnt(0)
	s_barrier
	s_setprio 1
	v_mfma_f32_16x16x32_bf16 v[124:127], v[156:159], v[188:191], v[124:127]
	v_mfma_f32_16x16x32_bf16 v[120:123], v[164:167], v[188:191], v[120:123]
	v_mfma_f32_16x16x32_bf16 v[108:111], v[156:159], v[196:199], v[108:111]
	v_mfma_f32_16x16x32_bf16 v[104:107], v[164:167], v[196:199], v[104:107]
	v_mfma_f32_16x16x32_bf16 v[92:95], v[156:159], v[204:207], v[92:95]
	v_mfma_f32_16x16x32_bf16 v[88:91], v[164:167], v[204:207], v[88:91]
	v_mfma_f32_16x16x32_bf16 v[76:79], v[156:159], v[212:215], v[76:79]
	v_mfma_f32_16x16x32_bf16 v[72:75], v[164:167], v[212:215], v[72:75]
	v_mfma_f32_16x16x32_bf16 v[124:127], v[160:163], v[192:195], v[124:127]
	v_mfma_f32_16x16x32_bf16 v[120:123], v[168:171], v[192:195], v[120:123]
	v_mfma_f32_16x16x32_bf16 v[108:111], v[160:163], v[200:203], v[108:111]
	v_mfma_f32_16x16x32_bf16 v[104:107], v[168:171], v[200:203], v[104:107]
	v_mfma_f32_16x16x32_bf16 v[92:95], v[160:163], v[208:211], v[92:95]
	v_mfma_f32_16x16x32_bf16 v[88:91], v[168:171], v[208:211], v[88:91]
	v_mfma_f32_16x16x32_bf16 v[76:79], v[160:163], v[216:219], v[76:79]
	v_mfma_f32_16x16x32_bf16 v[72:75], v[168:171], v[216:219], v[72:75]
	s_setprio 0
	s_setprio 1
	v_mfma_f32_16x16x32_bf16 v[116:119], v[172:175], v[188:191], v[116:119]
	v_mfma_f32_16x16x32_bf16 v[112:115], v[180:183], v[188:191], v[112:115]
	v_mfma_f32_16x16x32_bf16 v[100:103], v[172:175], v[196:199], v[100:103]
	v_mfma_f32_16x16x32_bf16 v[96:99], v[180:183], v[196:199], v[96:99]
	v_mfma_f32_16x16x32_bf16 v[84:87], v[172:175], v[204:207], v[84:87]
	v_mfma_f32_16x16x32_bf16 v[80:83], v[180:183], v[204:207], v[80:83]
	v_mfma_f32_16x16x32_bf16 v[68:71], v[172:175], v[212:215], v[68:71]
	v_mfma_f32_16x16x32_bf16 v[64:67], v[180:183], v[212:215], v[64:67]
	v_mfma_f32_16x16x32_bf16 v[116:119], v[176:179], v[192:195], v[116:119]
	v_mfma_f32_16x16x32_bf16 v[112:115], v[184:187], v[192:195], v[112:115]
	v_mfma_f32_16x16x32_bf16 v[100:103], v[176:179], v[200:203], v[100:103]
	v_mfma_f32_16x16x32_bf16 v[96:99], v[184:187], v[200:203], v[96:99]
	v_mfma_f32_16x16x32_bf16 v[84:87], v[176:179], v[208:211], v[84:87]
	v_mfma_f32_16x16x32_bf16 v[80:83], v[184:187], v[208:211], v[80:83]
	v_mfma_f32_16x16x32_bf16 v[68:71], v[176:179], v[216:219], v[68:71]
	v_mfma_f32_16x16x32_bf16 v[64:67], v[184:187], v[216:219], v[64:67]
	s_setprio 0
	s_barrier
	s_add_i32 s57, s47, s33
	v_lshl_add_u64 v[146:147], s[58:59], 0, v[130:131]
	s_mov_b32 m0, s57
	ds_read_b128 v[188:191], v150 offset:16384
	ds_read_b128 v[192:195], v150 offset:17408
	ds_read_b128 v[196:199], v150 offset:18432
	ds_read_b128 v[200:203], v150 offset:19456
	ds_read_b128 v[204:207], v150 offset:20480
	ds_read_b128 v[208:211], v150 offset:21504
	ds_read_b128 v[212:215], v150 offset:22528
	ds_read_b128 v[216:219], v150 offset:23552
	global_load_lds_dwordx4 v[146:147], off
	s_add_i32 m0, s57, 0x2000
	v_lshl_add_u64 v[222:223], s[58:59], 0, v[134:135]
	s_add_u32 s58, s58, s10
	s_addc_u32 s59, s59, s11
	s_add_i32 s57, s48, s33
	global_load_lds_dwordx4 v[222:223], off
	v_lshl_add_u64 v[224:225], s[58:59], 0, v[130:131]
	s_mov_b32 m0, s57
	v_lshl_add_u64 v[226:227], s[58:59], 0, v[134:135]
	global_load_lds_dwordx4 v[224:225], off
	s_add_i32 m0, s57, 0x2000
	v_lshl_add_u64 v[228:229], s[30:31], 0, v[128:129]
	global_load_lds_dwordx4 v[226:227], off
	s_mov_b32 m0, s36
	v_lshl_add_u64 v[230:231], s[30:31], 0, v[132:133]
	global_load_lds_dwordx4 v[228:229], off
	s_mov_b32 m0, s37
	s_nop 0
	global_load_lds_dwordx4 v[230:231], off
	s_waitcnt vmcnt(8)
	s_waitcnt lgkmcnt(0)
	s_barrier
; #define PG8_STAGE(bufoff, gbase, voff) do { _Pragma("unroll") for (int _i = 0; _i < 2; ++_i) \
;         __builtin_amdgcn_global_load_lds((const unsigned*)((const char*)(gbase) + (voff)[_i]), (PG8_LAS unsigned*)(lds + (bufoff) + ldsw + _i * 8192), 16, 0, 0); } while (0)
; #define PG8_LDA(dst, b, h) do { _Pragma("unroll") for (int m = 0; m < 4; ++m) _Pragma("unroll") for (int k = 0; k < 2; ++k) dst[m][k] = *(const PG8_LAS bf16x8*)(lds + PG8_SA(b, h) + aoff + m * 2048 + k * 1024); } while (0)
; #define PG8_LDB(dst, b, h) do { _Pragma("unroll") for (int n = 0; n < 2; ++n) _Pragma("unroll") for (int k = 0; k < 2; ++k) dst[n][k] = *(const PG8_LAS bf16x8*)(lds + PG8_SB(b, h) + boff + n * 2048 + k * 1024); } while (0)
; #define PG8_MMA(ai, bj, At, Bt) do { __builtin_amdgcn_s_setprio(1); _Pragma("unroll") for (int m = 0; m < 4; ++m) _Pragma("unroll") for (int n = 0; n < 2; ++n) _Pragma("unroll") for (int k = 0; k < 2; ++k) \
;         acc[ai][bj][m][n] = __builtin_amdgcn_mfma_f32_16x16x32_bf16(Bt[n][k], At[m][k], acc[ai][bj][m][n], 0, 0, 0); __builtin_amdgcn_s_setprio(0); } while (0)
; #define PG8_WAIT_V(n) asm volatile("s_waitcnt vmcnt(" #n ")" ::: "memory")
; #define PG8_WAIT_L(n) asm volatile("s_waitcnt lgkmcnt(" #n ")" ::: "memory")
; #define PG8_BAR __builtin_amdgcn_s_barrier()
; #define PG8_SCHED __builtin_amdgcn_sched_barrier(0)
; template <class Epi, class Sched, bool ALIGN_EPI = false, bool SP2 = false>
; __device__ __forceinline__ void gemm_phase(PG8_LAS unsigned char* lds, const Gemm g, const Sched& S, const Epi& E) {
;     ...
;             PG8_WAIT_V(8); PG8_WAIT_L(0); PG8_BAR; PG8_MMA(1, 0, At, B0); PG8_MMA(1, 1, At, B1); PG8_BAR; PG8_SCHED;
;             PG8_LDB(B0, 1, 0); PG8_LDB(B1, 1, 1); PG8_SCHED; PG8_LDA(At, 1, 0); PG8_STAGE(PG8_SA(0, 1), a2 + hstep, voffA);
;             PG8_WAIT_V(8); PG8_WAIT_L(0); PG8_BAR; PG8_MMA(0, 0, At, B0); PG8_MMA(0, 1, At, B1); PG8_BAR; PG8_SCHED;
	s_setprio 1
	v_mfma_f32_16x16x32_bf16 v[60:63], v[156:159], v[188:191], v[60:63]
	v_mfma_f32_16x16x32_bf16 v[56:59], v[164:167], v[188:191], v[56:59]
	v_mfma_f32_16x16x32_bf16 v[44:47], v[156:159], v[196:199], v[44:47]
	v_mfma_f32_16x16x32_bf16 v[40:43], v[164:167], v[196:199], v[40:43]
	v_mfma_f32_16x16x32_bf16 v[28:31], v[156:159], v[204:207], v[28:31]
	v_mfma_f32_16x16x32_bf16 v[24:27], v[164:167], v[204:207], v[24:27]
	v_mfma_f32_16x16x32_bf16 v[12:15], v[156:159], v[212:215], v[12:15]
	v_mfma_f32_16x16x32_bf16 v[8:11], v[164:167], v[212:215], v[8:11]
	v_mfma_f32_16x16x32_bf16 v[60:63], v[160:163], v[192:195], v[60:63]
	v_mfma_f32_16x16x32_bf16 v[56:59], v[168:171], v[192:195], v[56:59]
	v_mfma_f32_16x16x32_bf16 v[44:47], v[160:163], v[200:203], v[44:47]
	v_mfma_f32_16x16x32_bf16 v[40:43], v[168:171], v[200:203], v[40:43]
	v_mfma_f32_16x16x32_bf16 v[28:31], v[160:163], v[208:211], v[28:31]
	v_mfma_f32_16x16x32_bf16 v[24:27], v[168:171], v[208:211], v[24:27]
	v_mfma_f32_16x16x32_bf16 v[12:15], v[160:163], v[216:219], v[12:15]
	v_mfma_f32_16x16x32_bf16 v[8:11], v[168:171], v[216:219], v[8:11]
	s_setprio 0
	s_setprio 1
	v_mfma_f32_16x16x32_bf16 v[52:55], v[172:175], v[188:191], v[52:55]
	v_mfma_f32_16x16x32_bf16 v[48:51], v[180:183], v[188:191], v[48:51]
	v_mfma_f32_16x16x32_bf16 v[36:39], v[172:175], v[196:199], v[36:39]
	v_mfma_f32_16x16x32_bf16 v[32:35], v[180:183], v[196:199], v[32:35]
	v_mfma_f32_16x16x32_bf16 v[20:23], v[172:175], v[204:207], v[20:23]
	v_mfma_f32_16x16x32_bf16 v[16:19], v[180:183], v[204:207], v[16:19]
	v_mfma_f32_16x16x32_bf16 v[4:7], v[172:175], v[212:215], v[4:7]
	v_mfma_f32_16x16x32_bf16 v[0:3], v[180:183], v[212:215], v[0:3]
	v_mfma_f32_16x16x32_bf16 v[52:55], v[176:179], v[192:195], v[52:55]
	v_mfma_f32_16x16x32_bf16 v[48:51], v[184:187], v[192:195], v[48:51]
	v_mfma_f32_16x16x32_bf16 v[36:39], v[176:179], v[200:203], v[36:39]
	v_mfma_f32_16x16x32_bf16 v[32:35], v[184:187], v[200:203], v[32:35]
	v_mfma_f32_16x16x32_bf16 v[20:23], v[176:179], v[208:211], v[20:23]
	v_mfma_f32_16x16x32_bf16 v[16:19], v[184:187], v[208:211], v[16:19]
	v_mfma_f32_16x16x32_bf16 v[4:7], v[176:179], v[216:219], v[4:7]
	v_mfma_f32_16x16x32_bf16 v[0:3], v[184:187], v[216:219], v[0:3]
	s_setprio 0
	s_barrier
	s_add_i32 s57, 0, 0x18000
	v_add_u32_e32 v153, s57, v151
	s_add_i32 s58, 0, 0x1c000
	ds_read_b128 v[156:159], v153
	ds_read_b128 v[160:163], v153 offset:1024
	ds_read_b128 v[164:167], v153 offset:2048
	ds_read_b128 v[168:171], v153 offset:3072
	v_add_u32_e32 v153, s58, v151
	ds_read_b128 v[172:175], v153
	ds_read_b128 v[176:179], v153 offset:1024
	ds_read_b128 v[180:183], v153 offset:2048
	ds_read_b128 v[184:187], v153 offset:3072
	s_add_u32 s30, s30, s10
	s_addc_u32 s31, s31, s11
	s_mov_b32 m0, s38
	v_lshl_add_u64 v[232:233], s[30:31], 0, v[128:129]
	ds_read_b128 v[188:191], v150 offset:32768
	ds_read_b128 v[192:195], v150 offset:33792
	ds_read_b128 v[196:199], v150 offset:34816
	ds_read_b128 v[200:203], v150 offset:35840
	ds_read_b128 v[204:207], v150 offset:36864
	ds_read_b128 v[208:211], v150 offset:37888
	ds_read_b128 v[212:215], v150 offset:38912
	ds_read_b128 v[216:219], v150 offset:39936
	global_load_lds_dwordx4 v[232:233], off
	v_lshl_add_u64 v[232:233], s[30:31], 0, v[132:133]
	s_mov_b32 m0, s39
	s_nop 0
	global_load_lds_dwordx4 v[232:233], off
	s_waitcnt vmcnt(8)
	s_waitcnt lgkmcnt(0)
	s_barrier
	s_setprio 1
	v_mfma_f32_16x16x32_bf16 v[124:127], v[156:159], v[188:191], v[124:127]
	v_mfma_f32_16x16x32_bf16 v[120:123], v[164:167], v[188:191], v[120:123]
	v_mfma_f32_16x16x32_bf16 v[108:111], v[156:159], v[196:199], v[108:111]
	v_mfma_f32_16x16x32_bf16 v[104:107], v[164:167], v[196:199], v[104:107]
	v_mfma_f32_16x16x32_bf16 v[92:95], v[156:159], v[204:207], v[92:95]
	v_mfma_f32_16x16x32_bf16 v[88:91], v[164:167], v[204:207], v[88:91]
	v_mfma_f32_16x16x32_bf16 v[76:79], v[156:159], v[212:215], v[76:79]
	v_mfma_f32_16x16x32_bf16 v[72:75], v[164:167], v[212:215], v[72:75]
	v_mfma_f32_16x16x32_bf16 v[124:127], v[160:163], v[192:195], v[124:127]
	v_mfma_f32_16x16x32_bf16 v[120:123], v[168:171], v[192:195], v[120:123]
	v_mfma_f32_16x16x32_bf16 v[108:111], v[160:163], v[200:203], v[108:111]
	v_mfma_f32_16x16x32_bf16 v[104:107], v[168:171], v[200:203], v[104:107]
	v_mfma_f32_16x16x32_bf16 v[92:95], v[160:163], v[208:211], v[92:95]
	v_mfma_f32_16x16x32_bf16 v[88:91], v[168:171], v[208:211], v[88:91]
	v_mfma_f32_16x16x32_bf16 v[76:79], v[160:163], v[216:219], v[76:79]
	v_mfma_f32_16x16x32_bf16 v[72:75], v[168:171], v[216:219], v[72:75]
	s_setprio 0
	s_setprio 1
	v_mfma_f32_16x16x32_bf16 v[116:119], v[172:175], v[188:191], v[116:119]
	v_mfma_f32_16x16x32_bf16 v[112:115], v[180:183], v[188:191], v[112:115]
	v_mfma_f32_16x16x32_bf16 v[100:103], v[172:175], v[196:199], v[100:103]
	v_mfma_f32_16x16x32_bf16 v[96:99], v[180:183], v[196:199], v[96:99]
	v_mfma_f32_16x16x32_bf16 v[84:87], v[172:175], v[204:207], v[84:87]
	v_mfma_f32_16x16x32_bf16 v[80:83], v[180:183], v[204:207], v[80:83]
	v_mfma_f32_16x16x32_bf16 v[68:71], v[172:175], v[212:215], v[68:71]
	v_mfma_f32_16x16x32_bf16 v[64:67], v[180:183], v[212:215], v[64:67]
	v_mfma_f32_16x16x32_bf16 v[116:119], v[176:179], v[192:195], v[116:119]
	v_mfma_f32_16x16x32_bf16 v[112:115], v[184:187], v[192:195], v[112:115]
	v_mfma_f32_16x16x32_bf16 v[100:103], v[176:179], v[200:203], v[100:103]
	v_mfma_f32_16x16x32_bf16 v[96:99], v[184:187], v[200:203], v[96:99]
	v_mfma_f32_16x16x32_bf16 v[84:87], v[176:179], v[208:211], v[84:87]
	v_mfma_f32_16x16x32_bf16 v[80:83], v[184:187], v[208:211], v[80:83]
	v_mfma_f32_16x16x32_bf16 v[68:71], v[176:179], v[216:219], v[68:71]
	v_mfma_f32_16x16x32_bf16 v[64:67], v[184:187], v[216:219], v[64:67]
	s_setprio 0
	s_barrier
; #define PG8_STAGE(bufoff, gbase, voff) do { _Pragma("unroll") for (int _i = 0; _i < 2; ++_i) \
;         __builtin_amdgcn_global_load_lds((const unsigned*)((const char*)(gbase) + (voff)[_i]), (PG8_LAS unsigned*)(lds + (bufoff) + ldsw + _i * 8192), 16, 0, 0); } while (0)
; #define PG8_LDA(dst, b, h) do { _Pragma("unroll") for (int m = 0; m < 4; ++m) _Pragma("unroll") for (int k = 0; k < 2; ++k) dst[m][k] = *(const PG8_LAS bf16x8*)(lds + PG8_SA(b, h) + aoff + m * 2048 + k * 1024); } while (0)
; #define PG8_MMA(ai, bj, At, Bt) do { __builtin_amdgcn_s_setprio(1); _Pragma("unroll") for (int m = 0; m < 4; ++m) _Pragma("unroll") for (int n = 0; n < 2; ++n) _Pragma("unroll") for (int k = 0; k < 2; ++k) \
;         acc[ai][bj][m][n] = __builtin_amdgcn_mfma_f32_16x16x32_bf16(Bt[n][k], At[m][k], acc[ai][bj][m][n], 0, 0, 0); __builtin_amdgcn_s_setprio(0); } while (0)
; #define PG8_WAIT_V(n) asm volatile("s_waitcnt vmcnt(" #n ")" ::: "memory")
; #define PG8_WAIT_L(n) asm volatile("s_waitcnt lgkmcnt(" #n ")" ::: "memory")
; #define PG8_BAR __builtin_amdgcn_s_barrier()
; #define PG8_SCHED __builtin_amdgcn_sched_barrier(0)
; template <class Epi, class Sched, bool ALIGN_EPI = false, bool SP2 = false>
; __device__ __forceinline__ void gemm_phase(PG8_LAS unsigned char* lds, const Gemm g, const Sched& S, const Epi& E) {
;     ...
;             PG8_LDA(At, 1, 1); PG8_STAGE(PG8_SB(1, 0), b3, voffB); PG8_STAGE(PG8_SB(1, 1), b3 + hstep, voffB); PG8_STAGE(PG8_SA(1, 0), a3, voffA);
;             PG8_WAIT_V(8); PG8_WAIT_L(0); PG8_BAR; PG8_MMA(1, 0, At, B0); PG8_MMA(1, 1, At, B1); PG8_BAR; PG8_SCHED;
	s_add_i32 s30, s57, s33
	v_lshl_add_u64 v[146:147], v[146:147], 0, s[20:21]
	s_mov_b32 m0, s30
	ds_read_b128 v[188:191], v150 offset:49152
	ds_read_b128 v[192:195], v150 offset:50176
	ds_read_b128 v[196:199], v150 offset:51200
	ds_read_b128 v[200:203], v150 offset:52224
	ds_read_b128 v[204:207], v150 offset:53248
	ds_read_b128 v[208:211], v150 offset:54272
	ds_read_b128 v[212:215], v150 offset:55296
	ds_read_b128 v[216:219], v150 offset:56320
	global_load_lds_dwordx4 v[146:147], off
	v_lshl_add_u64 v[146:147], v[222:223], 0, s[20:21]
	s_add_i32 m0, s30, 0x2000
	s_add_i32 s30, s58, s33
	global_load_lds_dwordx4 v[146:147], off
	v_lshl_add_u64 v[146:147], v[224:225], 0, s[20:21]
	s_mov_b32 m0, s30
	s_nop 0
	global_load_lds_dwordx4 v[146:147], off
	v_lshl_add_u64 v[146:147], v[226:227], 0, s[20:21]
	s_add_i32 m0, s30, 0x2000
	s_nop 0
	global_load_lds_dwordx4 v[146:147], off
	v_lshl_add_u64 v[146:147], v[228:229], 0, s[20:21]
	s_mov_b32 m0, s40
	s_nop 0
	global_load_lds_dwordx4 v[146:147], off
	v_lshl_add_u64 v[146:147], v[230:231], 0, s[20:21]
	s_mov_b32 m0, s41
	s_nop 0
	global_load_lds_dwordx4 v[146:147], off
	s_waitcnt vmcnt(8)
	s_waitcnt lgkmcnt(0)
	s_barrier
	s_setprio 1
	v_mfma_f32_16x16x32_bf16 v[60:63], v[156:159], v[188:191], v[60:63]
	v_mfma_f32_16x16x32_bf16 v[56:59], v[164:167], v[188:191], v[56:59]
	v_mfma_f32_16x16x32_bf16 v[44:47], v[156:159], v[196:199], v[44:47]
	v_mfma_f32_16x16x32_bf16 v[40:43], v[164:167], v[196:199], v[40:43]
	v_mfma_f32_16x16x32_bf16 v[28:31], v[156:159], v[204:207], v[28:31]
	v_mfma_f32_16x16x32_bf16 v[24:27], v[164:167], v[204:207], v[24:27]
	v_mfma_f32_16x16x32_bf16 v[12:15], v[156:159], v[212:215], v[12:15]
	v_mfma_f32_16x16x32_bf16 v[8:11], v[164:167], v[212:215], v[8:11]
	v_mfma_f32_16x16x32_bf16 v[60:63], v[160:163], v[192:195], v[60:63]
	v_mfma_f32_16x16x32_bf16 v[56:59], v[168:171], v[192:195], v[56:59]
	v_mfma_f32_16x16x32_bf16 v[44:47], v[160:163], v[200:203], v[44:47]
	v_mfma_f32_16x16x32_bf16 v[40:43], v[168:171], v[200:203], v[40:43]
	v_mfma_f32_16x16x32_bf16 v[28:31], v[160:163], v[208:211], v[28:31]
	v_mfma_f32_16x16x32_bf16 v[24:27], v[168:171], v[208:211], v[24:27]
	v_mfma_f32_16x16x32_bf16 v[12:15], v[160:163], v[216:219], v[12:15]
	v_mfma_f32_16x16x32_bf16 v[8:11], v[168:171], v[216:219], v[8:11]
	s_setprio 0
	s_setprio 1
	v_mfma_f32_16x16x32_bf16 v[52:55], v[172:175], v[188:191], v[52:55]
	v_mfma_f32_16x16x32_bf16 v[48:51], v[180:183], v[188:191], v[48:51]
	v_mfma_f32_16x16x32_bf16 v[36:39], v[172:175], v[196:199], v[36:39]
	v_mfma_f32_16x16x32_bf16 v[32:35], v[180:183], v[196:199], v[32:35]
	v_mfma_f32_16x16x32_bf16 v[20:23], v[172:175], v[204:207], v[20:23]
	v_mfma_f32_16x16x32_bf16 v[16:19], v[180:183], v[204:207], v[16:19]
	v_mfma_f32_16x16x32_bf16 v[4:7], v[172:175], v[212:215], v[4:7]
	v_mfma_f32_16x16x32_bf16 v[0:3], v[180:183], v[212:215], v[0:3]
	v_mfma_f32_16x16x32_bf16 v[52:55], v[176:179], v[192:195], v[52:55]
	v_mfma_f32_16x16x32_bf16 v[48:51], v[184:187], v[192:195], v[48:51]
	v_mfma_f32_16x16x32_bf16 v[36:39], v[176:179], v[200:203], v[36:39]
	v_mfma_f32_16x16x32_bf16 v[32:35], v[184:187], v[200:203], v[32:35]
	v_mfma_f32_16x16x32_bf16 v[20:23], v[176:179], v[208:211], v[20:23]
	v_mfma_f32_16x16x32_bf16 v[16:19], v[184:187], v[208:211], v[16:19]
	v_mfma_f32_16x16x32_bf16 v[4:7], v[176:179], v[216:219], v[4:7]
	v_mfma_f32_16x16x32_bf16 v[0:3], v[184:187], v[216:219], v[0:3]
	s_setprio 0
	s_barrier
	s_add_u32 s28, s28, 0x100
	s_addc_u32 s29, s29, 0
	s_add_u32 s54, s54, 0x100
	s_addc_u32 s55, s55, 0
	s_cmp_ge_i32 s56, s42
	s_mov_b32 s30, s56
	s_cbranch_scc0 .LBB0_1107

; #define PG8_STAGE(bufoff, gbase, voff) do { _Pragma("unroll") for (int _i = 0; _i < 2; ++_i) \
;         __builtin_amdgcn_global_load_lds((const unsigned*)((const char*)(gbase) + (voff)[_i]), (PG8_LAS unsigned*)(lds + (bufoff) + ldsw + _i * 8192), 16, 0, 0); } while (0)
; #define PG8_LDA(dst, b, h) do { _Pragma("unroll") for (int m = 0; m < 4; ++m) _Pragma("unroll") for (int k = 0; k < 2; ++k) dst[m][k] = *(const PG8_LAS bf16x8*)(lds + PG8_SA(b, h) + aoff + m * 2048 + k * 1024); } while (0)
; #define PG8_LDB(dst, b, h) do { _Pragma("unroll") for (int n = 0; n < 2; ++n) _Pragma("unroll") for (int k = 0; k < 2; ++k) dst[n][k] = *(const PG8_LAS bf16x8*)(lds + PG8_SB(b, h) + boff + n * 2048 + k * 1024); } while (0)
; #define PG8_MMA(ai, bj, At, Bt) do { __builtin_amdgcn_s_setprio(1); _Pragma("unroll") for (int m = 0; m < 4; ++m) _Pragma("unroll") for (int n = 0; n < 2; ++n) _Pragma("unroll") for (int k = 0; k < 2; ++k) \
;         acc[ai][bj][m][n] = __builtin_amdgcn_mfma_f32_16x16x32_bf16(Bt[n][k], At[m][k], acc[ai][bj][m][n], 0, 0, 0); __builtin_amdgcn_s_setprio(0); } while (0)
; #define PG8_WAIT_V(n) asm volatile("s_waitcnt vmcnt(" #n ")" ::: "memory")
; #define PG8_WAIT_L(n) asm volatile("s_waitcnt lgkmcnt(" #n ")" ::: "memory")
; template <class Epi, class Sched, bool ALIGN_EPI = false, bool SP2 = false>
; __device__ __forceinline__ void gemm_phase(PG8_LAS unsigned char* lds, const Gemm g, const Sched& S, const Epi& E) {
;     ...
;             const bool last = (t == nt - 2);
;             const char* a1 = cA + (size_t)(t + 1) * kstep;
;             const char* a2 = last ? nA : cA + (size_t)(t + 2) * kstep; const char* b2 = last ? nB : cB + (size_t)(t + 2) * kstep;
;             const char* a3 = a2 + kstep; const char* b3 = b2 + kstep;
;             if (last && has_next) S.a_ready(nxt);
;             if constexpr (SP2) {
;             PG8_LDB(B0, 0, 0); PG8_LDB(B1, 0, 1); PG8_SCHED; PG8_LDA(At, 0, 0); PG8_STAGE(PG8_SA(1, 1), a1 + hstep, voffA);
;             PG8_WAIT_V(8); PG8_WAIT_L(0); PG8_BAR; PG8_MMA(0, 0, At, B0); PG8_MMA(0, 1, At, B1); PG8_BAR; PG8_SCHED;
;             PG8_LDA(At, 0, 1); PG8_STAGE(PG8_SB(0, 0), b2, voffB); PG8_STAGE(PG8_SB(0, 1), b2 + hstep, voffB); PG8_STAGE(PG8_SA(0, 0), a2, voffA);
;             PG8_WAIT_V(8); PG8_WAIT_L(0); PG8_BAR; PG8_MMA(1, 0, At, B0); PG8_MMA(1, 1, At, B1); PG8_BAR; PG8_SCHED;
.LBB0_1204:
	ds_read_b128 v[128:131], v213
	ds_read_b128 v[132:135], v213 offset:1024
	ds_read_b128 v[136:139], v213 offset:2048
	ds_read_b128 v[140:143], v213 offset:3072
	ds_read_b128 v[144:147], v214
	ds_read_b128 v[148:151], v214 offset:1024
	ds_read_b128 v[152:155], v214 offset:2048
	ds_read_b128 v[156:159], v214 offset:3072
	s_add_u32 s22, s20, 0xffea0080
	s_addc_u32 s23, s21, -1
	s_cmpk_eq_i32 s46, 0x54
	s_cselect_b32 s25, s5, s23
	s_cselect_b32 s24, s4, s22
	s_cselect_b32 s23, s19, s45
	s_cselect_b32 s22, s18, s44
	s_add_i32 m0, s27, 0xc000
	ds_read_b128 v[160:163], v215
	ds_read_b128 v[164:167], v215 offset:1024
	ds_read_b128 v[168:171], v215 offset:2048
	ds_read_b128 v[172:175], v215 offset:3072
	ds_read_b128 v[192:195], v215 offset:4096
	ds_read_b128 v[196:199], v215 offset:5120
	ds_read_b128 v[200:203], v215 offset:6144
	global_load_lds_dwordx4 v184, s[20:21]
	s_add_i32 m0, s27, 0xe000
	ds_read_b128 v[204:207], v215 offset:7168
	global_load_lds_dwordx4 v186, s[20:21]
	s_waitcnt vmcnt(8)
	s_waitcnt lgkmcnt(0)
	s_barrier
	s_setprio 1
	v_mfma_f32_16x16x32_bf16 v[124:127], v[128:131], v[160:163], v[124:127]
	v_mfma_f32_16x16x32_bf16 v[120:123], v[136:139], v[160:163], v[120:123]
	v_mfma_f32_16x16x32_bf16 v[108:111], v[128:131], v[168:171], v[108:111]
	v_mfma_f32_16x16x32_bf16 v[104:107], v[136:139], v[168:171], v[104:107]
	v_mfma_f32_16x16x32_bf16 v[92:95], v[128:131], v[192:195], v[92:95]
	v_mfma_f32_16x16x32_bf16 v[88:91], v[136:139], v[192:195], v[88:91]
	v_mfma_f32_16x16x32_bf16 v[76:79], v[128:131], v[200:203], v[76:79]
	v_mfma_f32_16x16x32_bf16 v[72:75], v[136:139], v[200:203], v[72:75]
	v_mfma_f32_16x16x32_bf16 v[124:127], v[132:135], v[164:167], v[124:127]
	v_mfma_f32_16x16x32_bf16 v[120:123], v[140:143], v[164:167], v[120:123]
	v_mfma_f32_16x16x32_bf16 v[108:111], v[132:135], v[172:175], v[108:111]
	v_mfma_f32_16x16x32_bf16 v[104:107], v[140:143], v[172:175], v[104:107]
	v_mfma_f32_16x16x32_bf16 v[92:95], v[132:135], v[196:199], v[92:95]
	v_mfma_f32_16x16x32_bf16 v[88:91], v[140:143], v[196:199], v[88:91]
	v_mfma_f32_16x16x32_bf16 v[76:79], v[132:135], v[204:207], v[76:79]
	v_mfma_f32_16x16x32_bf16 v[72:75], v[140:143], v[204:207], v[72:75]
	s_setprio 0
	s_setprio 1
	v_mfma_f32_16x16x32_bf16 v[116:119], v[144:147], v[160:163], v[116:119]
	v_mfma_f32_16x16x32_bf16 v[112:115], v[152:155], v[160:163], v[112:115]
	v_mfma_f32_16x16x32_bf16 v[100:103], v[144:147], v[168:171], v[100:103]
	v_mfma_f32_16x16x32_bf16 v[96:99], v[152:155], v[168:171], v[96:99]
	v_mfma_f32_16x16x32_bf16 v[84:87], v[144:147], v[192:195], v[84:87]
	v_mfma_f32_16x16x32_bf16 v[80:83], v[152:155], v[192:195], v[80:83]
	v_mfma_f32_16x16x32_bf16 v[68:71], v[144:147], v[200:203], v[68:71]
	v_mfma_f32_16x16x32_bf16 v[64:67], v[152:155], v[200:203], v[64:67]
	v_mfma_f32_16x16x32_bf16 v[116:119], v[148:151], v[164:167], v[116:119]
	v_mfma_f32_16x16x32_bf16 v[112:115], v[156:159], v[164:167], v[112:115]
	v_mfma_f32_16x16x32_bf16 v[100:103], v[148:151], v[172:175], v[100:103]
	v_mfma_f32_16x16x32_bf16 v[96:99], v[156:159], v[172:175], v[96:99]
	v_mfma_f32_16x16x32_bf16 v[84:87], v[148:151], v[196:199], v[84:87]
	v_mfma_f32_16x16x32_bf16 v[80:83], v[156:159], v[196:199], v[80:83]
	v_mfma_f32_16x16x32_bf16 v[68:71], v[148:151], v[204:207], v[68:71]
	v_mfma_f32_16x16x32_bf16 v[64:67], v[156:159], v[204:207], v[64:67]
	s_setprio 0
	s_barrier
	s_add_i32 s47, s38, s26
	s_add_u32 vcc_lo, s22, 0x80
	s_addc_u32 vcc_hi, s23, 0
	s_mov_b32 m0, s47
	ds_read_b128 v[160:163], v215 offset:16384
	ds_read_b128 v[164:167], v215 offset:17408
	ds_read_b128 v[168:171], v215 offset:18432
	ds_read_b128 v[172:175], v215 offset:19456
	global_load_lds_dwordx4 v178, s[22:23]
	s_add_i32 m0, s47, 0x2000
	s_add_u32 s48, s22, 0x160000
	s_addc_u32 s49, s23, 0
	s_add_i32 s47, s39, s26
	global_load_lds_dwordx4 v182, s[22:23]
	s_mov_b32 m0, s47
	ds_read_b128 v[204:207], v215 offset:23552
	global_load_lds_dwordx4 v178, s[48:49]
	s_add_i32 m0, s47, 0x2000
	ds_read_b128 v[200:203], v215 offset:22528
	global_load_lds_dwordx4 v182, s[48:49]
	s_add_u32 s98, s24, 0x80
	s_addc_u32 s99, s25, 0
	s_mov_b32 m0, s27
	ds_read_b128 v[196:199], v215 offset:21504
	global_load_lds_dwordx4 v176, s[24:25]
	s_mov_b32 m0, s28
	ds_read_b128 v[192:195], v215 offset:20480
	global_load_lds_dwordx4 v180, s[24:25]
	s_waitcnt vmcnt(8)
	s_waitcnt lgkmcnt(0)
	s_barrier
	s_setprio 1
	v_mfma_f32_16x16x32_bf16 v[60:63], v[128:131], v[160:163], v[60:63]
	v_mfma_f32_16x16x32_bf16 v[56:59], v[136:139], v[160:163], v[56:59]
	v_mfma_f32_16x16x32_bf16 v[44:47], v[128:131], v[168:171], v[44:47]
	v_mfma_f32_16x16x32_bf16 v[40:43], v[136:139], v[168:171], v[40:43]
	v_mfma_f32_16x16x32_bf16 v[28:31], v[128:131], v[192:195], v[28:31]
	v_mfma_f32_16x16x32_bf16 v[24:27], v[136:139], v[192:195], v[24:27]
	v_mfma_f32_16x16x32_bf16 v[12:15], v[128:131], v[200:203], v[12:15]
	v_mfma_f32_16x16x32_bf16 v[8:11], v[136:139], v[200:203], v[8:11]
	v_mfma_f32_16x16x32_bf16 v[60:63], v[132:135], v[164:167], v[60:63]
	v_mfma_f32_16x16x32_bf16 v[56:59], v[140:143], v[164:167], v[56:59]
	v_mfma_f32_16x16x32_bf16 v[44:47], v[132:135], v[172:175], v[44:47]
	v_mfma_f32_16x16x32_bf16 v[40:43], v[140:143], v[172:175], v[40:43]
	v_mfma_f32_16x16x32_bf16 v[28:31], v[132:135], v[196:199], v[28:31]
	v_mfma_f32_16x16x32_bf16 v[24:27], v[140:143], v[196:199], v[24:27]
	v_mfma_f32_16x16x32_bf16 v[12:15], v[132:135], v[204:207], v[12:15]
	v_mfma_f32_16x16x32_bf16 v[8:11], v[140:143], v[204:207], v[8:11]
	s_setprio 0
	s_setprio 1
	v_mfma_f32_16x16x32_bf16 v[52:55], v[144:147], v[160:163], v[52:55]
	v_mfma_f32_16x16x32_bf16 v[48:51], v[152:155], v[160:163], v[48:51]
	v_mfma_f32_16x16x32_bf16 v[36:39], v[144:147], v[168:171], v[36:39]
	v_mfma_f32_16x16x32_bf16 v[32:35], v[152:155], v[168:171], v[32:35]
	v_mfma_f32_16x16x32_bf16 v[20:23], v[144:147], v[192:195], v[20:23]
	v_mfma_f32_16x16x32_bf16 v[16:19], v[152:155], v[192:195], v[16:19]
	v_mfma_f32_16x16x32_bf16 v[4:7], v[144:147], v[200:203], v[4:7]
	v_mfma_f32_16x16x32_bf16 v[0:3], v[152:155], v[200:203], v[0:3]
	v_mfma_f32_16x16x32_bf16 v[52:55], v[148:151], v[164:167], v[52:55]
	v_mfma_f32_16x16x32_bf16 v[48:51], v[156:159], v[164:167], v[48:51]
	v_mfma_f32_16x16x32_bf16 v[36:39], v[148:151], v[172:175], v[36:39]
	v_mfma_f32_16x16x32_bf16 v[32:35], v[156:159], v[172:175], v[32:35]
	v_mfma_f32_16x16x32_bf16 v[20:23], v[148:151], v[196:199], v[20:23]
	v_mfma_f32_16x16x32_bf16 v[16:19], v[156:159], v[196:199], v[16:19]
	v_mfma_f32_16x16x32_bf16 v[4:7], v[148:151], v[204:207], v[4:7]
	v_mfma_f32_16x16x32_bf16 v[0:3], v[156:159], v[204:207], v[0:3]
	s_setprio 0
	s_barrier
; #define PG8_STAGE(bufoff, gbase, voff) do { _Pragma("unroll") for (int _i = 0; _i < 2; ++_i) \
;         __builtin_amdgcn_global_load_lds((const unsigned*)((const char*)(gbase) + (voff)[_i]), (PG8_LAS unsigned*)(lds + (bufoff) + ldsw + _i * 8192), 16, 0, 0); } while (0)
; #define PG8_LDA(dst, b, h) do { _Pragma("unroll") for (int m = 0; m < 4; ++m) _Pragma("unroll") for (int k = 0; k < 2; ++k) dst[m][k] = *(const PG8_LAS bf16x8*)(lds + PG8_SA(b, h) + aoff + m * 2048 + k * 1024); } while (0)
; #define PG8_LDB(dst, b, h) do { _Pragma("unroll") for (int n = 0; n < 2; ++n) _Pragma("unroll") for (int k = 0; k < 2; ++k) dst[n][k] = *(const PG8_LAS bf16x8*)(lds + PG8_SB(b, h) + boff + n * 2048 + k * 1024); } while (0)
; #define PG8_MMA(ai, bj, At, Bt) do { __builtin_amdgcn_s_setprio(1); _Pragma("unroll") for (int m = 0; m < 4; ++m) _Pragma("unroll") for (int n = 0; n < 2; ++n) _Pragma("unroll") for (int k = 0; k < 2; ++k) \
;         acc[ai][bj][m][n] = __builtin_amdgcn_mfma_f32_16x16x32_bf16(Bt[n][k], At[m][k], acc[ai][bj][m][n], 0, 0, 0); __builtin_amdgcn_s_setprio(0); } while (0)
; #define PG8_WAIT_V(n) asm volatile("s_waitcnt vmcnt(" #n ")" ::: "memory")
; #define PG8_WAIT_L(n) asm volatile("s_waitcnt lgkmcnt(" #n ")" ::: "memory")
; #define PG8_BAR __builtin_amdgcn_s_barrier()
; #define PG8_SCHED __builtin_amdgcn_sched_barrier(0)
; template <class Epi, class Sched, bool ALIGN_EPI = false, bool SP2 = false>
; __device__ __forceinline__ void gemm_phase(PG8_LAS unsigned char* lds, const Gemm g, const Sched& S, const Epi& E) {
;     ...
;             PG8_LDB(B0, 1, 0); PG8_LDB(B1, 1, 1); PG8_SCHED; PG8_LDA(At, 1, 0); PG8_STAGE(PG8_SA(0, 1), a2 + hstep, voffA);
;             PG8_WAIT_V(8); PG8_WAIT_L(0); PG8_BAR; PG8_MMA(0, 0, At, B0); PG8_MMA(0, 1, At, B1); PG8_BAR; PG8_SCHED;
;             PG8_LDA(At, 1, 1); PG8_STAGE(PG8_SB(1, 0), b3, voffB); PG8_STAGE(PG8_SB(1, 1), b3 + hstep, voffB); PG8_STAGE(PG8_SA(1, 0), a3, voffA);
;             PG8_WAIT_V(8); PG8_WAIT_L(0); PG8_BAR; PG8_MMA(1, 0, At, B0); PG8_MMA(1, 1, At, B1); PG8_BAR; PG8_SCHED;
;     ...
;         if constexpr (ALIGN_EPI) { if (wr == 0) PG8_BAR; }
	s_add_i32 s47, 0, 0x18000
	s_add_i32 s48, 0, 0x1c000
	v_add_u32_e32 v140, s47, v211
	v_add_u32_e32 v156, s48, v211
	ds_read_b128 v[128:131], v140
	ds_read_b128 v[132:135], v140 offset:1024
	ds_read_b128 v[136:139], v140 offset:2048
	ds_read_b128 v[140:143], v140 offset:3072
	ds_read_b128 v[144:147], v156
	ds_read_b128 v[148:151], v156 offset:1024
	ds_read_b128 v[152:155], v156 offset:2048
	ds_read_b128 v[156:159], v156 offset:3072
	s_add_u32 s24, s24, 0x160000
	s_addc_u32 s25, s25, 0
	s_mov_b32 m0, s29
	ds_read_b128 v[160:163], v215 offset:32768
	ds_read_b128 v[164:167], v215 offset:33792
	ds_read_b128 v[168:171], v215 offset:34816
	ds_read_b128 v[172:175], v215 offset:35840
	ds_read_b128 v[192:195], v215 offset:36864
	ds_read_b128 v[196:199], v215 offset:37888
	ds_read_b128 v[200:203], v215 offset:38912
	global_load_lds_dwordx4 v176, s[24:25]
	s_mov_b32 m0, s30
	ds_read_b128 v[204:207], v215 offset:39936
	global_load_lds_dwordx4 v180, s[24:25]
	s_waitcnt vmcnt(8)
	s_waitcnt lgkmcnt(0)
	s_barrier
	s_setprio 1
	v_mfma_f32_16x16x32_bf16 v[124:127], v[128:131], v[160:163], v[124:127]
	v_mfma_f32_16x16x32_bf16 v[120:123], v[136:139], v[160:163], v[120:123]
	v_mfma_f32_16x16x32_bf16 v[108:111], v[128:131], v[168:171], v[108:111]
	v_mfma_f32_16x16x32_bf16 v[104:107], v[136:139], v[168:171], v[104:107]
	v_mfma_f32_16x16x32_bf16 v[92:95], v[128:131], v[192:195], v[92:95]
	v_mfma_f32_16x16x32_bf16 v[88:91], v[136:139], v[192:195], v[88:91]
	v_mfma_f32_16x16x32_bf16 v[76:79], v[128:131], v[200:203], v[76:79]
	v_mfma_f32_16x16x32_bf16 v[72:75], v[136:139], v[200:203], v[72:75]
	v_mfma_f32_16x16x32_bf16 v[124:127], v[132:135], v[164:167], v[124:127]
	v_mfma_f32_16x16x32_bf16 v[120:123], v[140:143], v[164:167], v[120:123]
	v_mfma_f32_16x16x32_bf16 v[108:111], v[132:135], v[172:175], v[108:111]
	v_mfma_f32_16x16x32_bf16 v[104:107], v[140:143], v[172:175], v[104:107]
	v_mfma_f32_16x16x32_bf16 v[92:95], v[132:135], v[196:199], v[92:95]
	v_mfma_f32_16x16x32_bf16 v[88:91], v[140:143], v[196:199], v[88:91]
	v_mfma_f32_16x16x32_bf16 v[76:79], v[132:135], v[204:207], v[76:79]
	v_mfma_f32_16x16x32_bf16 v[72:75], v[140:143], v[204:207], v[72:75]
	s_setprio 0
	s_setprio 1
	v_mfma_f32_16x16x32_bf16 v[116:119], v[144:147], v[160:163], v[116:119]
	v_mfma_f32_16x16x32_bf16 v[112:115], v[152:155], v[160:163], v[112:115]
	v_mfma_f32_16x16x32_bf16 v[100:103], v[144:147], v[168:171], v[100:103]
	v_mfma_f32_16x16x32_bf16 v[96:99], v[152:155], v[168:171], v[96:99]
	v_mfma_f32_16x16x32_bf16 v[84:87], v[144:147], v[192:195], v[84:87]
	v_mfma_f32_16x16x32_bf16 v[80:83], v[152:155], v[192:195], v[80:83]
	v_mfma_f32_16x16x32_bf16 v[68:71], v[144:147], v[200:203], v[68:71]
	v_mfma_f32_16x16x32_bf16 v[64:67], v[152:155], v[200:203], v[64:67]
	v_mfma_f32_16x16x32_bf16 v[116:119], v[148:151], v[164:167], v[116:119]
	v_mfma_f32_16x16x32_bf16 v[112:115], v[156:159], v[164:167], v[112:115]
	v_mfma_f32_16x16x32_bf16 v[100:103], v[148:151], v[172:175], v[100:103]
	v_mfma_f32_16x16x32_bf16 v[96:99], v[156:159], v[172:175], v[96:99]
	v_mfma_f32_16x16x32_bf16 v[84:87], v[148:151], v[196:199], v[84:87]
	v_mfma_f32_16x16x32_bf16 v[80:83], v[156:159], v[196:199], v[80:83]
	v_mfma_f32_16x16x32_bf16 v[68:71], v[148:151], v[204:207], v[68:71]
	v_mfma_f32_16x16x32_bf16 v[64:67], v[156:159], v[204:207], v[64:67]
	s_setprio 0
	s_barrier
	s_add_i32 s24, s47, s26
	s_mov_b32 m0, s24
	ds_read_b128 v[160:163], v215 offset:49152
	ds_read_b128 v[164:167], v215 offset:50176
	ds_read_b128 v[168:171], v215 offset:51200
	ds_read_b128 v[172:175], v215 offset:52224
	global_load_lds_dwordx4 v178, vcc
	s_add_i32 m0, s24, 0x2000
	s_add_u32 s22, s22, 0x160080
	s_addc_u32 s23, s23, 0
	s_add_i32 s24, s48, s26
	global_load_lds_dwordx4 v182, vcc
	s_mov_b32 m0, s24
	ds_read_b128 v[204:207], v215 offset:56320
	global_load_lds_dwordx4 v178, s[22:23]
	s_add_i32 m0, s24, 0x2000
	ds_read_b128 v[200:203], v215 offset:55296
	global_load_lds_dwordx4 v182, s[22:23]
	s_mov_b32 m0, s33
	ds_read_b128 v[196:199], v215 offset:54272
	global_load_lds_dwordx4 v176, s[98:99]
	s_mov_b32 m0, s34
	ds_read_b128 v[192:195], v215 offset:53248
	global_load_lds_dwordx4 v180, s[98:99]
	s_waitcnt vmcnt(8)
	s_waitcnt lgkmcnt(0)
	s_barrier
	s_setprio 1
	v_mfma_f32_16x16x32_bf16 v[60:63], v[128:131], v[160:163], v[60:63]
	v_mfma_f32_16x16x32_bf16 v[56:59], v[136:139], v[160:163], v[56:59]
	v_mfma_f32_16x16x32_bf16 v[44:47], v[128:131], v[168:171], v[44:47]
	v_mfma_f32_16x16x32_bf16 v[40:43], v[136:139], v[168:171], v[40:43]
	v_mfma_f32_16x16x32_bf16 v[28:31], v[128:131], v[192:195], v[28:31]
	v_mfma_f32_16x16x32_bf16 v[24:27], v[136:139], v[192:195], v[24:27]
	v_mfma_f32_16x16x32_bf16 v[12:15], v[128:131], v[200:203], v[12:15]
	v_mfma_f32_16x16x32_bf16 v[8:11], v[136:139], v[200:203], v[8:11]
	v_mfma_f32_16x16x32_bf16 v[60:63], v[132:135], v[164:167], v[60:63]
	v_mfma_f32_16x16x32_bf16 v[56:59], v[140:143], v[164:167], v[56:59]
	v_mfma_f32_16x16x32_bf16 v[44:47], v[132:135], v[172:175], v[44:47]
	v_mfma_f32_16x16x32_bf16 v[40:43], v[140:143], v[172:175], v[40:43]
	v_mfma_f32_16x16x32_bf16 v[28:31], v[132:135], v[196:199], v[28:31]
	v_mfma_f32_16x16x32_bf16 v[24:27], v[140:143], v[196:199], v[24:27]
	v_mfma_f32_16x16x32_bf16 v[12:15], v[132:135], v[204:207], v[12:15]
	v_mfma_f32_16x16x32_bf16 v[8:11], v[140:143], v[204:207], v[8:11]
	s_setprio 0
	s_setprio 1
	v_mfma_f32_16x16x32_bf16 v[52:55], v[144:147], v[160:163], v[52:55]
	v_mfma_f32_16x16x32_bf16 v[48:51], v[152:155], v[160:163], v[48:51]
	v_mfma_f32_16x16x32_bf16 v[36:39], v[144:147], v[168:171], v[36:39]
	v_mfma_f32_16x16x32_bf16 v[32:35], v[152:155], v[168:171], v[32:35]
	v_mfma_f32_16x16x32_bf16 v[20:23], v[144:147], v[192:195], v[20:23]
	v_mfma_f32_16x16x32_bf16 v[16:19], v[152:155], v[192:195], v[16:19]
	v_mfma_f32_16x16x32_bf16 v[4:7], v[144:147], v[200:203], v[4:7]
	v_mfma_f32_16x16x32_bf16 v[0:3], v[152:155], v[200:203], v[0:3]
	v_mfma_f32_16x16x32_bf16 v[52:55], v[148:151], v[164:167], v[52:55]
	v_mfma_f32_16x16x32_bf16 v[48:51], v[156:159], v[164:167], v[48:51]
	v_mfma_f32_16x16x32_bf16 v[36:39], v[148:151], v[172:175], v[36:39]
	v_mfma_f32_16x16x32_bf16 v[32:35], v[156:159], v[172:175], v[32:35]
	v_mfma_f32_16x16x32_bf16 v[20:23], v[148:151], v[196:199], v[20:23]
	v_mfma_f32_16x16x32_bf16 v[16:19], v[156:159], v[196:199], v[16:19]
	v_mfma_f32_16x16x32_bf16 v[4:7], v[148:151], v[204:207], v[4:7]
	v_mfma_f32_16x16x32_bf16 v[0:3], v[156:159], v[204:207], v[0:3]
	s_setprio 0
	s_barrier
	s_add_i32 s46, s46, 2
	s_add_u32 s20, s20, 0x100
	s_addc_u32 s21, s21, 0
	s_add_u32 s44, s44, 0x100
	s_addc_u32 s45, s45, 0
	s_cmpk_gt_u32 s46, 0x55
	s_cbranch_scc0 .LBB0_1204
	s_and_b64 vcc, exec, s[16:17]
	s_cbranch_vccz .LBB0_1207
	s_barrier

; #define PG8_STAGE(bufoff, gbase, voff) do { _Pragma("unroll") for (int _i = 0; _i < 2; ++_i) \
;         __builtin_amdgcn_global_load_lds((const unsigned*)((const char*)(gbase) + (voff)[_i]), (PG8_LAS unsigned*)(lds + (bufoff) + ldsw + _i * 8192), 16, 0, 0); } while (0)
; #define PG8_LDA(dst, b, h) do { _Pragma("unroll") for (int m = 0; m < 4; ++m) _Pragma("unroll") for (int k = 0; k < 2; ++k) dst[m][k] = *(const PG8_LAS bf16x8*)(lds + PG8_SA(b, h) + aoff + m * 2048 + k * 1024); } while (0)
; #define PG8_LDB(dst, b, h) do { _Pragma("unroll") for (int n = 0; n < 2; ++n) _Pragma("unroll") for (int k = 0; k < 2; ++k) dst[n][k] = *(const PG8_LAS bf16x8*)(lds + PG8_SB(b, h) + boff + n * 2048 + k * 1024); } while (0)
; #define PG8_MMA(ai, bj, At, Bt) do { __builtin_amdgcn_s_setprio(1); _Pragma("unroll") for (int m = 0; m < 4; ++m) _Pragma("unroll") for (int n = 0; n < 2; ++n) _Pragma("unroll") for (int k = 0; k < 2; ++k) \
;         acc[ai][bj][m][n] = __builtin_amdgcn_mfma_f32_16x16x32_bf16(Bt[n][k], At[m][k], acc[ai][bj][m][n], 0, 0, 0); __builtin_amdgcn_s_setprio(0); } while (0)
; #define PG8_WAIT_V(n) asm volatile("s_waitcnt vmcnt(" #n ")" ::: "memory")
; #define PG8_WAIT_L(n) asm volatile("s_waitcnt lgkmcnt(" #n ")" ::: "memory")
; template <class Epi, class Sched, bool ALIGN_EPI = false, bool SP2 = false>
; __device__ __forceinline__ void gemm_phase(PG8_LAS unsigned char* lds, const Gemm g, const Sched& S, const Epi& E) {
;     ...
;             const bool last = (t == nt - 2);
;             const char* a1 = cA + (size_t)(t + 1) * kstep;
;             const char* a2 = last ? nA : cA + (size_t)(t + 2) * kstep; const char* b2 = last ? nB : cB + (size_t)(t + 2) * kstep;
;             const char* a3 = a2 + kstep; const char* b3 = b2 + kstep;
;             if (last && has_next) S.a_ready(nxt);
;             if constexpr (SP2) {
;             PG8_LDB(B0, 0, 0); PG8_LDB(B1, 0, 1); PG8_SCHED; PG8_LDA(At, 0, 0); PG8_STAGE(PG8_SA(1, 1), a1 + hstep, voffA);
;             PG8_WAIT_V(8); PG8_WAIT_L(0); PG8_BAR; PG8_MMA(0, 0, At, B0); PG8_MMA(0, 1, At, B1); PG8_BAR; PG8_SCHED;
;             PG8_LDA(At, 0, 1); PG8_STAGE(PG8_SB(0, 0), b2, voffB); PG8_STAGE(PG8_SB(0, 1), b2 + hstep, voffB); PG8_STAGE(PG8_SA(0, 0), a2, voffA);
;             PG8_WAIT_V(8); PG8_WAIT_L(0); PG8_BAR; PG8_MMA(1, 0, At, B0); PG8_MMA(1, 1, At, B1); PG8_BAR; PG8_SCHED;
.LBB0_1295:
	ds_read_b128 v[56:59], v203
	ds_read_b128 v[64:67], v203 offset:1024
	ds_read_b128 v[72:75], v203 offset:2048
	ds_read_b128 v[76:79], v203 offset:3072
	ds_read_b128 v[144:147], v204
	ds_read_b128 v[148:151], v204 offset:1024
	ds_read_b128 v[152:155], v204 offset:2048
	ds_read_b128 v[156:159], v204 offset:3072
	s_add_u32 s36, s34, 0xfff80080
	s_addc_u32 s37, s35, -1
	s_cmp_eq_u32 s56, 28
	s_cselect_b32 s39, s27, s37
	s_cselect_b32 s38, s52, s36
	s_cselect_b32 s37, s25, s55
	s_cselect_b32 s36, s53, s54
	s_add_i32 m0, s41, 0xc000
	ds_read_b128 v[160:163], v205
	ds_read_b128 v[164:167], v205 offset:1024
	ds_read_b128 v[168:171], v205 offset:2048
	ds_read_b128 v[188:191], v205 offset:3072
	ds_read_b128 v[192:195], v205 offset:4096
	ds_read_b128 v[196:199], v205 offset:5120
	ds_read_b128 v[208:211], v205 offset:6144
	global_load_lds_dwordx4 v180, s[34:35]
	s_add_i32 m0, s41, 0xe000
	ds_read_b128 v[212:215], v205 offset:7168
	global_load_lds_dwordx4 v182, s[34:35]
	s_waitcnt vmcnt(8)
	s_waitcnt lgkmcnt(0)
	s_barrier
	s_setprio 1
	v_mfma_f32_16x16x32_bf16 v[140:143], v[56:59], v[160:163], v[140:143]
	v_mfma_f32_16x16x32_bf16 v[136:139], v[72:75], v[160:163], v[136:139]
	v_mfma_f32_16x16x32_bf16 v[124:127], v[56:59], v[168:171], v[124:127]
	v_mfma_f32_16x16x32_bf16 v[120:123], v[72:75], v[168:171], v[120:123]
	v_mfma_f32_16x16x32_bf16 v[108:111], v[56:59], v[192:195], v[108:111]
	v_mfma_f32_16x16x32_bf16 v[104:107], v[72:75], v[192:195], v[104:107]
	v_mfma_f32_16x16x32_bf16 v[92:95], v[56:59], v[208:211], v[92:95]
	v_mfma_f32_16x16x32_bf16 v[88:91], v[72:75], v[208:211], v[88:91]
	v_mfma_f32_16x16x32_bf16 v[140:143], v[64:67], v[164:167], v[140:143]
	v_mfma_f32_16x16x32_bf16 v[136:139], v[76:79], v[164:167], v[136:139]
	v_mfma_f32_16x16x32_bf16 v[124:127], v[64:67], v[188:191], v[124:127]
	v_mfma_f32_16x16x32_bf16 v[120:123], v[76:79], v[188:191], v[120:123]
	v_mfma_f32_16x16x32_bf16 v[108:111], v[64:67], v[196:199], v[108:111]
	v_mfma_f32_16x16x32_bf16 v[104:107], v[76:79], v[196:199], v[104:107]
	v_mfma_f32_16x16x32_bf16 v[92:95], v[64:67], v[212:215], v[92:95]
	v_mfma_f32_16x16x32_bf16 v[88:91], v[76:79], v[212:215], v[88:91]
	s_setprio 0
	s_setprio 1
	v_mfma_f32_16x16x32_bf16 v[132:135], v[144:147], v[160:163], v[132:135]
	v_mfma_f32_16x16x32_bf16 v[128:131], v[152:155], v[160:163], v[128:131]
	v_mfma_f32_16x16x32_bf16 v[116:119], v[144:147], v[168:171], v[116:119]
	v_mfma_f32_16x16x32_bf16 v[112:115], v[152:155], v[168:171], v[112:115]
	v_mfma_f32_16x16x32_bf16 v[100:103], v[144:147], v[192:195], v[100:103]
	v_mfma_f32_16x16x32_bf16 v[96:99], v[152:155], v[192:195], v[96:99]
	v_mfma_f32_16x16x32_bf16 v[84:87], v[144:147], v[208:211], v[84:87]
	v_mfma_f32_16x16x32_bf16 v[80:83], v[152:155], v[208:211], v[80:83]
	v_mfma_f32_16x16x32_bf16 v[132:135], v[148:151], v[164:167], v[132:135]
	v_mfma_f32_16x16x32_bf16 v[128:131], v[156:159], v[164:167], v[128:131]
	v_mfma_f32_16x16x32_bf16 v[116:119], v[148:151], v[188:191], v[116:119]
	v_mfma_f32_16x16x32_bf16 v[112:115], v[156:159], v[188:191], v[112:115]
	v_mfma_f32_16x16x32_bf16 v[100:103], v[148:151], v[196:199], v[100:103]
	v_mfma_f32_16x16x32_bf16 v[96:99], v[156:159], v[196:199], v[96:99]
	v_mfma_f32_16x16x32_bf16 v[84:87], v[148:151], v[212:215], v[84:87]
	v_mfma_f32_16x16x32_bf16 v[80:83], v[156:159], v[212:215], v[80:83]
	s_setprio 0
	s_barrier
	s_add_i32 s57, s49, s40
	s_add_u32 vcc_lo, s36, 0x80
	s_addc_u32 vcc_hi, s37, 0
	s_mov_b32 m0, s57
	ds_read_b128 v[160:163], v205 offset:16384
	ds_read_b128 v[164:167], v205 offset:17408
	ds_read_b128 v[168:171], v205 offset:18432
	ds_read_b128 v[188:191], v205 offset:19456
	global_load_lds_dwordx4 v174, s[36:37]
	s_add_i32 m0, s57, 0x2000
	s_add_u32 s58, s36, 0x80000
	s_addc_u32 s59, s37, 0
	s_add_i32 s57, s50, s40
	global_load_lds_dwordx4 v178, s[36:37]
	s_mov_b32 m0, s57
	ds_read_b128 v[212:215], v205 offset:23552
	global_load_lds_dwordx4 v174, s[58:59]
	s_add_i32 m0, s57, 0x2000
	ds_read_b128 v[208:211], v205 offset:22528
	global_load_lds_dwordx4 v178, s[58:59]
	s_add_u32 s98, s38, 0x80
	s_addc_u32 s99, s39, 0
	s_mov_b32 m0, s41
	ds_read_b128 v[196:199], v205 offset:21504
	global_load_lds_dwordx4 v172, s[38:39]
	s_mov_b32 m0, s42
	ds_read_b128 v[192:195], v205 offset:20480
	global_load_lds_dwordx4 v176, s[38:39]
	s_waitcnt vmcnt(8)
	s_waitcnt lgkmcnt(0)
	s_barrier
	s_setprio 1
	v_mfma_f32_16x16x32_bf16 v[68:71], v[56:59], v[160:163], v[68:71]
	v_mfma_f32_16x16x32_bf16 v[60:63], v[72:75], v[160:163], v[60:63]
	v_mfma_f32_16x16x32_bf16 v[44:47], v[56:59], v[168:171], v[44:47]
	v_mfma_f32_16x16x32_bf16 v[40:43], v[72:75], v[168:171], v[40:43]
	v_mfma_f32_16x16x32_bf16 v[28:31], v[56:59], v[192:195], v[28:31]
	v_mfma_f32_16x16x32_bf16 v[24:27], v[72:75], v[192:195], v[24:27]
	v_mfma_f32_16x16x32_bf16 v[12:15], v[56:59], v[208:211], v[12:15]
	v_mfma_f32_16x16x32_bf16 v[8:11], v[72:75], v[208:211], v[8:11]
	v_mfma_f32_16x16x32_bf16 v[68:71], v[64:67], v[164:167], v[68:71]
	v_mfma_f32_16x16x32_bf16 v[60:63], v[76:79], v[164:167], v[60:63]
	v_mfma_f32_16x16x32_bf16 v[44:47], v[64:67], v[188:191], v[44:47]
	v_mfma_f32_16x16x32_bf16 v[40:43], v[76:79], v[188:191], v[40:43]
	v_mfma_f32_16x16x32_bf16 v[28:31], v[64:67], v[196:199], v[28:31]
	v_mfma_f32_16x16x32_bf16 v[24:27], v[76:79], v[196:199], v[24:27]
	v_mfma_f32_16x16x32_bf16 v[12:15], v[64:67], v[212:215], v[12:15]
	v_mfma_f32_16x16x32_bf16 v[8:11], v[76:79], v[212:215], v[8:11]
	s_setprio 0
	s_setprio 1
	v_mfma_f32_16x16x32_bf16 v[52:55], v[144:147], v[160:163], v[52:55]
	v_mfma_f32_16x16x32_bf16 v[48:51], v[152:155], v[160:163], v[48:51]
	v_mfma_f32_16x16x32_bf16 v[36:39], v[144:147], v[168:171], v[36:39]
	v_mfma_f32_16x16x32_bf16 v[32:35], v[152:155], v[168:171], v[32:35]
	v_mfma_f32_16x16x32_bf16 v[20:23], v[144:147], v[192:195], v[20:23]
	v_mfma_f32_16x16x32_bf16 v[16:19], v[152:155], v[192:195], v[16:19]
	v_mfma_f32_16x16x32_bf16 v[4:7], v[144:147], v[208:211], v[4:7]
	v_mfma_f32_16x16x32_bf16 v[0:3], v[152:155], v[208:211], v[0:3]
	v_mfma_f32_16x16x32_bf16 v[52:55], v[148:151], v[164:167], v[52:55]
	v_mfma_f32_16x16x32_bf16 v[48:51], v[156:159], v[164:167], v[48:51]
	v_mfma_f32_16x16x32_bf16 v[36:39], v[148:151], v[188:191], v[36:39]
	v_mfma_f32_16x16x32_bf16 v[32:35], v[156:159], v[188:191], v[32:35]
	v_mfma_f32_16x16x32_bf16 v[20:23], v[148:151], v[196:199], v[20:23]
	v_mfma_f32_16x16x32_bf16 v[16:19], v[156:159], v[196:199], v[16:19]
	v_mfma_f32_16x16x32_bf16 v[4:7], v[148:151], v[212:215], v[4:7]
	v_mfma_f32_16x16x32_bf16 v[0:3], v[156:159], v[212:215], v[0:3]
	s_setprio 0
	s_barrier
; #define PG8_STAGE(bufoff, gbase, voff) do { _Pragma("unroll") for (int _i = 0; _i < 2; ++_i) \
;         __builtin_amdgcn_global_load_lds((const unsigned*)((const char*)(gbase) + (voff)[_i]), (PG8_LAS unsigned*)(lds + (bufoff) + ldsw + _i * 8192), 16, 0, 0); } while (0)
; #define PG8_LDA(dst, b, h) do { _Pragma("unroll") for (int m = 0; m < 4; ++m) _Pragma("unroll") for (int k = 0; k < 2; ++k) dst[m][k] = *(const PG8_LAS bf16x8*)(lds + PG8_SA(b, h) + aoff + m * 2048 + k * 1024); } while (0)
; #define PG8_LDB(dst, b, h) do { _Pragma("unroll") for (int n = 0; n < 2; ++n) _Pragma("unroll") for (int k = 0; k < 2; ++k) dst[n][k] = *(const PG8_LAS bf16x8*)(lds + PG8_SB(b, h) + boff + n * 2048 + k * 1024); } while (0)
; #define PG8_MMA(ai, bj, At, Bt) do { __builtin_amdgcn_s_setprio(1); _Pragma("unroll") for (int m = 0; m < 4; ++m) _Pragma("unroll") for (int n = 0; n < 2; ++n) _Pragma("unroll") for (int k = 0; k < 2; ++k) \
;         acc[ai][bj][m][n] = __builtin_amdgcn_mfma_f32_16x16x32_bf16(Bt[n][k], At[m][k], acc[ai][bj][m][n], 0, 0, 0); __builtin_amdgcn_s_setprio(0); } while (0)
; #define PG8_WAIT_V(n) asm volatile("s_waitcnt vmcnt(" #n ")" ::: "memory")
; #define PG8_WAIT_L(n) asm volatile("s_waitcnt lgkmcnt(" #n ")" ::: "memory")
; #define PG8_BAR __builtin_amdgcn_s_barrier()
; #define PG8_SCHED __builtin_amdgcn_sched_barrier(0)
; template <class Epi, class Sched, bool ALIGN_EPI = false, bool SP2 = false>
; __device__ __forceinline__ void gemm_phase(PG8_LAS unsigned char* lds, const Gemm g, const Sched& S, const Epi& E) {
;     ...
;             PG8_LDB(B0, 1, 0); PG8_LDB(B1, 1, 1); PG8_SCHED; PG8_LDA(At, 1, 0); PG8_STAGE(PG8_SA(0, 1), a2 + hstep, voffA);
;             PG8_WAIT_V(8); PG8_WAIT_L(0); PG8_BAR; PG8_MMA(0, 0, At, B0); PG8_MMA(0, 1, At, B1); PG8_BAR; PG8_SCHED;
;             PG8_LDA(At, 1, 1); PG8_STAGE(PG8_SB(1, 0), b3, voffB); PG8_STAGE(PG8_SB(1, 1), b3 + hstep, voffB); PG8_STAGE(PG8_SA(1, 0), a3, voffA);
;             PG8_WAIT_V(8); PG8_WAIT_L(0); PG8_BAR; PG8_MMA(1, 0, At, B0); PG8_MMA(1, 1, At, B1); PG8_BAR; PG8_SCHED;
;     ...
;         if constexpr (ALIGN_EPI) { if (wr == 0) PG8_BAR; }
	s_add_i32 s57, 0, 0x18000
	s_add_i32 s58, 0, 0x1c000
	v_add_u32_e32 v76, s57, v201
	v_add_u32_e32 v156, s58, v201
	ds_read_b128 v[56:59], v76
	ds_read_b128 v[64:67], v76 offset:1024
	ds_read_b128 v[72:75], v76 offset:2048
	ds_read_b128 v[76:79], v76 offset:3072
	ds_read_b128 v[144:147], v156
	ds_read_b128 v[148:151], v156 offset:1024
	ds_read_b128 v[152:155], v156 offset:2048
	ds_read_b128 v[156:159], v156 offset:3072
	s_add_u32 s38, s38, 0x80000
	s_addc_u32 s39, s39, 0
	s_mov_b32 m0, s43
	ds_read_b128 v[160:163], v205 offset:32768
	ds_read_b128 v[164:167], v205 offset:33792
	ds_read_b128 v[168:171], v205 offset:34816
	ds_read_b128 v[188:191], v205 offset:35840
	ds_read_b128 v[192:195], v205 offset:36864
	ds_read_b128 v[196:199], v205 offset:37888
	ds_read_b128 v[208:211], v205 offset:38912
	global_load_lds_dwordx4 v172, s[38:39]
	s_mov_b32 m0, s44
	ds_read_b128 v[212:215], v205 offset:39936
	global_load_lds_dwordx4 v176, s[38:39]
	s_waitcnt vmcnt(8)
	s_waitcnt lgkmcnt(0)
	s_barrier
	s_setprio 1
	v_mfma_f32_16x16x32_bf16 v[140:143], v[56:59], v[160:163], v[140:143]
	v_mfma_f32_16x16x32_bf16 v[136:139], v[72:75], v[160:163], v[136:139]
	v_mfma_f32_16x16x32_bf16 v[124:127], v[56:59], v[168:171], v[124:127]
	v_mfma_f32_16x16x32_bf16 v[120:123], v[72:75], v[168:171], v[120:123]
	v_mfma_f32_16x16x32_bf16 v[108:111], v[56:59], v[192:195], v[108:111]
	v_mfma_f32_16x16x32_bf16 v[104:107], v[72:75], v[192:195], v[104:107]
	v_mfma_f32_16x16x32_bf16 v[92:95], v[56:59], v[208:211], v[92:95]
	v_mfma_f32_16x16x32_bf16 v[88:91], v[72:75], v[208:211], v[88:91]
	v_mfma_f32_16x16x32_bf16 v[140:143], v[64:67], v[164:167], v[140:143]
	v_mfma_f32_16x16x32_bf16 v[136:139], v[76:79], v[164:167], v[136:139]
	v_mfma_f32_16x16x32_bf16 v[124:127], v[64:67], v[188:191], v[124:127]
	v_mfma_f32_16x16x32_bf16 v[120:123], v[76:79], v[188:191], v[120:123]
	v_mfma_f32_16x16x32_bf16 v[108:111], v[64:67], v[196:199], v[108:111]
	v_mfma_f32_16x16x32_bf16 v[104:107], v[76:79], v[196:199], v[104:107]
	v_mfma_f32_16x16x32_bf16 v[92:95], v[64:67], v[212:215], v[92:95]
	v_mfma_f32_16x16x32_bf16 v[88:91], v[76:79], v[212:215], v[88:91]
	s_setprio 0
	s_setprio 1
	v_mfma_f32_16x16x32_bf16 v[132:135], v[144:147], v[160:163], v[132:135]
	v_mfma_f32_16x16x32_bf16 v[128:131], v[152:155], v[160:163], v[128:131]
	v_mfma_f32_16x16x32_bf16 v[116:119], v[144:147], v[168:171], v[116:119]
	v_mfma_f32_16x16x32_bf16 v[112:115], v[152:155], v[168:171], v[112:115]
	v_mfma_f32_16x16x32_bf16 v[100:103], v[144:147], v[192:195], v[100:103]
	v_mfma_f32_16x16x32_bf16 v[96:99], v[152:155], v[192:195], v[96:99]
	v_mfma_f32_16x16x32_bf16 v[84:87], v[144:147], v[208:211], v[84:87]
	v_mfma_f32_16x16x32_bf16 v[80:83], v[152:155], v[208:211], v[80:83]
	v_mfma_f32_16x16x32_bf16 v[132:135], v[148:151], v[164:167], v[132:135]
	v_mfma_f32_16x16x32_bf16 v[128:131], v[156:159], v[164:167], v[128:131]
	v_mfma_f32_16x16x32_bf16 v[116:119], v[148:151], v[188:191], v[116:119]
	v_mfma_f32_16x16x32_bf16 v[112:115], v[156:159], v[188:191], v[112:115]
	v_mfma_f32_16x16x32_bf16 v[100:103], v[148:151], v[196:199], v[100:103]
	v_mfma_f32_16x16x32_bf16 v[96:99], v[156:159], v[196:199], v[96:99]
	v_mfma_f32_16x16x32_bf16 v[84:87], v[148:151], v[212:215], v[84:87]
	v_mfma_f32_16x16x32_bf16 v[80:83], v[156:159], v[212:215], v[80:83]
	s_setprio 0
	s_barrier
	s_add_i32 s38, s57, s40
	s_mov_b32 m0, s38
	ds_read_b128 v[160:163], v205 offset:49152
	ds_read_b128 v[164:167], v205 offset:50176
	ds_read_b128 v[168:171], v205 offset:51200
	ds_read_b128 v[188:191], v205 offset:52224
	global_load_lds_dwordx4 v174, vcc
	s_add_i32 m0, s38, 0x2000
	s_add_u32 s36, s36, 0x80080
	s_addc_u32 s37, s37, 0
	s_add_i32 s38, s58, s40
	global_load_lds_dwordx4 v178, vcc
	s_mov_b32 m0, s38
	ds_read_b128 v[212:215], v205 offset:56320
	global_load_lds_dwordx4 v174, s[36:37]
	s_add_i32 m0, s38, 0x2000
	ds_read_b128 v[208:211], v205 offset:55296
	global_load_lds_dwordx4 v178, s[36:37]
	s_mov_b32 m0, s46
	ds_read_b128 v[196:199], v205 offset:54272
	global_load_lds_dwordx4 v172, s[98:99]
	s_mov_b32 m0, s47
	ds_read_b128 v[192:195], v205 offset:53248
	global_load_lds_dwordx4 v176, s[98:99]
	s_waitcnt vmcnt(8)
	s_waitcnt lgkmcnt(0)
	s_barrier
	s_setprio 1
	v_mfma_f32_16x16x32_bf16 v[68:71], v[56:59], v[160:163], v[68:71]
	v_mfma_f32_16x16x32_bf16 v[60:63], v[72:75], v[160:163], v[60:63]
	v_mfma_f32_16x16x32_bf16 v[44:47], v[56:59], v[168:171], v[44:47]
	v_mfma_f32_16x16x32_bf16 v[40:43], v[72:75], v[168:171], v[40:43]
	v_mfma_f32_16x16x32_bf16 v[28:31], v[56:59], v[192:195], v[28:31]
	v_mfma_f32_16x16x32_bf16 v[24:27], v[72:75], v[192:195], v[24:27]
	v_mfma_f32_16x16x32_bf16 v[12:15], v[56:59], v[208:211], v[12:15]
	v_mfma_f32_16x16x32_bf16 v[8:11], v[72:75], v[208:211], v[8:11]
	v_mfma_f32_16x16x32_bf16 v[68:71], v[64:67], v[164:167], v[68:71]
	v_mfma_f32_16x16x32_bf16 v[60:63], v[76:79], v[164:167], v[60:63]
	v_mfma_f32_16x16x32_bf16 v[44:47], v[64:67], v[188:191], v[44:47]
	v_mfma_f32_16x16x32_bf16 v[40:43], v[76:79], v[188:191], v[40:43]
	v_mfma_f32_16x16x32_bf16 v[28:31], v[64:67], v[196:199], v[28:31]
	v_mfma_f32_16x16x32_bf16 v[24:27], v[76:79], v[196:199], v[24:27]
	v_mfma_f32_16x16x32_bf16 v[12:15], v[64:67], v[212:215], v[12:15]
	v_mfma_f32_16x16x32_bf16 v[8:11], v[76:79], v[212:215], v[8:11]
	s_setprio 0
	s_setprio 1
	v_mfma_f32_16x16x32_bf16 v[52:55], v[144:147], v[160:163], v[52:55]
	v_mfma_f32_16x16x32_bf16 v[48:51], v[152:155], v[160:163], v[48:51]
	v_mfma_f32_16x16x32_bf16 v[36:39], v[144:147], v[168:171], v[36:39]
	v_mfma_f32_16x16x32_bf16 v[32:35], v[152:155], v[168:171], v[32:35]
	v_mfma_f32_16x16x32_bf16 v[20:23], v[144:147], v[192:195], v[20:23]
	v_mfma_f32_16x16x32_bf16 v[16:19], v[152:155], v[192:195], v[16:19]
	v_mfma_f32_16x16x32_bf16 v[4:7], v[144:147], v[208:211], v[4:7]
	v_mfma_f32_16x16x32_bf16 v[0:3], v[152:155], v[208:211], v[0:3]
	v_mfma_f32_16x16x32_bf16 v[52:55], v[148:151], v[164:167], v[52:55]
	v_mfma_f32_16x16x32_bf16 v[48:51], v[156:159], v[164:167], v[48:51]
	v_mfma_f32_16x16x32_bf16 v[36:39], v[148:151], v[188:191], v[36:39]
	v_mfma_f32_16x16x32_bf16 v[32:35], v[156:159], v[188:191], v[32:35]
	v_mfma_f32_16x16x32_bf16 v[20:23], v[148:151], v[196:199], v[20:23]
	v_mfma_f32_16x16x32_bf16 v[16:19], v[156:159], v[196:199], v[16:19]
	v_mfma_f32_16x16x32_bf16 v[4:7], v[148:151], v[212:215], v[4:7]
	v_mfma_f32_16x16x32_bf16 v[0:3], v[156:159], v[212:215], v[0:3]
	s_setprio 0
	s_barrier
	s_add_i32 s56, s56, 2
	s_add_u32 s34, s34, 0x100
	s_addc_u32 s35, s35, 0
	s_add_u32 s54, s54, 0x100
	s_addc_u32 s55, s55, 0
	s_cmp_gt_u32 s56, 29
	s_cbranch_scc0 .LBB0_1295
	s_and_b64 vcc, exec, s[16:17]
	s_cbranch_vccz .LBB0_1298
	s_barrier
